# K-loops: the LDS-DMA stage of the 12-read phases (1,5) is issued in the following phase's memory part after its fragment reads; stage order and vmcnt points unchanged
# speedup vs baseline: 1.0042x; 1.0042x over previous
.LBB0_122:
	v_mov_b64_e32 v[0:1], 0x180
	s_ashr_i32 s15, s14, 31
	v_cmp_lt_i64_e32 vcc, s[16:17], v[0:1]
	s_lshl_b64 s[16:17], s[14:15], 19
	s_add_u32 s16, s30, s16
	s_addc_u32 s17, s31, s17
	s_and_b64 s[18:19], vcc, exec
	s_cselect_b32 s7, s17, s21
	s_cselect_b32 s9, s16, s20
	s_ashr_i32 s13, s12, 31
	s_lshl_b64 s[18:19], s[12:13], 19
	s_add_u32 s18, s34, s18
	s_addc_u32 s19, s35, s19
	s_and_b64 s[22:23], vcc, exec
	s_cselect_b32 s13, s19, s3
	s_cselect_b32 s15, s18, s2
	s_add_u32 s20, s20, 0x40080
	s_addc_u32 s21, s21, 0
	s_add_u32 s50, s2, 0x100
	s_addc_u32 s51, s3, 0
	s_mov_b32 s52, -2
	s_add_u32 s2, s20, 0xfffc0080
	s_addc_u32 s3, s21, -1
	ds_read_b128 v[24:27], v164
	ds_read_b128 v[28:31], v164 offset:1024
	ds_read_b128 v[32:35], v164 offset:2048
	ds_read_b128 v[36:39], v164 offset:3072
	s_cmp_eq_u32 s52, 12
	s_cselect_b32 s23, s7, s3
	s_cselect_b32 s22, s9, s2
	s_cselect_b32 s3, s13, s51
	s_cselect_b32 s2, s15, s50
	ds_read_b128 v[154:157], v165
	ds_read_b128 v[158:161], v165 offset:1024
	ds_read_b128 v[180:183], v165 offset:2048
	ds_read_b128 v[184:187], v165 offset:3072
	ds_read_b128 v[188:191], v165 offset:4096
	ds_read_b128 v[192:195], v165 offset:5120
	ds_read_b128 v[196:199], v165 offset:6144
	ds_read_b128 v[200:203], v165 offset:7168
	s_waitcnt lgkmcnt(8)
	s_barrier
	s_waitcnt lgkmcnt(0)
	v_mfma_f32_16x16x32_bf16 v[140:143], v[24:27], v[154:157], 0
	v_mfma_f32_16x16x32_bf16 v[136:139], v[32:35], v[154:157], 0
	v_mfma_f32_16x16x32_bf16 v[124:127], v[24:27], v[180:183], 0
	v_mfma_f32_16x16x32_bf16 v[120:123], v[32:35], v[180:183], 0
	v_mfma_f32_16x16x32_bf16 v[108:111], v[24:27], v[188:191], 0
	v_mfma_f32_16x16x32_bf16 v[104:107], v[32:35], v[188:191], 0
	v_mfma_f32_16x16x32_bf16 v[92:95], v[24:27], v[196:199], 0
	v_mfma_f32_16x16x32_bf16 v[88:91], v[32:35], v[196:199], 0
	v_mfma_f32_16x16x32_bf16 v[140:143], v[28:31], v[158:161], v[140:143]
	v_mfma_f32_16x16x32_bf16 v[136:139], v[36:39], v[158:161], v[136:139]
	v_mfma_f32_16x16x32_bf16 v[124:127], v[28:31], v[184:187], v[124:127]
	v_mfma_f32_16x16x32_bf16 v[120:123], v[36:39], v[184:187], v[120:123]
	v_mfma_f32_16x16x32_bf16 v[108:111], v[28:31], v[192:195], v[108:111]
	v_mfma_f32_16x16x32_bf16 v[104:107], v[36:39], v[192:195], v[104:107]
	v_mfma_f32_16x16x32_bf16 v[92:95], v[28:31], v[200:203], v[92:95]
	v_mfma_f32_16x16x32_bf16 v[88:91], v[36:39], v[200:203], v[88:91]
	s_barrier
	s_add_i32 m0, s37, 0xc000
	ds_read_b128 v[204:207], v164 offset:16384
	ds_read_b128 v[208:211], v164 offset:17408
	ds_read_b128 v[212:215], v164 offset:18432
	global_load_lds_dwordx4 v150, s[20:21]
	s_add_i32 m0, s37, 0xe000
	ds_read_b128 v[216:219], v164 offset:19456
	global_load_lds_dwordx4 v152, s[20:21]
	s_add_u32 s98, s2, 0x80
	s_addc_u32 s99, s3, 0
	s_add_i32 m0, s36, 0x10000
	s_nop 0
	global_load_lds_dwordx4 v168, s[2:3]
	s_add_i32 m0, s36, 0x12000
	s_nop 0
	global_load_lds_dwordx4 v148, s[2:3]
	s_barrier
	s_waitcnt lgkmcnt(0)
	v_mfma_f32_16x16x32_bf16 v[132:135], v[204:207], v[154:157], 0
	v_mfma_f32_16x16x32_bf16 v[128:131], v[212:215], v[154:157], 0
	v_mfma_f32_16x16x32_bf16 v[116:119], v[204:207], v[180:183], 0
	v_mfma_f32_16x16x32_bf16 v[112:115], v[212:215], v[180:183], 0
	v_mfma_f32_16x16x32_bf16 v[100:103], v[204:207], v[188:191], 0
	v_mfma_f32_16x16x32_bf16 v[96:99], v[212:215], v[188:191], 0
	v_mfma_f32_16x16x32_bf16 v[84:87], v[204:207], v[196:199], 0
	v_mfma_f32_16x16x32_bf16 v[80:83], v[212:215], v[196:199], 0
	v_mfma_f32_16x16x32_bf16 v[132:135], v[208:211], v[158:161], v[132:135]
	v_mfma_f32_16x16x32_bf16 v[128:131], v[216:219], v[158:161], v[128:131]
	v_mfma_f32_16x16x32_bf16 v[116:119], v[208:211], v[184:187], v[116:119]
	v_mfma_f32_16x16x32_bf16 v[112:115], v[216:219], v[184:187], v[112:115]
	v_mfma_f32_16x16x32_bf16 v[100:103], v[208:211], v[192:195], v[100:103]
	v_mfma_f32_16x16x32_bf16 v[96:99], v[216:219], v[192:195], v[96:99]
	v_mfma_f32_16x16x32_bf16 v[84:87], v[208:211], v[200:203], v[84:87]
	v_mfma_f32_16x16x32_bf16 v[80:83], v[216:219], v[200:203], v[80:83]
	s_mov_b32 m0, s37
	s_add_u32 s100, s22, 0x80
	s_addc_u32 s101, s23, 0
	s_barrier
	ds_read_b128 v[154:157], v165 offset:16384
	ds_read_b128 v[158:161], v165 offset:17408
	ds_read_b128 v[180:183], v165 offset:18432
	ds_read_b128 v[184:187], v165 offset:19456
	ds_read_b128 v[188:191], v165 offset:20480
	ds_read_b128 v[192:195], v165 offset:21504
	ds_read_b128 v[196:199], v165 offset:22528
	global_load_lds_dwordx4 v144, s[22:23]
	s_mov_b32 m0, s38
	ds_read_b128 v[200:203], v165 offset:23552
	global_load_lds_dwordx4 v146, s[22:23]
	s_barrier
	s_waitcnt lgkmcnt(0)
	v_mfma_f32_16x16x32_bf16 v[76:79], v[24:27], v[154:157], 0
	v_mfma_f32_16x16x32_bf16 v[72:75], v[32:35], v[154:157], 0
	v_mfma_f32_16x16x32_bf16 v[60:63], v[24:27], v[180:183], 0
	v_mfma_f32_16x16x32_bf16 v[56:59], v[32:35], v[180:183], 0
	v_mfma_f32_16x16x32_bf16 v[44:47], v[24:27], v[188:191], 0
	v_mfma_f32_16x16x32_bf16 v[40:43], v[32:35], v[188:191], 0
	v_mfma_f32_16x16x32_bf16 v[12:15], v[24:27], v[196:199], 0
	v_mfma_f32_16x16x32_bf16 v[8:11], v[32:35], v[196:199], 0
	v_mfma_f32_16x16x32_bf16 v[76:79], v[28:31], v[158:161], v[76:79]
	v_mfma_f32_16x16x32_bf16 v[72:75], v[36:39], v[158:161], v[72:75]
	v_mfma_f32_16x16x32_bf16 v[60:63], v[28:31], v[184:187], v[60:63]
	v_mfma_f32_16x16x32_bf16 v[56:59], v[36:39], v[184:187], v[56:59]
	v_mfma_f32_16x16x32_bf16 v[44:47], v[28:31], v[192:195], v[44:47]
	v_mfma_f32_16x16x32_bf16 v[40:43], v[36:39], v[192:195], v[40:43]
	v_mfma_f32_16x16x32_bf16 v[12:15], v[28:31], v[200:203], v[12:15]
	v_mfma_f32_16x16x32_bf16 v[8:11], v[36:39], v[200:203], v[8:11]
	s_barrier
	s_add_i32 m0, s36, 0x14000
	s_add_u32 s54, s2, 0x40000
	s_addc_u32 s55, s3, 0
	global_load_lds_dwordx4 v168, s[54:55]
	s_add_i32 m0, s36, 0x16000
	s_add_u32 s22, s22, 0x40000
	s_addc_u32 s23, s23, 0
	global_load_lds_dwordx4 v148, s[54:55]
	s_waitcnt vmcnt(6)
	s_barrier
	v_mfma_f32_16x16x32_bf16 v[20:23], v[204:207], v[188:191], 0
	v_mfma_f32_16x16x32_bf16 v[16:19], v[212:215], v[188:191], 0
	v_mfma_f32_16x16x32_bf16 v[4:7], v[204:207], v[196:199], 0
	v_mfma_f32_16x16x32_bf16 v[0:3], v[212:215], v[196:199], 0
	v_mfma_f32_16x16x32_bf16 v[24:27], v[204:207], v[154:157], 0
	v_mfma_f32_16x16x32_bf16 v[28:31], v[212:215], v[154:157], 0
	v_mfma_f32_16x16x32_bf16 v[32:35], v[204:207], v[180:183], 0
	v_mfma_f32_16x16x32_bf16 v[36:39], v[212:215], v[180:183], 0
	v_mfma_f32_16x16x32_bf16 v[20:23], v[208:211], v[192:195], v[20:23]
	v_mfma_f32_16x16x32_bf16 v[16:19], v[216:219], v[192:195], v[16:19]
	v_mfma_f32_16x16x32_bf16 v[4:7], v[208:211], v[200:203], v[4:7]
	v_mfma_f32_16x16x32_bf16 v[0:3], v[216:219], v[200:203], v[0:3]
	v_mfma_f32_16x16x32_bf16 v[24:27], v[208:211], v[158:161], v[24:27]
	v_mfma_f32_16x16x32_bf16 v[28:31], v[216:219], v[158:161], v[28:31]
	v_mfma_f32_16x16x32_bf16 v[32:35], v[208:211], v[184:187], v[32:35]
	v_mfma_f32_16x16x32_bf16 v[36:39], v[216:219], v[184:187], v[36:39]
	s_barrier
	ds_read_b128 v[48:51], v164 offset:32768
	ds_read_b128 v[52:55], v164 offset:33792
	ds_read_b128 v[64:67], v164 offset:34816
	ds_read_b128 v[68:71], v164 offset:35840
	ds_read_b128 v[154:157], v165 offset:32768
	ds_read_b128 v[158:161], v165 offset:33792
	ds_read_b128 v[180:183], v165 offset:34816
	ds_read_b128 v[184:187], v165 offset:35840
	ds_read_b128 v[188:191], v165 offset:36864
	ds_read_b128 v[192:195], v165 offset:37888
	ds_read_b128 v[196:199], v165 offset:38912
	ds_read_b128 v[200:203], v165 offset:39936
	s_waitcnt lgkmcnt(8)
	s_barrier
	s_waitcnt lgkmcnt(0)
	v_mfma_f32_16x16x32_bf16 v[140:143], v[48:51], v[154:157], v[140:143]
	v_mfma_f32_16x16x32_bf16 v[136:139], v[64:67], v[154:157], v[136:139]
	v_mfma_f32_16x16x32_bf16 v[124:127], v[48:51], v[180:183], v[124:127]
	v_mfma_f32_16x16x32_bf16 v[120:123], v[64:67], v[180:183], v[120:123]
	v_mfma_f32_16x16x32_bf16 v[108:111], v[48:51], v[188:191], v[108:111]
	v_mfma_f32_16x16x32_bf16 v[104:107], v[64:67], v[188:191], v[104:107]
	v_mfma_f32_16x16x32_bf16 v[92:95], v[48:51], v[196:199], v[92:95]
	v_mfma_f32_16x16x32_bf16 v[88:91], v[64:67], v[196:199], v[88:91]
	v_mfma_f32_16x16x32_bf16 v[140:143], v[52:55], v[158:161], v[140:143]
	v_mfma_f32_16x16x32_bf16 v[136:139], v[68:71], v[158:161], v[136:139]
	v_mfma_f32_16x16x32_bf16 v[124:127], v[52:55], v[184:187], v[124:127]
	v_mfma_f32_16x16x32_bf16 v[120:123], v[68:71], v[184:187], v[120:123]
	v_mfma_f32_16x16x32_bf16 v[108:111], v[52:55], v[192:195], v[108:111]
	v_mfma_f32_16x16x32_bf16 v[104:107], v[68:71], v[192:195], v[104:107]
	v_mfma_f32_16x16x32_bf16 v[92:95], v[52:55], v[200:203], v[92:95]
	v_mfma_f32_16x16x32_bf16 v[88:91], v[68:71], v[200:203], v[88:91]
	s_barrier
	s_mov_b32 m0, s39
	ds_read_b128 v[204:207], v164 offset:49152
	ds_read_b128 v[208:211], v164 offset:50176
	ds_read_b128 v[212:215], v164 offset:51200
	global_load_lds_dwordx4 v144, s[22:23]
	s_mov_b32 m0, s40
	ds_read_b128 v[216:219], v164 offset:52224
	global_load_lds_dwordx4 v146, s[22:23]
	s_add_i32 m0, s36, 0x18000
	s_nop 0
	global_load_lds_dwordx4 v168, s[98:99]
	s_add_i32 m0, s36, 0x1a000
	s_nop 0
	global_load_lds_dwordx4 v148, s[98:99]
	s_barrier
	s_waitcnt lgkmcnt(0)
	v_mfma_f32_16x16x32_bf16 v[132:135], v[204:207], v[154:157], v[132:135]
	v_mfma_f32_16x16x32_bf16 v[128:131], v[212:215], v[154:157], v[128:131]
	v_mfma_f32_16x16x32_bf16 v[116:119], v[204:207], v[180:183], v[116:119]
	v_mfma_f32_16x16x32_bf16 v[112:115], v[212:215], v[180:183], v[112:115]
	v_mfma_f32_16x16x32_bf16 v[100:103], v[204:207], v[188:191], v[100:103]
	v_mfma_f32_16x16x32_bf16 v[96:99], v[212:215], v[188:191], v[96:99]
	v_mfma_f32_16x16x32_bf16 v[84:87], v[204:207], v[196:199], v[84:87]
	v_mfma_f32_16x16x32_bf16 v[80:83], v[212:215], v[196:199], v[80:83]
	v_mfma_f32_16x16x32_bf16 v[132:135], v[208:211], v[158:161], v[132:135]
	v_mfma_f32_16x16x32_bf16 v[128:131], v[216:219], v[158:161], v[128:131]
	v_mfma_f32_16x16x32_bf16 v[116:119], v[208:211], v[184:187], v[116:119]
	v_mfma_f32_16x16x32_bf16 v[112:115], v[216:219], v[184:187], v[112:115]
	v_mfma_f32_16x16x32_bf16 v[100:103], v[208:211], v[192:195], v[100:103]
	v_mfma_f32_16x16x32_bf16 v[96:99], v[216:219], v[192:195], v[96:99]
	v_mfma_f32_16x16x32_bf16 v[84:87], v[208:211], v[200:203], v[84:87]
	v_mfma_f32_16x16x32_bf16 v[80:83], v[216:219], v[200:203], v[80:83]
	s_mov_b32 m0, s45
	s_barrier
	ds_read_b128 v[154:157], v165 offset:49152
	ds_read_b128 v[158:161], v165 offset:50176
	ds_read_b128 v[180:183], v165 offset:51200
	ds_read_b128 v[184:187], v165 offset:52224
	ds_read_b128 v[188:191], v165 offset:53248
	ds_read_b128 v[192:195], v165 offset:54272
	ds_read_b128 v[196:199], v165 offset:55296
	global_load_lds_dwordx4 v144, s[100:101]
	s_mov_b32 m0, s46
	ds_read_b128 v[200:203], v165 offset:56320
	global_load_lds_dwordx4 v146, s[100:101]
	s_barrier
	s_waitcnt lgkmcnt(0)
	v_mfma_f32_16x16x32_bf16 v[76:79], v[48:51], v[154:157], v[76:79]
	v_mfma_f32_16x16x32_bf16 v[72:75], v[64:67], v[154:157], v[72:75]
	v_mfma_f32_16x16x32_bf16 v[60:63], v[48:51], v[180:183], v[60:63]
	v_mfma_f32_16x16x32_bf16 v[56:59], v[64:67], v[180:183], v[56:59]
	v_mfma_f32_16x16x32_bf16 v[44:47], v[48:51], v[188:191], v[44:47]
	v_mfma_f32_16x16x32_bf16 v[40:43], v[64:67], v[188:191], v[40:43]
	v_mfma_f32_16x16x32_bf16 v[12:15], v[48:51], v[196:199], v[12:15]
	v_mfma_f32_16x16x32_bf16 v[8:11], v[64:67], v[196:199], v[8:11]
	v_mfma_f32_16x16x32_bf16 v[76:79], v[52:55], v[158:161], v[76:79]
	v_mfma_f32_16x16x32_bf16 v[72:75], v[68:71], v[158:161], v[72:75]
	v_mfma_f32_16x16x32_bf16 v[60:63], v[52:55], v[184:187], v[60:63]
	v_mfma_f32_16x16x32_bf16 v[56:59], v[68:71], v[184:187], v[56:59]
	v_mfma_f32_16x16x32_bf16 v[44:47], v[52:55], v[192:195], v[44:47]
	v_mfma_f32_16x16x32_bf16 v[40:43], v[68:71], v[192:195], v[40:43]
	v_mfma_f32_16x16x32_bf16 v[12:15], v[52:55], v[200:203], v[12:15]
	v_mfma_f32_16x16x32_bf16 v[8:11], v[68:71], v[200:203], v[8:11]
	s_barrier
	s_add_i32 m0, s36, 0x1c000
	s_add_u32 s2, s2, 0x40080
	s_addc_u32 s3, s3, 0
	global_load_lds_dwordx4 v168, s[2:3]
	s_add_i32 m0, s36, 0x1e000
	s_add_i32 s52, s52, 2
	global_load_lds_dwordx4 v148, s[2:3]
	s_waitcnt vmcnt(6)
	s_barrier
	v_mfma_f32_16x16x32_bf16 v[24:27], v[204:207], v[154:157], v[24:27]
	v_mfma_f32_16x16x32_bf16 v[68:71], v[208:211], v[158:161], v[24:27]
	v_mfma_f32_16x16x32_bf16 v[24:27], v[212:215], v[154:157], v[28:31]
	v_mfma_f32_16x16x32_bf16 v[64:67], v[216:219], v[158:161], v[24:27]
	v_mfma_f32_16x16x32_bf16 v[24:27], v[204:207], v[180:183], v[32:35]
	v_mfma_f32_16x16x32_bf16 v[52:55], v[208:211], v[184:187], v[24:27]
	v_mfma_f32_16x16x32_bf16 v[24:27], v[212:215], v[180:183], v[36:39]
	v_mfma_f32_16x16x32_bf16 v[20:23], v[204:207], v[188:191], v[20:23]
	v_mfma_f32_16x16x32_bf16 v[16:19], v[212:215], v[188:191], v[16:19]
	v_mfma_f32_16x16x32_bf16 v[4:7], v[204:207], v[196:199], v[4:7]
	v_mfma_f32_16x16x32_bf16 v[0:3], v[212:215], v[196:199], v[0:3]
	v_mfma_f32_16x16x32_bf16 v[48:51], v[216:219], v[184:187], v[24:27]
	v_mfma_f32_16x16x32_bf16 v[20:23], v[208:211], v[192:195], v[20:23]
	v_mfma_f32_16x16x32_bf16 v[16:19], v[216:219], v[192:195], v[16:19]
	v_mfma_f32_16x16x32_bf16 v[4:7], v[208:211], v[200:203], v[4:7]
	v_mfma_f32_16x16x32_bf16 v[0:3], v[216:219], v[200:203], v[0:3]
	s_add_u32 s20, s20, 0x100
	s_addc_u32 s21, s21, 0
	s_add_u32 s50, s50, 0x100
	s_addc_u32 s51, s51, 0
	s_cmp_gt_u32 s52, 13
	s_barrier
.LBB0_123:
	s_add_u32 s2, s20, 0xfffc0080
	s_addc_u32 s3, s21, -1
	ds_read_b128 v[24:27], v164
	ds_read_b128 v[28:31], v164 offset:1024
	ds_read_b128 v[32:35], v164 offset:2048
	ds_read_b128 v[36:39], v164 offset:3072
	s_cmp_eq_u32 s52, 12
	s_cselect_b32 s23, s7, s3
	s_cselect_b32 s22, s9, s2
	s_cselect_b32 s3, s13, s51
	s_cselect_b32 s2, s15, s50
	ds_read_b128 v[154:157], v165
	ds_read_b128 v[158:161], v165 offset:1024
	ds_read_b128 v[180:183], v165 offset:2048
	ds_read_b128 v[184:187], v165 offset:3072
	ds_read_b128 v[188:191], v165 offset:4096
	ds_read_b128 v[192:195], v165 offset:5120
	ds_read_b128 v[196:199], v165 offset:6144
	ds_read_b128 v[200:203], v165 offset:7168
	s_waitcnt lgkmcnt(8)
	s_barrier
	s_waitcnt lgkmcnt(0)
	v_mfma_f32_16x16x32_bf16 v[140:143], v[24:27], v[154:157], v[140:143]
	v_mfma_f32_16x16x32_bf16 v[136:139], v[32:35], v[154:157], v[136:139]
	v_mfma_f32_16x16x32_bf16 v[124:127], v[24:27], v[180:183], v[124:127]
	v_mfma_f32_16x16x32_bf16 v[120:123], v[32:35], v[180:183], v[120:123]
	v_mfma_f32_16x16x32_bf16 v[108:111], v[24:27], v[188:191], v[108:111]
	v_mfma_f32_16x16x32_bf16 v[104:107], v[32:35], v[188:191], v[104:107]
	v_mfma_f32_16x16x32_bf16 v[92:95], v[24:27], v[196:199], v[92:95]
	v_mfma_f32_16x16x32_bf16 v[88:91], v[32:35], v[196:199], v[88:91]
	v_mfma_f32_16x16x32_bf16 v[140:143], v[28:31], v[158:161], v[140:143]
	v_mfma_f32_16x16x32_bf16 v[136:139], v[36:39], v[158:161], v[136:139]
	v_mfma_f32_16x16x32_bf16 v[124:127], v[28:31], v[184:187], v[124:127]
	v_mfma_f32_16x16x32_bf16 v[120:123], v[36:39], v[184:187], v[120:123]
	v_mfma_f32_16x16x32_bf16 v[108:111], v[28:31], v[192:195], v[108:111]
	v_mfma_f32_16x16x32_bf16 v[104:107], v[36:39], v[192:195], v[104:107]
	v_mfma_f32_16x16x32_bf16 v[92:95], v[28:31], v[200:203], v[92:95]
	v_mfma_f32_16x16x32_bf16 v[88:91], v[36:39], v[200:203], v[88:91]
	s_barrier
	s_add_i32 m0, s37, 0xc000
	ds_read_b128 v[204:207], v164 offset:16384
	ds_read_b128 v[208:211], v164 offset:17408
	ds_read_b128 v[212:215], v164 offset:18432
	global_load_lds_dwordx4 v150, s[20:21]
	s_add_i32 m0, s37, 0xe000
	ds_read_b128 v[216:219], v164 offset:19456
	global_load_lds_dwordx4 v152, s[20:21]
	s_add_u32 s98, s2, 0x80
	s_addc_u32 s99, s3, 0
	s_add_i32 m0, s36, 0x10000
	s_nop 0
	global_load_lds_dwordx4 v168, s[2:3]
	s_add_i32 m0, s36, 0x12000
	s_nop 0
	global_load_lds_dwordx4 v148, s[2:3]
	s_barrier
	s_waitcnt lgkmcnt(0)
	v_mfma_f32_16x16x32_bf16 v[132:135], v[204:207], v[154:157], v[132:135]
	v_mfma_f32_16x16x32_bf16 v[128:131], v[212:215], v[154:157], v[128:131]
	v_mfma_f32_16x16x32_bf16 v[116:119], v[204:207], v[180:183], v[116:119]
	v_mfma_f32_16x16x32_bf16 v[112:115], v[212:215], v[180:183], v[112:115]
	v_mfma_f32_16x16x32_bf16 v[100:103], v[204:207], v[188:191], v[100:103]
	v_mfma_f32_16x16x32_bf16 v[96:99], v[212:215], v[188:191], v[96:99]
	v_mfma_f32_16x16x32_bf16 v[84:87], v[204:207], v[196:199], v[84:87]
	v_mfma_f32_16x16x32_bf16 v[80:83], v[212:215], v[196:199], v[80:83]
	v_mfma_f32_16x16x32_bf16 v[132:135], v[208:211], v[158:161], v[132:135]
	v_mfma_f32_16x16x32_bf16 v[128:131], v[216:219], v[158:161], v[128:131]
	v_mfma_f32_16x16x32_bf16 v[116:119], v[208:211], v[184:187], v[116:119]
	v_mfma_f32_16x16x32_bf16 v[112:115], v[216:219], v[184:187], v[112:115]
	v_mfma_f32_16x16x32_bf16 v[100:103], v[208:211], v[192:195], v[100:103]
	v_mfma_f32_16x16x32_bf16 v[96:99], v[216:219], v[192:195], v[96:99]
	v_mfma_f32_16x16x32_bf16 v[84:87], v[208:211], v[200:203], v[84:87]
	v_mfma_f32_16x16x32_bf16 v[80:83], v[216:219], v[200:203], v[80:83]
	s_mov_b32 m0, s37
	s_add_u32 s100, s22, 0x80
	s_addc_u32 s101, s23, 0
	s_barrier
	ds_read_b128 v[154:157], v165 offset:16384
	ds_read_b128 v[158:161], v165 offset:17408
	ds_read_b128 v[180:183], v165 offset:18432
	ds_read_b128 v[184:187], v165 offset:19456
	ds_read_b128 v[188:191], v165 offset:20480
	ds_read_b128 v[192:195], v165 offset:21504
	ds_read_b128 v[196:199], v165 offset:22528
	global_load_lds_dwordx4 v144, s[22:23]
	s_mov_b32 m0, s38
	ds_read_b128 v[200:203], v165 offset:23552
	global_load_lds_dwordx4 v146, s[22:23]
	s_barrier
	s_waitcnt lgkmcnt(0)
	v_mfma_f32_16x16x32_bf16 v[76:79], v[24:27], v[154:157], v[76:79]
	v_mfma_f32_16x16x32_bf16 v[72:75], v[32:35], v[154:157], v[72:75]
	v_mfma_f32_16x16x32_bf16 v[60:63], v[24:27], v[180:183], v[60:63]
	v_mfma_f32_16x16x32_bf16 v[56:59], v[32:35], v[180:183], v[56:59]
	v_mfma_f32_16x16x32_bf16 v[44:47], v[24:27], v[188:191], v[44:47]
	v_mfma_f32_16x16x32_bf16 v[40:43], v[32:35], v[188:191], v[40:43]
	v_mfma_f32_16x16x32_bf16 v[12:15], v[24:27], v[196:199], v[12:15]
	v_mfma_f32_16x16x32_bf16 v[8:11], v[32:35], v[196:199], v[8:11]
	v_mfma_f32_16x16x32_bf16 v[76:79], v[28:31], v[158:161], v[76:79]
	v_mfma_f32_16x16x32_bf16 v[72:75], v[36:39], v[158:161], v[72:75]
	v_mfma_f32_16x16x32_bf16 v[60:63], v[28:31], v[184:187], v[60:63]
	v_mfma_f32_16x16x32_bf16 v[56:59], v[36:39], v[184:187], v[56:59]
	v_mfma_f32_16x16x32_bf16 v[44:47], v[28:31], v[192:195], v[44:47]
	v_mfma_f32_16x16x32_bf16 v[40:43], v[36:39], v[192:195], v[40:43]
	v_mfma_f32_16x16x32_bf16 v[12:15], v[28:31], v[200:203], v[12:15]
	v_mfma_f32_16x16x32_bf16 v[8:11], v[36:39], v[200:203], v[8:11]
	s_barrier
	s_add_i32 m0, s36, 0x14000
	s_add_u32 s54, s2, 0x40000
	s_addc_u32 s55, s3, 0
	global_load_lds_dwordx4 v168, s[54:55]
	s_add_i32 m0, s36, 0x16000
	s_add_u32 s22, s22, 0x40000
	s_addc_u32 s23, s23, 0
	global_load_lds_dwordx4 v148, s[54:55]
	s_waitcnt vmcnt(6)
	s_barrier
	v_mfma_f32_16x16x32_bf16 v[20:23], v[204:207], v[188:191], v[20:23]
	v_mfma_f32_16x16x32_bf16 v[16:19], v[212:215], v[188:191], v[16:19]
	v_mfma_f32_16x16x32_bf16 v[4:7], v[204:207], v[196:199], v[4:7]
	v_mfma_f32_16x16x32_bf16 v[0:3], v[212:215], v[196:199], v[0:3]
	v_mfma_f32_16x16x32_bf16 v[24:27], v[204:207], v[154:157], v[68:71]
	v_mfma_f32_16x16x32_bf16 v[28:31], v[212:215], v[154:157], v[64:67]
	v_mfma_f32_16x16x32_bf16 v[32:35], v[204:207], v[180:183], v[52:55]
	v_mfma_f32_16x16x32_bf16 v[36:39], v[212:215], v[180:183], v[48:51]
	v_mfma_f32_16x16x32_bf16 v[20:23], v[208:211], v[192:195], v[20:23]
	v_mfma_f32_16x16x32_bf16 v[16:19], v[216:219], v[192:195], v[16:19]
	v_mfma_f32_16x16x32_bf16 v[4:7], v[208:211], v[200:203], v[4:7]
	v_mfma_f32_16x16x32_bf16 v[0:3], v[216:219], v[200:203], v[0:3]
	v_mfma_f32_16x16x32_bf16 v[24:27], v[208:211], v[158:161], v[24:27]
	v_mfma_f32_16x16x32_bf16 v[28:31], v[216:219], v[158:161], v[28:31]
	v_mfma_f32_16x16x32_bf16 v[32:35], v[208:211], v[184:187], v[32:35]
	v_mfma_f32_16x16x32_bf16 v[36:39], v[216:219], v[184:187], v[36:39]
	s_barrier
	ds_read_b128 v[48:51], v164 offset:32768
	ds_read_b128 v[52:55], v164 offset:33792
	ds_read_b128 v[64:67], v164 offset:34816
	ds_read_b128 v[68:71], v164 offset:35840
	ds_read_b128 v[154:157], v165 offset:32768
	ds_read_b128 v[158:161], v165 offset:33792
	ds_read_b128 v[180:183], v165 offset:34816
	ds_read_b128 v[184:187], v165 offset:35840
	ds_read_b128 v[188:191], v165 offset:36864
	ds_read_b128 v[192:195], v165 offset:37888
	ds_read_b128 v[196:199], v165 offset:38912
	ds_read_b128 v[200:203], v165 offset:39936
	s_waitcnt lgkmcnt(8)
	s_barrier
	s_waitcnt lgkmcnt(0)
	v_mfma_f32_16x16x32_bf16 v[140:143], v[48:51], v[154:157], v[140:143]
	v_mfma_f32_16x16x32_bf16 v[136:139], v[64:67], v[154:157], v[136:139]
	v_mfma_f32_16x16x32_bf16 v[124:127], v[48:51], v[180:183], v[124:127]
	v_mfma_f32_16x16x32_bf16 v[120:123], v[64:67], v[180:183], v[120:123]
	v_mfma_f32_16x16x32_bf16 v[108:111], v[48:51], v[188:191], v[108:111]
	v_mfma_f32_16x16x32_bf16 v[104:107], v[64:67], v[188:191], v[104:107]
	v_mfma_f32_16x16x32_bf16 v[92:95], v[48:51], v[196:199], v[92:95]
	v_mfma_f32_16x16x32_bf16 v[88:91], v[64:67], v[196:199], v[88:91]
	v_mfma_f32_16x16x32_bf16 v[140:143], v[52:55], v[158:161], v[140:143]
	v_mfma_f32_16x16x32_bf16 v[136:139], v[68:71], v[158:161], v[136:139]
	v_mfma_f32_16x16x32_bf16 v[124:127], v[52:55], v[184:187], v[124:127]
	v_mfma_f32_16x16x32_bf16 v[120:123], v[68:71], v[184:187], v[120:123]
	v_mfma_f32_16x16x32_bf16 v[108:111], v[52:55], v[192:195], v[108:111]
	v_mfma_f32_16x16x32_bf16 v[104:107], v[68:71], v[192:195], v[104:107]
	v_mfma_f32_16x16x32_bf16 v[92:95], v[52:55], v[200:203], v[92:95]
	v_mfma_f32_16x16x32_bf16 v[88:91], v[68:71], v[200:203], v[88:91]
	s_barrier
	s_mov_b32 m0, s39
	ds_read_b128 v[204:207], v164 offset:49152
	ds_read_b128 v[208:211], v164 offset:50176
	ds_read_b128 v[212:215], v164 offset:51200
	global_load_lds_dwordx4 v144, s[22:23]
	s_mov_b32 m0, s40
	ds_read_b128 v[216:219], v164 offset:52224
	global_load_lds_dwordx4 v146, s[22:23]
	s_add_i32 m0, s36, 0x18000
	s_nop 0
	global_load_lds_dwordx4 v168, s[98:99]
	s_add_i32 m0, s36, 0x1a000
	s_nop 0
	global_load_lds_dwordx4 v148, s[98:99]
	s_barrier
	s_waitcnt lgkmcnt(0)
	v_mfma_f32_16x16x32_bf16 v[132:135], v[204:207], v[154:157], v[132:135]
	v_mfma_f32_16x16x32_bf16 v[128:131], v[212:215], v[154:157], v[128:131]
	v_mfma_f32_16x16x32_bf16 v[116:119], v[204:207], v[180:183], v[116:119]
	v_mfma_f32_16x16x32_bf16 v[112:115], v[212:215], v[180:183], v[112:115]
	v_mfma_f32_16x16x32_bf16 v[100:103], v[204:207], v[188:191], v[100:103]
	v_mfma_f32_16x16x32_bf16 v[96:99], v[212:215], v[188:191], v[96:99]
	v_mfma_f32_16x16x32_bf16 v[84:87], v[204:207], v[196:199], v[84:87]
	v_mfma_f32_16x16x32_bf16 v[80:83], v[212:215], v[196:199], v[80:83]
	v_mfma_f32_16x16x32_bf16 v[132:135], v[208:211], v[158:161], v[132:135]
	v_mfma_f32_16x16x32_bf16 v[128:131], v[216:219], v[158:161], v[128:131]
	v_mfma_f32_16x16x32_bf16 v[116:119], v[208:211], v[184:187], v[116:119]
	v_mfma_f32_16x16x32_bf16 v[112:115], v[216:219], v[184:187], v[112:115]
	v_mfma_f32_16x16x32_bf16 v[100:103], v[208:211], v[192:195], v[100:103]
	v_mfma_f32_16x16x32_bf16 v[96:99], v[216:219], v[192:195], v[96:99]
	v_mfma_f32_16x16x32_bf16 v[84:87], v[208:211], v[200:203], v[84:87]
	v_mfma_f32_16x16x32_bf16 v[80:83], v[216:219], v[200:203], v[80:83]
	s_mov_b32 m0, s45
	s_barrier
	ds_read_b128 v[154:157], v165 offset:49152
	ds_read_b128 v[158:161], v165 offset:50176
	ds_read_b128 v[180:183], v165 offset:51200
	ds_read_b128 v[184:187], v165 offset:52224
	ds_read_b128 v[188:191], v165 offset:53248
	ds_read_b128 v[192:195], v165 offset:54272
	ds_read_b128 v[196:199], v165 offset:55296
	global_load_lds_dwordx4 v144, s[100:101]
	s_mov_b32 m0, s46
	ds_read_b128 v[200:203], v165 offset:56320
	global_load_lds_dwordx4 v146, s[100:101]
	s_barrier
	s_waitcnt lgkmcnt(0)
	v_mfma_f32_16x16x32_bf16 v[76:79], v[48:51], v[154:157], v[76:79]
	v_mfma_f32_16x16x32_bf16 v[72:75], v[64:67], v[154:157], v[72:75]
	v_mfma_f32_16x16x32_bf16 v[60:63], v[48:51], v[180:183], v[60:63]
	v_mfma_f32_16x16x32_bf16 v[56:59], v[64:67], v[180:183], v[56:59]
	v_mfma_f32_16x16x32_bf16 v[44:47], v[48:51], v[188:191], v[44:47]
	v_mfma_f32_16x16x32_bf16 v[40:43], v[64:67], v[188:191], v[40:43]
	v_mfma_f32_16x16x32_bf16 v[12:15], v[48:51], v[196:199], v[12:15]
	v_mfma_f32_16x16x32_bf16 v[8:11], v[64:67], v[196:199], v[8:11]
	v_mfma_f32_16x16x32_bf16 v[76:79], v[52:55], v[158:161], v[76:79]
	v_mfma_f32_16x16x32_bf16 v[72:75], v[68:71], v[158:161], v[72:75]
	v_mfma_f32_16x16x32_bf16 v[60:63], v[52:55], v[184:187], v[60:63]
	v_mfma_f32_16x16x32_bf16 v[56:59], v[68:71], v[184:187], v[56:59]
	v_mfma_f32_16x16x32_bf16 v[44:47], v[52:55], v[192:195], v[44:47]
	v_mfma_f32_16x16x32_bf16 v[40:43], v[68:71], v[192:195], v[40:43]
	v_mfma_f32_16x16x32_bf16 v[12:15], v[52:55], v[200:203], v[12:15]
	v_mfma_f32_16x16x32_bf16 v[8:11], v[68:71], v[200:203], v[8:11]
	s_barrier
	s_add_i32 m0, s36, 0x1c000
	s_add_u32 s2, s2, 0x40080
	s_addc_u32 s3, s3, 0
	global_load_lds_dwordx4 v168, s[2:3]
	s_add_i32 m0, s36, 0x1e000
	s_add_i32 s52, s52, 2
	global_load_lds_dwordx4 v148, s[2:3]
	s_waitcnt vmcnt(6)
	s_barrier
	v_mfma_f32_16x16x32_bf16 v[24:27], v[204:207], v[154:157], v[24:27]
	v_mfma_f32_16x16x32_bf16 v[68:71], v[208:211], v[158:161], v[24:27]
	v_mfma_f32_16x16x32_bf16 v[24:27], v[212:215], v[154:157], v[28:31]
	v_mfma_f32_16x16x32_bf16 v[64:67], v[216:219], v[158:161], v[24:27]
	v_mfma_f32_16x16x32_bf16 v[24:27], v[204:207], v[180:183], v[32:35]
	v_mfma_f32_16x16x32_bf16 v[52:55], v[208:211], v[184:187], v[24:27]
	v_mfma_f32_16x16x32_bf16 v[24:27], v[212:215], v[180:183], v[36:39]
	v_mfma_f32_16x16x32_bf16 v[20:23], v[204:207], v[188:191], v[20:23]
	v_mfma_f32_16x16x32_bf16 v[16:19], v[212:215], v[188:191], v[16:19]
	v_mfma_f32_16x16x32_bf16 v[4:7], v[204:207], v[196:199], v[4:7]
	v_mfma_f32_16x16x32_bf16 v[0:3], v[212:215], v[196:199], v[0:3]
	v_mfma_f32_16x16x32_bf16 v[48:51], v[216:219], v[184:187], v[24:27]
	v_mfma_f32_16x16x32_bf16 v[20:23], v[208:211], v[192:195], v[20:23]
	v_mfma_f32_16x16x32_bf16 v[16:19], v[216:219], v[192:195], v[16:19]
	v_mfma_f32_16x16x32_bf16 v[4:7], v[208:211], v[200:203], v[4:7]
	v_mfma_f32_16x16x32_bf16 v[0:3], v[216:219], v[200:203], v[0:3]
	s_add_u32 s20, s20, 0x100
	s_addc_u32 s21, s21, 0
	s_add_u32 s50, s50, 0x100
	s_addc_u32 s51, s51, 0
	s_cmp_gt_u32 s52, 13
	s_barrier
	s_cbranch_scc0 .LBB0_123
	s_lshl_b32 s2, s6, 8
	s_add_i32 s3, s2, s43
	s_lshl_b32 s2, s8, 8
	s_cmp_gt_i32 s8, 3
	s_cselect_b64 s[20:21], -1, 0
	s_and_b64 s[22:23], s[20:21], exec
	s_mov_b32 s7, 0x8982000
	s_cselect_b32 s7, s7, 0x7182000
	s_add_u32 s22, s26, s7
	s_addc_u32 s23, s25, 0
	s_add_i32 s7, s6, -16
	v_mov_b32_e32 v160, v163
	v_mov_b32_e32 v24, v162
	s_lshr_b32 s7, s7, 3
	s_add_i32 s96, s7, 1
	v_add_u32_e32 v154, s3, v24
	s_lshl_b64 s[50:51], s[96:97], 11
	v_ashrrev_i32_e32 v155, 31, v154
	s_cmp_gt_i32 s6, 15
	v_lshl_add_u64 v[156:157], v[154:155], 2, s[10:11]
	s_cselect_b32 s7, s51, 0
	s_cselect_b32 s6, s50, 0
	global_load_dword v166, v[156:157], off
	global_load_dword v191, v[156:157], off offset:64
	global_load_dword v192, v[156:157], off offset:128
	global_load_dword v193, v[156:157], off offset:192
	global_load_dword v194, v[156:157], off offset:512
	global_load_dword v195, v[156:157], off offset:576
	global_load_dword v196, v[156:157], off offset:640
	global_load_dword v197, v[156:157], off offset:704
	s_lshl_b64 s[6:7], s[6:7], 2
	s_add_u32 s9, s41, s6
	s_addc_u32 s13, s42, s7
	s_ashr_i32 s3, s2, 31
	s_lshl_b64 s[6:7], s[2:3], 2
	s_add_u32 s3, s9, s6
	s_addc_u32 s7, s13, s7
	v_lshlrev_b32_e32 v158, 3, v160
	s_add_u32 s6, s3, s49
	s_addc_u32 s7, s7, 0
	v_ashrrev_i32_e32 v159, 31, v158
	v_lshl_add_u64 v[24:25], v[158:159], 2, s[6:7]
	global_load_dwordx4 v[36:39], v[24:25], off
	global_load_dwordx4 v[32:35], v[24:25], off offset:16
	global_load_dwordx4 v[28:31], v[24:25], off offset:512
	s_nop 0
	global_load_dwordx4 v[24:27], v[24:25], off offset:528
	s_and_b32 s2, s2, 0x300
	s_or_b32 s2, s2, s44
	v_add_u32_e32 v158, s2, v158
	v_cmp_eq_u32_e64 s[6:7], 0, v160
	v_lshlrev_b64 v[160:161], 11, v[154:155]
	s_cmp_lt_i32 s8, 4
	s_waitcnt vmcnt(0)
	v_ashrrev_i32_e32 v159, 31, v158
	v_lshl_add_u64 v[158:159], v[158:159], 1, s[22:23]
	v_lshl_add_u64 v[160:161], v[158:159], 0, v[160:161]
	v_lshl_add_u64 v[156:157], v[154:155], 2, s[0:1]
	s_and_b64 s[6:7], s[6:7], s[20:21]
	s_mov_b64 s[2:3], 0x8000
	s_mov_b64 s[50:51], 0x28000
	v_mov_b32_e32 v180, 0xc0135761
	v_mov_b32_e32 v181, 0xc0135761
	v_mov_b32_e32 v182, 0xbdd2d3e7
	v_mov_b32_e32 v183, 0xbdd2d3e7
	v_fmamk_f32 v166, v166, 0x3a800000, v225
	v_fmamk_f32 v190, v191, 0x3a800000, v225
	v_fmamk_f32 v192, v192, 0x3a800000, v225
	v_fmamk_f32 v188, v193, 0x3a800000, v225
	v_fmamk_f32 v194, v194, 0x3a800000, v225
	v_fmamk_f32 v186, v195, 0x3a800000, v225
	v_fmamk_f32 v196, v196, 0x3a800000, v225
	v_fmamk_f32 v184, v197, 0x3a800000, v225
	v_rsq_f32_e32 v166, v166
	v_rsq_f32_e32 v190, v190
	v_rsq_f32_e32 v192, v192
	v_rsq_f32_e32 v188, v188
	v_rsq_f32_e32 v194, v194
	v_rsq_f32_e32 v186, v186
	v_rsq_f32_e32 v196, v196
	v_rsq_f32_e32 v184, v184
	v_pk_fma_f32 v[140:141], v[140:141], v[166:167], v[36:37] op_sel_hi:[1,0,1]
	v_pk_fma_f32 v[142:143], v[142:143], v[166:167], v[38:39] op_sel_hi:[1,0,1]
	v_pk_fma_f32 v[136:137], v[136:137], v[166:167], v[32:33] op_sel_hi:[1,0,1]
	v_pk_fma_f32 v[138:139], v[138:139], v[166:167], v[34:35] op_sel_hi:[1,0,1]
	v_pk_fma_f32 v[132:133], v[132:133], v[166:167], v[28:29] op_sel_hi:[1,0,1]
	v_pk_fma_f32 v[134:135], v[134:135], v[166:167], v[30:31] op_sel_hi:[1,0,1]
	v_pk_fma_f32 v[128:129], v[128:129], v[166:167], v[24:25] op_sel_hi:[1,0,1]
	v_pk_fma_f32 v[130:131], v[130:131], v[166:167], v[26:27] op_sel_hi:[1,0,1]
	v_pk_fma_f32 v[124:125], v[124:125], v[190:191], v[36:37] op_sel_hi:[1,0,1]
	v_pk_fma_f32 v[126:127], v[126:127], v[190:191], v[38:39] op_sel_hi:[1,0,1]
	v_pk_fma_f32 v[120:121], v[120:121], v[190:191], v[32:33] op_sel_hi:[1,0,1]
	v_pk_fma_f32 v[122:123], v[122:123], v[190:191], v[34:35] op_sel_hi:[1,0,1]
	v_pk_fma_f32 v[116:117], v[116:117], v[190:191], v[28:29] op_sel_hi:[1,0,1]
	v_pk_fma_f32 v[118:119], v[118:119], v[190:191], v[30:31] op_sel_hi:[1,0,1]
	v_pk_fma_f32 v[112:113], v[112:113], v[190:191], v[24:25] op_sel_hi:[1,0,1]
	v_pk_fma_f32 v[114:115], v[114:115], v[190:191], v[26:27] op_sel_hi:[1,0,1]
	v_pk_fma_f32 v[108:109], v[108:109], v[192:193], v[36:37] op_sel_hi:[1,0,1]
	v_pk_fma_f32 v[110:111], v[110:111], v[192:193], v[38:39] op_sel_hi:[1,0,1]
	v_pk_fma_f32 v[104:105], v[104:105], v[192:193], v[32:33] op_sel_hi:[1,0,1]
	v_pk_fma_f32 v[106:107], v[106:107], v[192:193], v[34:35] op_sel_hi:[1,0,1]
	v_pk_fma_f32 v[100:101], v[100:101], v[192:193], v[28:29] op_sel_hi:[1,0,1]
	v_pk_fma_f32 v[102:103], v[102:103], v[192:193], v[30:31] op_sel_hi:[1,0,1]
	v_pk_fma_f32 v[96:97], v[96:97], v[192:193], v[24:25] op_sel_hi:[1,0,1]
	v_pk_fma_f32 v[98:99], v[98:99], v[192:193], v[26:27] op_sel_hi:[1,0,1]
	v_pk_fma_f32 v[92:93], v[92:93], v[188:189], v[36:37] op_sel_hi:[1,0,1]
	v_pk_fma_f32 v[94:95], v[94:95], v[188:189], v[38:39] op_sel_hi:[1,0,1]
	v_pk_fma_f32 v[88:89], v[88:89], v[188:189], v[32:33] op_sel_hi:[1,0,1]
	v_pk_fma_f32 v[90:91], v[90:91], v[188:189], v[34:35] op_sel_hi:[1,0,1]
	v_pk_fma_f32 v[84:85], v[84:85], v[188:189], v[28:29] op_sel_hi:[1,0,1]
	v_pk_fma_f32 v[86:87], v[86:87], v[188:189], v[30:31] op_sel_hi:[1,0,1]
	v_pk_fma_f32 v[80:81], v[80:81], v[188:189], v[24:25] op_sel_hi:[1,0,1]
	v_pk_fma_f32 v[82:83], v[82:83], v[188:189], v[26:27] op_sel_hi:[1,0,1]
	v_pk_fma_f32 v[76:77], v[76:77], v[194:195], v[36:37] op_sel_hi:[1,0,1]
	v_pk_fma_f32 v[78:79], v[78:79], v[194:195], v[38:39] op_sel_hi:[1,0,1]
	v_pk_fma_f32 v[72:73], v[72:73], v[194:195], v[32:33] op_sel_hi:[1,0,1]
	v_pk_fma_f32 v[74:75], v[74:75], v[194:195], v[34:35] op_sel_hi:[1,0,1]
	v_pk_fma_f32 v[68:69], v[68:69], v[194:195], v[28:29] op_sel_hi:[1,0,1]
	v_pk_fma_f32 v[70:71], v[70:71], v[194:195], v[30:31] op_sel_hi:[1,0,1]
	v_pk_fma_f32 v[64:65], v[64:65], v[194:195], v[24:25] op_sel_hi:[1,0,1]
	v_pk_fma_f32 v[66:67], v[66:67], v[194:195], v[26:27] op_sel_hi:[1,0,1]
	v_pk_fma_f32 v[60:61], v[60:61], v[186:187], v[36:37] op_sel_hi:[1,0,1]
	v_pk_fma_f32 v[62:63], v[62:63], v[186:187], v[38:39] op_sel_hi:[1,0,1]
	v_pk_fma_f32 v[56:57], v[56:57], v[186:187], v[32:33] op_sel_hi:[1,0,1]
	v_pk_fma_f32 v[58:59], v[58:59], v[186:187], v[34:35] op_sel_hi:[1,0,1]
	v_pk_fma_f32 v[52:53], v[52:53], v[186:187], v[28:29] op_sel_hi:[1,0,1]
	v_pk_fma_f32 v[54:55], v[54:55], v[186:187], v[30:31] op_sel_hi:[1,0,1]
	v_pk_fma_f32 v[48:49], v[48:49], v[186:187], v[24:25] op_sel_hi:[1,0,1]
	v_pk_fma_f32 v[50:51], v[50:51], v[186:187], v[26:27] op_sel_hi:[1,0,1]
	v_pk_fma_f32 v[44:45], v[44:45], v[196:197], v[36:37] op_sel_hi:[1,0,1]
	v_pk_fma_f32 v[46:47], v[46:47], v[196:197], v[38:39] op_sel_hi:[1,0,1]
	v_pk_fma_f32 v[40:41], v[40:41], v[196:197], v[32:33] op_sel_hi:[1,0,1]
	v_pk_fma_f32 v[42:43], v[42:43], v[196:197], v[34:35] op_sel_hi:[1,0,1]
	v_pk_fma_f32 v[20:21], v[20:21], v[196:197], v[28:29] op_sel_hi:[1,0,1]
	v_pk_fma_f32 v[22:23], v[22:23], v[196:197], v[30:31] op_sel_hi:[1,0,1]
	v_pk_fma_f32 v[16:17], v[16:17], v[196:197], v[24:25] op_sel_hi:[1,0,1]
	v_pk_fma_f32 v[18:19], v[18:19], v[196:197], v[26:27] op_sel_hi:[1,0,1]
	v_pk_fma_f32 v[12:13], v[12:13], v[184:185], v[36:37] op_sel_hi:[1,0,1]
	v_pk_fma_f32 v[14:15], v[14:15], v[184:185], v[38:39] op_sel_hi:[1,0,1]
	v_pk_fma_f32 v[8:9], v[8:9], v[184:185], v[32:33] op_sel_hi:[1,0,1]
	v_pk_fma_f32 v[10:11], v[10:11], v[184:185], v[34:35] op_sel_hi:[1,0,1]
	v_pk_fma_f32 v[4:5], v[4:5], v[184:185], v[28:29] op_sel_hi:[1,0,1]
	v_pk_fma_f32 v[6:7], v[6:7], v[184:185], v[30:31] op_sel_hi:[1,0,1]
	v_pk_fma_f32 v[0:1], v[0:1], v[184:185], v[24:25] op_sel_hi:[1,0,1]
	v_pk_fma_f32 v[2:3], v[2:3], v[184:185], v[26:27] op_sel_hi:[1,0,1]
	v_pk_mul_f32 v[24:25], v[140:141], v[140:141]
	v_pk_mul_f32 v[26:27], v[142:143], v[142:143]
	v_pk_mul_f32 v[28:29], v[136:137], v[136:137]
	v_pk_mul_f32 v[30:31], v[138:139], v[138:139]
	v_pk_mul_f32 v[32:33], v[132:133], v[132:133]
	v_pk_mul_f32 v[34:35], v[134:135], v[134:135]
	v_pk_mul_f32 v[36:37], v[128:129], v[128:129]
	v_pk_mul_f32 v[38:39], v[130:131], v[130:131]
	v_pk_fma_f32 v[24:25], v[24:25], v[182:183], v[180:181]
	v_pk_fma_f32 v[26:27], v[26:27], v[182:183], v[180:181]
	v_pk_fma_f32 v[28:29], v[28:29], v[182:183], v[180:181]
	v_pk_fma_f32 v[30:31], v[30:31], v[182:183], v[180:181]
	v_pk_fma_f32 v[32:33], v[32:33], v[182:183], v[180:181]
	v_pk_fma_f32 v[34:35], v[34:35], v[182:183], v[180:181]
	v_pk_fma_f32 v[36:37], v[36:37], v[182:183], v[180:181]
	v_pk_fma_f32 v[38:39], v[38:39], v[182:183], v[180:181]
	v_pk_mul_f32 v[24:25], v[24:25], v[140:141]
	v_pk_mul_f32 v[26:27], v[26:27], v[142:143]
	v_pk_mul_f32 v[28:29], v[28:29], v[136:137]
	v_pk_mul_f32 v[30:31], v[30:31], v[138:139]
	v_pk_mul_f32 v[32:33], v[32:33], v[132:133]
	v_pk_mul_f32 v[34:35], v[34:35], v[134:135]
	v_pk_mul_f32 v[36:37], v[36:37], v[128:129]
	v_pk_mul_f32 v[38:39], v[38:39], v[130:131]
	v_exp_f32_e32 v24, v24
	v_exp_f32_e32 v25, v25
	v_exp_f32_e32 v26, v26
	v_exp_f32_e32 v27, v27
	v_exp_f32_e32 v28, v28
	v_exp_f32_e32 v29, v29
	v_exp_f32_e32 v30, v30
	v_exp_f32_e32 v31, v31
	v_exp_f32_e32 v32, v32
	v_exp_f32_e32 v33, v33
	v_exp_f32_e32 v34, v34
	v_exp_f32_e32 v35, v35
	v_exp_f32_e32 v36, v36
	v_exp_f32_e32 v37, v37
	v_exp_f32_e32 v38, v38
	v_exp_f32_e32 v39, v39
	v_pk_add_f32 v[24:25], v[24:25], 1.0 op_sel_hi:[1,0]
	v_pk_add_f32 v[26:27], v[26:27], 1.0 op_sel_hi:[1,0]
	v_pk_add_f32 v[28:29], v[28:29], 1.0 op_sel_hi:[1,0]
	v_pk_add_f32 v[30:31], v[30:31], 1.0 op_sel_hi:[1,0]
	v_pk_add_f32 v[32:33], v[32:33], 1.0 op_sel_hi:[1,0]
	v_pk_add_f32 v[34:35], v[34:35], 1.0 op_sel_hi:[1,0]
	v_pk_add_f32 v[36:37], v[36:37], 1.0 op_sel_hi:[1,0]
	v_pk_add_f32 v[38:39], v[38:39], 1.0 op_sel_hi:[1,0]
	v_rcp_f32_e32 v24, v24
	v_rcp_f32_e32 v25, v25
	v_rcp_f32_e32 v26, v26
	v_rcp_f32_e32 v27, v27
	v_rcp_f32_e32 v28, v28
	v_rcp_f32_e32 v29, v29
	v_rcp_f32_e32 v30, v30
	v_rcp_f32_e32 v31, v31
	v_rcp_f32_e32 v32, v32
	v_rcp_f32_e32 v33, v33
	v_rcp_f32_e32 v34, v34
	v_rcp_f32_e32 v35, v35
	v_rcp_f32_e32 v36, v36
	v_rcp_f32_e32 v37, v37
	v_rcp_f32_e32 v38, v38
	v_rcp_f32_e32 v39, v39
	v_pk_mul_f32 v[140:141], v[140:141], v[24:25]
	v_pk_mul_f32 v[142:143], v[142:143], v[26:27]
	v_pk_mul_f32 v[136:137], v[136:137], v[28:29]
	v_pk_mul_f32 v[138:139], v[138:139], v[30:31]
	v_pk_mul_f32 v[132:133], v[132:133], v[32:33]
	v_pk_mul_f32 v[134:135], v[134:135], v[34:35]
	v_pk_mul_f32 v[128:129], v[128:129], v[36:37]
	v_pk_mul_f32 v[130:131], v[130:131], v[38:39]
	v_cvt_pk_bf16_f32 v24, v140, v141
	v_cvt_pk_bf16_f32 v25, v142, v143
	v_cvt_pk_bf16_f32 v26, v136, v137
	v_cvt_pk_bf16_f32 v27, v138, v139
	v_cvt_pk_bf16_f32 v28, v132, v133
	v_cvt_pk_bf16_f32 v29, v134, v135
	v_cvt_pk_bf16_f32 v30, v128, v129
	v_cvt_pk_bf16_f32 v31, v130, v131
	global_store_dwordx4 v[160:161], v[24:27], off
	global_store_dwordx4 v[160:161], v[28:31], off offset:256
	s_and_b64 vcc, exec, s[20:21]
	s_cbranch_vccz .Lio_skip_0
	v_pk_mul_f32 v[32:33], v[140:141], v[140:141]
	v_pk_fma_f32 v[32:33], v[142:143], v[142:143], v[32:33]
	v_pk_fma_f32 v[32:33], v[136:137], v[136:137], v[32:33]
	v_pk_fma_f32 v[32:33], v[138:139], v[138:139], v[32:33]
	v_pk_fma_f32 v[32:33], v[132:133], v[132:133], v[32:33]
	v_pk_fma_f32 v[32:33], v[134:135], v[134:135], v[32:33]
	v_pk_fma_f32 v[32:33], v[128:129], v[128:129], v[32:33]
	v_pk_fma_f32 v[32:33], v[130:131], v[130:131], v[32:33]
	s_nop 0
	v_add_f32_e32 v32, v32, v33
	v_mov_b32_e32 v33, v32
	s_nop 1
	v_permlane16_swap_b32_e32 v32, v33
	v_add_f32_e32 v32, v32, v33
	v_mov_b32_e32 v33, v32
	s_nop 1
	v_permlane32_swap_b32_e32 v32, v33
	s_and_saveexec_b64 vcc, s[6:7]
	v_add_f32_e32 v32, v32, v33
	global_atomic_add_f32 v[156:157], v32, off
	s_mov_b64 exec, vcc

.Lie_done_b:
.LBB0_354:
	s_ashr_i32 s31, s30, 31
	v_cmp_lt_i64_e32 vcc, s[8:9], v[170:171]
	s_lshl_b64 s[8:9], s[30:31], 19
	s_add_u32 s34, s52, s8
	s_addc_u32 s35, s53, s9
	s_and_b64 s[8:9], vcc, exec
	s_cselect_b32 s1, s35, s7
	s_cselect_b32 s31, s34, s6
	s_ashr_i32 s29, s28, 31
	s_lshl_b64 s[8:9], s[28:29], 19
	s_add_u32 s36, s43, s8
	s_addc_u32 s37, s42, s9
	s_and_b64 s[8:9], vcc, exec
	s_cselect_b32 s29, s37, s3
	s_cselect_b32 s38, s36, s2
	s_add_u32 s6, s6, 0x40080
	s_addc_u32 s7, s7, 0
	s_add_u32 s39, s2, 0x100
	s_addc_u32 s40, s3, 0
	s_mov_b32 s41, -2
	s_add_u32 s2, s6, 0xfffc0080
	s_addc_u32 s3, s7, -1
	ds_read_b128 v[128:131], v208
	ds_read_b128 v[132:135], v208 offset:1024
	ds_read_b128 v[136:139], v208 offset:2048
	ds_read_b128 v[140:143], v208 offset:3072
	s_cmp_eq_u32 s41, 12
	s_cselect_b32 s9, s1, s3
	s_cselect_b32 s8, s31, s2
	s_cselect_b32 s3, s29, s40
	s_cselect_b32 s2, s38, s39
	ds_read_b128 v[144:147], v209
	ds_read_b128 v[148:151], v209 offset:1024
	ds_read_b128 v[152:155], v209 offset:2048
	ds_read_b128 v[156:159], v209 offset:3072
	ds_read_b128 v[180:183], v209 offset:4096
	ds_read_b128 v[184:187], v209 offset:5120
	ds_read_b128 v[188:191], v209 offset:6144
	ds_read_b128 v[192:195], v209 offset:7168
	s_waitcnt lgkmcnt(8)
	s_barrier
	s_waitcnt lgkmcnt(0)
	v_mfma_f32_16x16x32_bf16 v[124:127], v[128:131], v[144:147], 0
	v_mfma_f32_16x16x32_bf16 v[120:123], v[136:139], v[144:147], 0
	v_mfma_f32_16x16x32_bf16 v[116:119], v[128:131], v[152:155], 0
	v_mfma_f32_16x16x32_bf16 v[112:115], v[136:139], v[152:155], 0
	v_mfma_f32_16x16x32_bf16 v[100:103], v[128:131], v[180:183], 0
	v_mfma_f32_16x16x32_bf16 v[96:99], v[136:139], v[180:183], 0
	v_mfma_f32_16x16x32_bf16 v[84:87], v[128:131], v[188:191], 0
	v_mfma_f32_16x16x32_bf16 v[80:83], v[136:139], v[188:191], 0
	v_mfma_f32_16x16x32_bf16 v[124:127], v[132:135], v[148:151], v[124:127]
	v_mfma_f32_16x16x32_bf16 v[120:123], v[140:143], v[148:151], v[120:123]
	v_mfma_f32_16x16x32_bf16 v[116:119], v[132:135], v[156:159], v[116:119]
	v_mfma_f32_16x16x32_bf16 v[112:115], v[140:143], v[156:159], v[112:115]
	v_mfma_f32_16x16x32_bf16 v[100:103], v[132:135], v[184:187], v[100:103]
	v_mfma_f32_16x16x32_bf16 v[96:99], v[140:143], v[184:187], v[96:99]
	v_mfma_f32_16x16x32_bf16 v[84:87], v[132:135], v[192:195], v[84:87]
	v_mfma_f32_16x16x32_bf16 v[80:83], v[140:143], v[192:195], v[80:83]
	s_barrier
	s_add_i32 m0, s21, 0xc000
	ds_read_b128 v[196:199], v208 offset:16384
	ds_read_b128 v[200:203], v208 offset:17408
	ds_read_b128 v[210:213], v208 offset:18432
	global_load_lds_dwordx4 v164, s[6:7]
	s_add_i32 m0, s21, 0xe000
	ds_read_b128 v[214:217], v208 offset:19456
	global_load_lds_dwordx4 v166, s[6:7]
	s_add_u32 s98, s2, 0x80
	s_addc_u32 s99, s3, 0
	s_add_i32 m0, s54, 0x10000
	s_nop 0
	global_load_lds_dwordx4 v160, s[2:3]
	s_add_i32 m0, s54, 0x12000
	s_nop 0
	global_load_lds_dwordx4 v162, s[2:3]
	s_barrier
	s_waitcnt lgkmcnt(0)
	v_mfma_f32_16x16x32_bf16 v[108:111], v[196:199], v[144:147], 0
	v_mfma_f32_16x16x32_bf16 v[104:107], v[210:213], v[144:147], 0
	v_mfma_f32_16x16x32_bf16 v[92:95], v[196:199], v[152:155], 0
	v_mfma_f32_16x16x32_bf16 v[88:91], v[210:213], v[152:155], 0
	v_mfma_f32_16x16x32_bf16 v[76:79], v[196:199], v[180:183], 0
	v_mfma_f32_16x16x32_bf16 v[72:75], v[210:213], v[180:183], 0
	v_mfma_f32_16x16x32_bf16 v[68:71], v[196:199], v[188:191], 0
	v_mfma_f32_16x16x32_bf16 v[64:67], v[210:213], v[188:191], 0
	v_mfma_f32_16x16x32_bf16 v[108:111], v[200:203], v[148:151], v[108:111]
	v_mfma_f32_16x16x32_bf16 v[104:107], v[214:217], v[148:151], v[104:107]
	v_mfma_f32_16x16x32_bf16 v[92:95], v[200:203], v[156:159], v[92:95]
	v_mfma_f32_16x16x32_bf16 v[88:91], v[214:217], v[156:159], v[88:91]
	v_mfma_f32_16x16x32_bf16 v[76:79], v[200:203], v[184:187], v[76:79]
	v_mfma_f32_16x16x32_bf16 v[72:75], v[214:217], v[184:187], v[72:75]
	v_mfma_f32_16x16x32_bf16 v[68:71], v[200:203], v[192:195], v[68:71]
	v_mfma_f32_16x16x32_bf16 v[64:67], v[214:217], v[192:195], v[64:67]
	s_mov_b32 m0, s21
	s_add_u32 s100, s8, 0x80
	s_addc_u32 s101, s9, 0
	s_barrier
	ds_read_b128 v[144:147], v209 offset:16384
	ds_read_b128 v[148:151], v209 offset:17408
	ds_read_b128 v[152:155], v209 offset:18432
	ds_read_b128 v[156:159], v209 offset:19456
	ds_read_b128 v[180:183], v209 offset:20480
	ds_read_b128 v[184:187], v209 offset:21504
	ds_read_b128 v[188:191], v209 offset:22528
	global_load_lds_dwordx4 v160, s[8:9]
	s_mov_b32 m0, s55
	ds_read_b128 v[192:195], v209 offset:23552
	global_load_lds_dwordx4 v162, s[8:9]
	s_barrier
	s_waitcnt lgkmcnt(0)
	v_mfma_f32_16x16x32_bf16 v[60:63], v[128:131], v[144:147], 0
	v_mfma_f32_16x16x32_bf16 v[56:59], v[136:139], v[144:147], 0
	v_mfma_f32_16x16x32_bf16 v[52:55], v[128:131], v[152:155], 0
	v_mfma_f32_16x16x32_bf16 v[48:51], v[136:139], v[152:155], 0
	v_mfma_f32_16x16x32_bf16 v[36:39], v[128:131], v[180:183], 0
	v_mfma_f32_16x16x32_bf16 v[32:35], v[136:139], v[180:183], 0
	v_mfma_f32_16x16x32_bf16 v[20:23], v[128:131], v[188:191], 0
	v_mfma_f32_16x16x32_bf16 v[16:19], v[136:139], v[188:191], 0
	v_mfma_f32_16x16x32_bf16 v[60:63], v[132:135], v[148:151], v[60:63]
	v_mfma_f32_16x16x32_bf16 v[56:59], v[140:143], v[148:151], v[56:59]
	v_mfma_f32_16x16x32_bf16 v[52:55], v[132:135], v[156:159], v[52:55]
	v_mfma_f32_16x16x32_bf16 v[48:51], v[140:143], v[156:159], v[48:51]
	v_mfma_f32_16x16x32_bf16 v[36:39], v[132:135], v[184:187], v[36:39]
	v_mfma_f32_16x16x32_bf16 v[32:35], v[140:143], v[184:187], v[32:35]
	v_mfma_f32_16x16x32_bf16 v[20:23], v[132:135], v[192:195], v[20:23]
	v_mfma_f32_16x16x32_bf16 v[16:19], v[140:143], v[192:195], v[16:19]
	s_barrier
	s_add_i32 m0, s54, 0x14000
	s_add_u32 s64, s2, 0x40000
	s_addc_u32 s65, s3, 0
	global_load_lds_dwordx4 v160, s[64:65]
	s_add_i32 m0, s54, 0x16000
	s_add_u32 s8, s8, 0x40000
	s_addc_u32 s9, s9, 0
	global_load_lds_dwordx4 v162, s[64:65]
	s_waitcnt vmcnt(6)
	s_barrier
	v_mfma_f32_16x16x32_bf16 v[44:47], v[196:199], v[144:147], 0
	v_mfma_f32_16x16x32_bf16 v[40:43], v[210:213], v[144:147], 0
	v_mfma_f32_16x16x32_bf16 v[28:31], v[196:199], v[152:155], 0
	v_mfma_f32_16x16x32_bf16 v[24:27], v[210:213], v[152:155], 0
	v_mfma_f32_16x16x32_bf16 v[12:15], v[196:199], v[180:183], 0
	v_mfma_f32_16x16x32_bf16 v[8:11], v[210:213], v[180:183], 0
	v_mfma_f32_16x16x32_bf16 v[4:7], v[196:199], v[188:191], 0
	v_mfma_f32_16x16x32_bf16 v[0:3], v[210:213], v[188:191], 0
	v_mfma_f32_16x16x32_bf16 v[44:47], v[200:203], v[148:151], v[44:47]
	v_mfma_f32_16x16x32_bf16 v[40:43], v[214:217], v[148:151], v[40:43]
	v_mfma_f32_16x16x32_bf16 v[28:31], v[200:203], v[156:159], v[28:31]
	v_mfma_f32_16x16x32_bf16 v[24:27], v[214:217], v[156:159], v[24:27]
	v_mfma_f32_16x16x32_bf16 v[12:15], v[200:203], v[184:187], v[12:15]
	v_mfma_f32_16x16x32_bf16 v[8:11], v[214:217], v[184:187], v[8:11]
	v_mfma_f32_16x16x32_bf16 v[4:7], v[200:203], v[192:195], v[4:7]
	v_mfma_f32_16x16x32_bf16 v[0:3], v[214:217], v[192:195], v[0:3]
	s_barrier
	ds_read_b128 v[128:131], v208 offset:32768
	ds_read_b128 v[132:135], v208 offset:33792
	ds_read_b128 v[136:139], v208 offset:34816
	ds_read_b128 v[140:143], v208 offset:35840
	ds_read_b128 v[144:147], v209 offset:32768
	ds_read_b128 v[148:151], v209 offset:33792
	ds_read_b128 v[152:155], v209 offset:34816
	ds_read_b128 v[156:159], v209 offset:35840
	ds_read_b128 v[180:183], v209 offset:36864
	ds_read_b128 v[184:187], v209 offset:37888
	ds_read_b128 v[188:191], v209 offset:38912
	ds_read_b128 v[192:195], v209 offset:39936
	s_waitcnt lgkmcnt(8)
	s_barrier
	s_waitcnt lgkmcnt(0)
	v_mfma_f32_16x16x32_bf16 v[124:127], v[128:131], v[144:147], v[124:127]
	v_mfma_f32_16x16x32_bf16 v[120:123], v[136:139], v[144:147], v[120:123]
	v_mfma_f32_16x16x32_bf16 v[116:119], v[128:131], v[152:155], v[116:119]
	v_mfma_f32_16x16x32_bf16 v[112:115], v[136:139], v[152:155], v[112:115]
	v_mfma_f32_16x16x32_bf16 v[100:103], v[128:131], v[180:183], v[100:103]
	v_mfma_f32_16x16x32_bf16 v[96:99], v[136:139], v[180:183], v[96:99]
	v_mfma_f32_16x16x32_bf16 v[84:87], v[128:131], v[188:191], v[84:87]
	v_mfma_f32_16x16x32_bf16 v[80:83], v[136:139], v[188:191], v[80:83]
	v_mfma_f32_16x16x32_bf16 v[124:127], v[132:135], v[148:151], v[124:127]
	v_mfma_f32_16x16x32_bf16 v[120:123], v[140:143], v[148:151], v[120:123]
	v_mfma_f32_16x16x32_bf16 v[116:119], v[132:135], v[156:159], v[116:119]
	v_mfma_f32_16x16x32_bf16 v[112:115], v[140:143], v[156:159], v[112:115]
	v_mfma_f32_16x16x32_bf16 v[100:103], v[132:135], v[184:187], v[100:103]
	v_mfma_f32_16x16x32_bf16 v[96:99], v[140:143], v[184:187], v[96:99]
	v_mfma_f32_16x16x32_bf16 v[84:87], v[132:135], v[192:195], v[84:87]
	v_mfma_f32_16x16x32_bf16 v[80:83], v[140:143], v[192:195], v[80:83]
	s_barrier
	s_mov_b32 m0, s56
	ds_read_b128 v[196:199], v208 offset:49152
	ds_read_b128 v[200:203], v208 offset:50176
	ds_read_b128 v[210:213], v208 offset:51200
	global_load_lds_dwordx4 v160, s[8:9]
	s_mov_b32 m0, s57
	ds_read_b128 v[214:217], v208 offset:52224
	global_load_lds_dwordx4 v162, s[8:9]
	s_add_i32 m0, s54, 0x18000
	s_nop 0
	global_load_lds_dwordx4 v160, s[98:99]
	s_add_i32 m0, s54, 0x1a000
	s_nop 0
	global_load_lds_dwordx4 v162, s[98:99]
	s_barrier
	s_waitcnt lgkmcnt(0)
	v_mfma_f32_16x16x32_bf16 v[108:111], v[196:199], v[144:147], v[108:111]
	v_mfma_f32_16x16x32_bf16 v[104:107], v[210:213], v[144:147], v[104:107]
	v_mfma_f32_16x16x32_bf16 v[92:95], v[196:199], v[152:155], v[92:95]
	v_mfma_f32_16x16x32_bf16 v[88:91], v[210:213], v[152:155], v[88:91]
	v_mfma_f32_16x16x32_bf16 v[76:79], v[196:199], v[180:183], v[76:79]
	v_mfma_f32_16x16x32_bf16 v[72:75], v[210:213], v[180:183], v[72:75]
	v_mfma_f32_16x16x32_bf16 v[68:71], v[196:199], v[188:191], v[68:71]
	v_mfma_f32_16x16x32_bf16 v[64:67], v[210:213], v[188:191], v[64:67]
	v_mfma_f32_16x16x32_bf16 v[108:111], v[200:203], v[148:151], v[108:111]
	v_mfma_f32_16x16x32_bf16 v[104:107], v[214:217], v[148:151], v[104:107]
	v_mfma_f32_16x16x32_bf16 v[92:95], v[200:203], v[156:159], v[92:95]
	v_mfma_f32_16x16x32_bf16 v[88:91], v[214:217], v[156:159], v[88:91]
	v_mfma_f32_16x16x32_bf16 v[76:79], v[200:203], v[184:187], v[76:79]
	v_mfma_f32_16x16x32_bf16 v[72:75], v[214:217], v[184:187], v[72:75]
	v_mfma_f32_16x16x32_bf16 v[68:71], v[200:203], v[192:195], v[68:71]
	v_mfma_f32_16x16x32_bf16 v[64:67], v[214:217], v[192:195], v[64:67]
	s_mov_b32 m0, s60
	s_barrier
	ds_read_b128 v[144:147], v209 offset:49152
	ds_read_b128 v[148:151], v209 offset:50176
	ds_read_b128 v[152:155], v209 offset:51200
	ds_read_b128 v[156:159], v209 offset:52224
	ds_read_b128 v[180:183], v209 offset:53248
	ds_read_b128 v[184:187], v209 offset:54272
	ds_read_b128 v[188:191], v209 offset:55296
	global_load_lds_dwordx4 v160, s[100:101]
	s_mov_b32 m0, s61
	ds_read_b128 v[192:195], v209 offset:56320
	global_load_lds_dwordx4 v162, s[100:101]
	s_barrier
	s_waitcnt lgkmcnt(0)
	v_mfma_f32_16x16x32_bf16 v[60:63], v[128:131], v[144:147], v[60:63]
	v_mfma_f32_16x16x32_bf16 v[56:59], v[136:139], v[144:147], v[56:59]
	v_mfma_f32_16x16x32_bf16 v[52:55], v[128:131], v[152:155], v[52:55]
	v_mfma_f32_16x16x32_bf16 v[48:51], v[136:139], v[152:155], v[48:51]
	v_mfma_f32_16x16x32_bf16 v[36:39], v[128:131], v[180:183], v[36:39]
	v_mfma_f32_16x16x32_bf16 v[32:35], v[136:139], v[180:183], v[32:35]
	v_mfma_f32_16x16x32_bf16 v[20:23], v[128:131], v[188:191], v[20:23]
	v_mfma_f32_16x16x32_bf16 v[16:19], v[136:139], v[188:191], v[16:19]
	v_mfma_f32_16x16x32_bf16 v[60:63], v[132:135], v[148:151], v[60:63]
	v_mfma_f32_16x16x32_bf16 v[56:59], v[140:143], v[148:151], v[56:59]
	v_mfma_f32_16x16x32_bf16 v[52:55], v[132:135], v[156:159], v[52:55]
	v_mfma_f32_16x16x32_bf16 v[48:51], v[140:143], v[156:159], v[48:51]
	v_mfma_f32_16x16x32_bf16 v[36:39], v[132:135], v[184:187], v[36:39]
	v_mfma_f32_16x16x32_bf16 v[32:35], v[140:143], v[184:187], v[32:35]
	v_mfma_f32_16x16x32_bf16 v[20:23], v[132:135], v[192:195], v[20:23]
	v_mfma_f32_16x16x32_bf16 v[16:19], v[140:143], v[192:195], v[16:19]
	s_barrier
	s_add_i32 m0, s54, 0x1c000
	s_add_u32 s2, s2, 0x40080
	s_addc_u32 s3, s3, 0
	global_load_lds_dwordx4 v160, s[2:3]
	s_add_i32 m0, s54, 0x1e000
	s_add_i32 s41, s41, 2
	global_load_lds_dwordx4 v162, s[2:3]
	s_waitcnt vmcnt(6)
	s_barrier
	v_mfma_f32_16x16x32_bf16 v[44:47], v[196:199], v[144:147], v[44:47]
	v_mfma_f32_16x16x32_bf16 v[40:43], v[210:213], v[144:147], v[40:43]
	v_mfma_f32_16x16x32_bf16 v[28:31], v[196:199], v[152:155], v[28:31]
	v_mfma_f32_16x16x32_bf16 v[24:27], v[210:213], v[152:155], v[24:27]
	v_mfma_f32_16x16x32_bf16 v[12:15], v[196:199], v[180:183], v[12:15]
	v_mfma_f32_16x16x32_bf16 v[8:11], v[210:213], v[180:183], v[8:11]
	v_mfma_f32_16x16x32_bf16 v[4:7], v[196:199], v[188:191], v[4:7]
	v_mfma_f32_16x16x32_bf16 v[0:3], v[210:213], v[188:191], v[0:3]
	v_mfma_f32_16x16x32_bf16 v[44:47], v[200:203], v[148:151], v[44:47]
	v_mfma_f32_16x16x32_bf16 v[40:43], v[214:217], v[148:151], v[40:43]
	v_mfma_f32_16x16x32_bf16 v[28:31], v[200:203], v[156:159], v[28:31]
	v_mfma_f32_16x16x32_bf16 v[24:27], v[214:217], v[156:159], v[24:27]
	v_mfma_f32_16x16x32_bf16 v[12:15], v[200:203], v[184:187], v[12:15]
	v_mfma_f32_16x16x32_bf16 v[8:11], v[214:217], v[184:187], v[8:11]
	v_mfma_f32_16x16x32_bf16 v[4:7], v[200:203], v[192:195], v[4:7]
	v_mfma_f32_16x16x32_bf16 v[0:3], v[214:217], v[192:195], v[0:3]
	s_add_u32 s6, s6, 0x100
	s_addc_u32 s7, s7, 0
	s_add_u32 s39, s39, 0x100
	s_addc_u32 s40, s40, 0
	s_cmp_gt_u32 s41, 13
	s_barrier
.LBB0_355:
	s_add_u32 s2, s6, 0xfffc0080
	s_addc_u32 s3, s7, -1
	ds_read_b128 v[128:131], v208
	ds_read_b128 v[132:135], v208 offset:1024
	ds_read_b128 v[136:139], v208 offset:2048
	ds_read_b128 v[140:143], v208 offset:3072
	s_cmp_eq_u32 s41, 12
	s_cselect_b32 s9, s1, s3
	s_cselect_b32 s8, s31, s2
	s_cselect_b32 s3, s29, s40
	s_cselect_b32 s2, s38, s39
	ds_read_b128 v[144:147], v209
	ds_read_b128 v[148:151], v209 offset:1024
	ds_read_b128 v[152:155], v209 offset:2048
	ds_read_b128 v[156:159], v209 offset:3072
	ds_read_b128 v[180:183], v209 offset:4096
	ds_read_b128 v[184:187], v209 offset:5120
	ds_read_b128 v[188:191], v209 offset:6144
	ds_read_b128 v[192:195], v209 offset:7168
	s_waitcnt lgkmcnt(8)
	s_barrier
	s_waitcnt lgkmcnt(0)
	v_mfma_f32_16x16x32_bf16 v[124:127], v[128:131], v[144:147], v[124:127]
	v_mfma_f32_16x16x32_bf16 v[120:123], v[136:139], v[144:147], v[120:123]
	v_mfma_f32_16x16x32_bf16 v[116:119], v[128:131], v[152:155], v[116:119]
	v_mfma_f32_16x16x32_bf16 v[112:115], v[136:139], v[152:155], v[112:115]
	v_mfma_f32_16x16x32_bf16 v[100:103], v[128:131], v[180:183], v[100:103]
	v_mfma_f32_16x16x32_bf16 v[96:99], v[136:139], v[180:183], v[96:99]
	v_mfma_f32_16x16x32_bf16 v[84:87], v[128:131], v[188:191], v[84:87]
	v_mfma_f32_16x16x32_bf16 v[80:83], v[136:139], v[188:191], v[80:83]
	v_mfma_f32_16x16x32_bf16 v[124:127], v[132:135], v[148:151], v[124:127]
	v_mfma_f32_16x16x32_bf16 v[120:123], v[140:143], v[148:151], v[120:123]
	v_mfma_f32_16x16x32_bf16 v[116:119], v[132:135], v[156:159], v[116:119]
	v_mfma_f32_16x16x32_bf16 v[112:115], v[140:143], v[156:159], v[112:115]
	v_mfma_f32_16x16x32_bf16 v[100:103], v[132:135], v[184:187], v[100:103]
	v_mfma_f32_16x16x32_bf16 v[96:99], v[140:143], v[184:187], v[96:99]
	v_mfma_f32_16x16x32_bf16 v[84:87], v[132:135], v[192:195], v[84:87]
	v_mfma_f32_16x16x32_bf16 v[80:83], v[140:143], v[192:195], v[80:83]
	s_barrier
	s_add_i32 m0, s21, 0xc000
	ds_read_b128 v[196:199], v208 offset:16384
	ds_read_b128 v[200:203], v208 offset:17408
	ds_read_b128 v[210:213], v208 offset:18432
	global_load_lds_dwordx4 v164, s[6:7]
	s_add_i32 m0, s21, 0xe000
	ds_read_b128 v[214:217], v208 offset:19456
	global_load_lds_dwordx4 v166, s[6:7]
	s_add_u32 s98, s2, 0x80
	s_addc_u32 s99, s3, 0
	s_add_i32 m0, s54, 0x10000
	s_nop 0
	global_load_lds_dwordx4 v160, s[2:3]
	s_add_i32 m0, s54, 0x12000
	s_nop 0
	global_load_lds_dwordx4 v162, s[2:3]
	s_barrier
	s_waitcnt lgkmcnt(0)
	v_mfma_f32_16x16x32_bf16 v[108:111], v[196:199], v[144:147], v[108:111]
	v_mfma_f32_16x16x32_bf16 v[104:107], v[210:213], v[144:147], v[104:107]
	v_mfma_f32_16x16x32_bf16 v[92:95], v[196:199], v[152:155], v[92:95]
	v_mfma_f32_16x16x32_bf16 v[88:91], v[210:213], v[152:155], v[88:91]
	v_mfma_f32_16x16x32_bf16 v[76:79], v[196:199], v[180:183], v[76:79]
	v_mfma_f32_16x16x32_bf16 v[72:75], v[210:213], v[180:183], v[72:75]
	v_mfma_f32_16x16x32_bf16 v[68:71], v[196:199], v[188:191], v[68:71]
	v_mfma_f32_16x16x32_bf16 v[64:67], v[210:213], v[188:191], v[64:67]
	v_mfma_f32_16x16x32_bf16 v[108:111], v[200:203], v[148:151], v[108:111]
	v_mfma_f32_16x16x32_bf16 v[104:107], v[214:217], v[148:151], v[104:107]
	v_mfma_f32_16x16x32_bf16 v[92:95], v[200:203], v[156:159], v[92:95]
	v_mfma_f32_16x16x32_bf16 v[88:91], v[214:217], v[156:159], v[88:91]
	v_mfma_f32_16x16x32_bf16 v[76:79], v[200:203], v[184:187], v[76:79]
	v_mfma_f32_16x16x32_bf16 v[72:75], v[214:217], v[184:187], v[72:75]
	v_mfma_f32_16x16x32_bf16 v[68:71], v[200:203], v[192:195], v[68:71]
	v_mfma_f32_16x16x32_bf16 v[64:67], v[214:217], v[192:195], v[64:67]
	s_mov_b32 m0, s21
	s_add_u32 s100, s8, 0x80
	s_addc_u32 s101, s9, 0
	s_barrier
	ds_read_b128 v[144:147], v209 offset:16384
	ds_read_b128 v[148:151], v209 offset:17408
	ds_read_b128 v[152:155], v209 offset:18432
	ds_read_b128 v[156:159], v209 offset:19456
	ds_read_b128 v[180:183], v209 offset:20480
	ds_read_b128 v[184:187], v209 offset:21504
	ds_read_b128 v[188:191], v209 offset:22528
	global_load_lds_dwordx4 v160, s[8:9]
	s_mov_b32 m0, s55
	ds_read_b128 v[192:195], v209 offset:23552
	global_load_lds_dwordx4 v162, s[8:9]
	s_barrier
	s_waitcnt lgkmcnt(0)
	v_mfma_f32_16x16x32_bf16 v[60:63], v[128:131], v[144:147], v[60:63]
	v_mfma_f32_16x16x32_bf16 v[56:59], v[136:139], v[144:147], v[56:59]
	v_mfma_f32_16x16x32_bf16 v[52:55], v[128:131], v[152:155], v[52:55]
	v_mfma_f32_16x16x32_bf16 v[48:51], v[136:139], v[152:155], v[48:51]
	v_mfma_f32_16x16x32_bf16 v[36:39], v[128:131], v[180:183], v[36:39]
	v_mfma_f32_16x16x32_bf16 v[32:35], v[136:139], v[180:183], v[32:35]
	v_mfma_f32_16x16x32_bf16 v[20:23], v[128:131], v[188:191], v[20:23]
	v_mfma_f32_16x16x32_bf16 v[16:19], v[136:139], v[188:191], v[16:19]
	v_mfma_f32_16x16x32_bf16 v[60:63], v[132:135], v[148:151], v[60:63]
	v_mfma_f32_16x16x32_bf16 v[56:59], v[140:143], v[148:151], v[56:59]
	v_mfma_f32_16x16x32_bf16 v[52:55], v[132:135], v[156:159], v[52:55]
	v_mfma_f32_16x16x32_bf16 v[48:51], v[140:143], v[156:159], v[48:51]
	v_mfma_f32_16x16x32_bf16 v[36:39], v[132:135], v[184:187], v[36:39]
	v_mfma_f32_16x16x32_bf16 v[32:35], v[140:143], v[184:187], v[32:35]
	v_mfma_f32_16x16x32_bf16 v[20:23], v[132:135], v[192:195], v[20:23]
	v_mfma_f32_16x16x32_bf16 v[16:19], v[140:143], v[192:195], v[16:19]
	s_barrier
	s_add_i32 m0, s54, 0x14000
	s_add_u32 s64, s2, 0x40000
	s_addc_u32 s65, s3, 0
	global_load_lds_dwordx4 v160, s[64:65]
	s_add_i32 m0, s54, 0x16000
	s_add_u32 s8, s8, 0x40000
	s_addc_u32 s9, s9, 0
	global_load_lds_dwordx4 v162, s[64:65]
	s_waitcnt vmcnt(6)
	s_barrier
	v_mfma_f32_16x16x32_bf16 v[44:47], v[196:199], v[144:147], v[44:47]
	v_mfma_f32_16x16x32_bf16 v[40:43], v[210:213], v[144:147], v[40:43]
	v_mfma_f32_16x16x32_bf16 v[28:31], v[196:199], v[152:155], v[28:31]
	v_mfma_f32_16x16x32_bf16 v[24:27], v[210:213], v[152:155], v[24:27]
	v_mfma_f32_16x16x32_bf16 v[12:15], v[196:199], v[180:183], v[12:15]
	v_mfma_f32_16x16x32_bf16 v[8:11], v[210:213], v[180:183], v[8:11]
	v_mfma_f32_16x16x32_bf16 v[4:7], v[196:199], v[188:191], v[4:7]
	v_mfma_f32_16x16x32_bf16 v[0:3], v[210:213], v[188:191], v[0:3]
	v_mfma_f32_16x16x32_bf16 v[44:47], v[200:203], v[148:151], v[44:47]
	v_mfma_f32_16x16x32_bf16 v[40:43], v[214:217], v[148:151], v[40:43]
	v_mfma_f32_16x16x32_bf16 v[28:31], v[200:203], v[156:159], v[28:31]
	v_mfma_f32_16x16x32_bf16 v[24:27], v[214:217], v[156:159], v[24:27]
	v_mfma_f32_16x16x32_bf16 v[12:15], v[200:203], v[184:187], v[12:15]
	v_mfma_f32_16x16x32_bf16 v[8:11], v[214:217], v[184:187], v[8:11]
	v_mfma_f32_16x16x32_bf16 v[4:7], v[200:203], v[192:195], v[4:7]
	v_mfma_f32_16x16x32_bf16 v[0:3], v[214:217], v[192:195], v[0:3]
	s_barrier
	ds_read_b128 v[128:131], v208 offset:32768
	ds_read_b128 v[132:135], v208 offset:33792
	ds_read_b128 v[136:139], v208 offset:34816
	ds_read_b128 v[140:143], v208 offset:35840
	ds_read_b128 v[144:147], v209 offset:32768
	ds_read_b128 v[148:151], v209 offset:33792
	ds_read_b128 v[152:155], v209 offset:34816
	ds_read_b128 v[156:159], v209 offset:35840
	ds_read_b128 v[180:183], v209 offset:36864
	ds_read_b128 v[184:187], v209 offset:37888
	ds_read_b128 v[188:191], v209 offset:38912
	ds_read_b128 v[192:195], v209 offset:39936
	s_waitcnt lgkmcnt(8)
	s_barrier
	s_waitcnt lgkmcnt(0)
	v_mfma_f32_16x16x32_bf16 v[124:127], v[128:131], v[144:147], v[124:127]
	v_mfma_f32_16x16x32_bf16 v[120:123], v[136:139], v[144:147], v[120:123]
	v_mfma_f32_16x16x32_bf16 v[116:119], v[128:131], v[152:155], v[116:119]
	v_mfma_f32_16x16x32_bf16 v[112:115], v[136:139], v[152:155], v[112:115]
	v_mfma_f32_16x16x32_bf16 v[100:103], v[128:131], v[180:183], v[100:103]
	v_mfma_f32_16x16x32_bf16 v[96:99], v[136:139], v[180:183], v[96:99]
	v_mfma_f32_16x16x32_bf16 v[84:87], v[128:131], v[188:191], v[84:87]
	v_mfma_f32_16x16x32_bf16 v[80:83], v[136:139], v[188:191], v[80:83]
	v_mfma_f32_16x16x32_bf16 v[124:127], v[132:135], v[148:151], v[124:127]
	v_mfma_f32_16x16x32_bf16 v[120:123], v[140:143], v[148:151], v[120:123]
	v_mfma_f32_16x16x32_bf16 v[116:119], v[132:135], v[156:159], v[116:119]
	v_mfma_f32_16x16x32_bf16 v[112:115], v[140:143], v[156:159], v[112:115]
	v_mfma_f32_16x16x32_bf16 v[100:103], v[132:135], v[184:187], v[100:103]
	v_mfma_f32_16x16x32_bf16 v[96:99], v[140:143], v[184:187], v[96:99]
	v_mfma_f32_16x16x32_bf16 v[84:87], v[132:135], v[192:195], v[84:87]
	v_mfma_f32_16x16x32_bf16 v[80:83], v[140:143], v[192:195], v[80:83]
	s_barrier
	s_mov_b32 m0, s56
	ds_read_b128 v[196:199], v208 offset:49152
	ds_read_b128 v[200:203], v208 offset:50176
	ds_read_b128 v[210:213], v208 offset:51200
	global_load_lds_dwordx4 v160, s[8:9]
	s_mov_b32 m0, s57
	ds_read_b128 v[214:217], v208 offset:52224
	global_load_lds_dwordx4 v162, s[8:9]
	s_add_i32 m0, s54, 0x18000
	s_nop 0
	global_load_lds_dwordx4 v160, s[98:99]
	s_add_i32 m0, s54, 0x1a000
	s_nop 0
	global_load_lds_dwordx4 v162, s[98:99]
	s_barrier
	s_waitcnt lgkmcnt(0)
	v_mfma_f32_16x16x32_bf16 v[108:111], v[196:199], v[144:147], v[108:111]
	v_mfma_f32_16x16x32_bf16 v[104:107], v[210:213], v[144:147], v[104:107]
	v_mfma_f32_16x16x32_bf16 v[92:95], v[196:199], v[152:155], v[92:95]
	v_mfma_f32_16x16x32_bf16 v[88:91], v[210:213], v[152:155], v[88:91]
	v_mfma_f32_16x16x32_bf16 v[76:79], v[196:199], v[180:183], v[76:79]
	v_mfma_f32_16x16x32_bf16 v[72:75], v[210:213], v[180:183], v[72:75]
	v_mfma_f32_16x16x32_bf16 v[68:71], v[196:199], v[188:191], v[68:71]
	v_mfma_f32_16x16x32_bf16 v[64:67], v[210:213], v[188:191], v[64:67]
	v_mfma_f32_16x16x32_bf16 v[108:111], v[200:203], v[148:151], v[108:111]
	v_mfma_f32_16x16x32_bf16 v[104:107], v[214:217], v[148:151], v[104:107]
	v_mfma_f32_16x16x32_bf16 v[92:95], v[200:203], v[156:159], v[92:95]
	v_mfma_f32_16x16x32_bf16 v[88:91], v[214:217], v[156:159], v[88:91]
	v_mfma_f32_16x16x32_bf16 v[76:79], v[200:203], v[184:187], v[76:79]
	v_mfma_f32_16x16x32_bf16 v[72:75], v[214:217], v[184:187], v[72:75]
	v_mfma_f32_16x16x32_bf16 v[68:71], v[200:203], v[192:195], v[68:71]
	v_mfma_f32_16x16x32_bf16 v[64:67], v[214:217], v[192:195], v[64:67]
	s_mov_b32 m0, s60
	s_barrier
	ds_read_b128 v[144:147], v209 offset:49152
	ds_read_b128 v[148:151], v209 offset:50176
	ds_read_b128 v[152:155], v209 offset:51200
	ds_read_b128 v[156:159], v209 offset:52224
	ds_read_b128 v[180:183], v209 offset:53248
	ds_read_b128 v[184:187], v209 offset:54272
	ds_read_b128 v[188:191], v209 offset:55296
	global_load_lds_dwordx4 v160, s[100:101]
	s_mov_b32 m0, s61
	ds_read_b128 v[192:195], v209 offset:56320
	global_load_lds_dwordx4 v162, s[100:101]
	s_barrier
	s_waitcnt lgkmcnt(0)
	v_mfma_f32_16x16x32_bf16 v[60:63], v[128:131], v[144:147], v[60:63]
	v_mfma_f32_16x16x32_bf16 v[56:59], v[136:139], v[144:147], v[56:59]
	v_mfma_f32_16x16x32_bf16 v[52:55], v[128:131], v[152:155], v[52:55]
	v_mfma_f32_16x16x32_bf16 v[48:51], v[136:139], v[152:155], v[48:51]
	v_mfma_f32_16x16x32_bf16 v[36:39], v[128:131], v[180:183], v[36:39]
	v_mfma_f32_16x16x32_bf16 v[32:35], v[136:139], v[180:183], v[32:35]
	v_mfma_f32_16x16x32_bf16 v[20:23], v[128:131], v[188:191], v[20:23]
	v_mfma_f32_16x16x32_bf16 v[16:19], v[136:139], v[188:191], v[16:19]
	v_mfma_f32_16x16x32_bf16 v[60:63], v[132:135], v[148:151], v[60:63]
	v_mfma_f32_16x16x32_bf16 v[56:59], v[140:143], v[148:151], v[56:59]
	v_mfma_f32_16x16x32_bf16 v[52:55], v[132:135], v[156:159], v[52:55]
	v_mfma_f32_16x16x32_bf16 v[48:51], v[140:143], v[156:159], v[48:51]
	v_mfma_f32_16x16x32_bf16 v[36:39], v[132:135], v[184:187], v[36:39]
	v_mfma_f32_16x16x32_bf16 v[32:35], v[140:143], v[184:187], v[32:35]
	v_mfma_f32_16x16x32_bf16 v[20:23], v[132:135], v[192:195], v[20:23]
	v_mfma_f32_16x16x32_bf16 v[16:19], v[140:143], v[192:195], v[16:19]
	s_barrier
	s_add_i32 m0, s54, 0x1c000
	s_add_u32 s2, s2, 0x40080
	s_addc_u32 s3, s3, 0
	global_load_lds_dwordx4 v160, s[2:3]
	s_add_i32 m0, s54, 0x1e000
	s_add_i32 s41, s41, 2
	global_load_lds_dwordx4 v162, s[2:3]
	s_waitcnt vmcnt(6)
	s_barrier
	v_mfma_f32_16x16x32_bf16 v[44:47], v[196:199], v[144:147], v[44:47]
	v_mfma_f32_16x16x32_bf16 v[40:43], v[210:213], v[144:147], v[40:43]
	v_mfma_f32_16x16x32_bf16 v[28:31], v[196:199], v[152:155], v[28:31]
	v_mfma_f32_16x16x32_bf16 v[24:27], v[210:213], v[152:155], v[24:27]
	v_mfma_f32_16x16x32_bf16 v[12:15], v[196:199], v[180:183], v[12:15]
	v_mfma_f32_16x16x32_bf16 v[8:11], v[210:213], v[180:183], v[8:11]
	v_mfma_f32_16x16x32_bf16 v[4:7], v[196:199], v[188:191], v[4:7]
	v_mfma_f32_16x16x32_bf16 v[0:3], v[210:213], v[188:191], v[0:3]
	v_mfma_f32_16x16x32_bf16 v[44:47], v[200:203], v[148:151], v[44:47]
	v_mfma_f32_16x16x32_bf16 v[40:43], v[214:217], v[148:151], v[40:43]
	v_mfma_f32_16x16x32_bf16 v[28:31], v[200:203], v[156:159], v[28:31]
	v_mfma_f32_16x16x32_bf16 v[24:27], v[214:217], v[156:159], v[24:27]
	v_mfma_f32_16x16x32_bf16 v[12:15], v[200:203], v[184:187], v[12:15]
	v_mfma_f32_16x16x32_bf16 v[8:11], v[214:217], v[184:187], v[8:11]
	v_mfma_f32_16x16x32_bf16 v[4:7], v[200:203], v[192:195], v[4:7]
	v_mfma_f32_16x16x32_bf16 v[0:3], v[214:217], v[192:195], v[0:3]
	s_add_u32 s6, s6, 0x100
	s_addc_u32 s7, s7, 0
	s_add_u32 s39, s39, 0x100
	s_addc_u32 s40, s40, 0
	s_cmp_gt_u32 s41, 13
	s_barrier
	s_cbranch_scc0 .LBB0_355
	s_lshl_b32 s1, s0, 8
	v_mov_b32_e32 v211, v206
	v_mov_b32_e32 v210, v207
	s_add_i32 s1, s1, s59
	s_cmp_lt_i32 s20, 3
	v_add_u32_e32 v180, s1, v211
	s_mov_b64 s[2:3], -1
	s_cbranch_scc0 .LBB0_490
	s_cmp_gt_i32 s0, 15
	s_cselect_b64 s[2:3], -1, 0
	s_cmp_lt_i32 s0, 16
	s_cselect_b64 s[38:39], -1, 0
	s_cmp_eq_u32 s20, 2
	s_cselect_b64 s[8:9], -1, 0
	s_cmp_lg_u32 s20, 2
	s_cselect_b64 s[0:1], -1, 0
	s_and_b64 s[40:41], s[8:9], s[22:23]
	v_lshlrev_b32_e32 v182, 2, v210
	s_mov_b64 s[6:7], -1
	s_and_b64 vcc, exec, s[40:41]
	v_ashrrev_i32_e32 v183, 31, v182
	s_cbranch_vccnz .LBB0_447
	s_and_b64 s[6:7], s[8:9], exec
	s_cselect_b32 s6, s46, s44
	s_cselect_b32 s7, s47, s45
	v_mov_b32_e32 v128, s7
	v_mov_b32_e32 v129, s6
	v_lshl_add_u64 v[128:129], v[182:183], 2, v[128:129]
	global_load_dwordx4 v[140:143], v[128:129], off
	global_load_dwordx4 v[136:139], v[128:129], off offset:64
	global_load_dwordx4 v[132:135], v[128:129], off offset:128
	s_nop 0
	global_load_dwordx4 v[128:131], v[128:129], off offset:192
	v_mul_f32_e32 v144, v125, v125
	v_mul_f32_e32 v145, v127, v127
	v_fmac_f32_e32 v144, v124, v124
	v_fmac_f32_e32 v145, v126, v126
	v_add_f32_e32 v144, v144, v145
	v_mul_f32_e32 v145, v121, v121
	v_mul_f32_e32 v146, v123, v123
	v_fmac_f32_e32 v145, v120, v120
	v_fmac_f32_e32 v146, v122, v122
	v_add_f32_e32 v145, v145, v146
	v_add_f32_e32 v144, v144, v145
	v_mul_f32_e32 v145, v109, v109
	v_mul_f32_e32 v146, v111, v111
	v_fmac_f32_e32 v145, v108, v108
	v_fmac_f32_e32 v146, v110, v110
	v_add_f32_e32 v145, v145, v146
	v_add_f32_e32 v144, v144, v145
	v_mul_f32_e32 v145, v105, v105
	v_mul_f32_e32 v146, v107, v107
	v_fmac_f32_e32 v145, v104, v104
	v_fmac_f32_e32 v146, v106, v106
	v_add_f32_e32 v145, v145, v146
	v_add_f32_e32 v144, v144, v145
	v_mov_b32_e32 v145, v144
	s_nop 1
	v_permlane16_swap_b32_e32 v144, v145
	v_add_f32_e32 v144, v144, v145
	v_mov_b32_e32 v145, v144
	s_nop 1
	v_permlane32_swap_b32_e32 v144, v145
	v_add_f32_e32 v144, v144, v145
	v_fmamk_f32 v144, v144, 0x3c800000, v225
	v_cmp_gt_f32_e32 vcc, s93, v144
	v_mul_f32_e32 v145, 0x4b800000, v144
	v_and_b32_e32 v202, 63, v211
	v_cndmask_b32_e32 v144, v144, v145, vcc
	v_rsq_f32_e32 v144, v144
	v_cndmask_b32_e64 v168, 0, 1, s[2:3]
	v_cmp_ne_u32_e64 s[6:7], 1, v168
	v_lshlrev_b32_e32 v186, 7, v202
	v_mul_f32_e32 v145, 0x45800000, v144
	v_cndmask_b32_e32 v152, v144, v145, vcc
	v_pk_mul_f32 v[144:145], v[124:125], v[152:153] op_sel_hi:[1,0]
	v_pk_mul_f32 v[146:147], v[126:127], v[152:153] op_sel_hi:[1,0]
	v_pk_mul_f32 v[148:149], v[108:109], v[152:153] op_sel_hi:[1,0]
	v_pk_mul_f32 v[150:151], v[110:111], v[152:153] op_sel_hi:[1,0]
	v_pk_mul_f32 v[184:185], v[104:105], v[152:153] op_sel_hi:[1,0]
	s_andn2_b64 vcc, exec, s[2:3]
	s_waitcnt vmcnt(0)
	v_pk_mul_f32 v[158:159], v[142:143], v[146:147]
	v_pk_mul_f32 v[156:157], v[140:141], v[144:145]
	v_pk_mul_f32 v[144:145], v[120:121], v[152:153] op_sel_hi:[1,0]
	v_pk_mul_f32 v[146:147], v[122:123], v[152:153] op_sel_hi:[1,0]
	v_pk_mul_f32 v[152:153], v[106:107], v[152:153] op_sel_hi:[1,0]
	v_pk_mul_f32 v[146:147], v[138:139], v[146:147]
	v_pk_mul_f32 v[144:145], v[136:137], v[144:145]
	v_pk_mul_f32 v[150:151], v[134:135], v[150:151]
	v_pk_mul_f32 v[148:149], v[132:133], v[148:149]
	v_pk_mul_f32 v[154:155], v[130:131], v[152:153]
	v_pk_mul_f32 v[152:153], v[128:129], v[184:185]
	v_lshl_add_u64 v[184:185], v[182:183], 3, s[18:19]
	s_cbranch_vccnz .LBB0_360
	v_lshlrev_b32_e32 v168, 1, v180
	v_and_b32_e32 v168, 0xf80, v168
	v_lshl_add_u64 v[188:189], v[184:185], 0, v[168:169]
	global_load_dwordx4 v[190:193], v[188:189], off offset:16
	global_load_dwordx4 v[194:197], v[188:189], off
	v_mov_b32_e32 v187, v169
	s_waitcnt vmcnt(0)
	v_mul_f32_e32 v198, v158, v190
	v_mov_b32_e32 v188, v194
	v_mov_b32_e32 v189, v196
	v_mov_b32_e32 v196, v195
	v_mul_f32_e32 v200, v146, v191
	v_mul_f32_e32 v204, v146, v190
	v_mul_f32_e32 v212, v158, v191
	v_mov_b32_e32 v146, v159
	v_mov_b32_e32 v158, v147
	v_pk_mul_f32 v[194:195], v[144:145], v[196:197]
	v_pk_mul_f32 v[144:145], v[144:145], v[188:189]
	v_pk_mul_f32 v[190:191], v[146:147], v[192:193]
	v_pk_mul_f32 v[146:147], v[158:159], v[192:193]
	v_lshl_add_u64 v[192:193], v[184:185], 0, v[186:187]
	v_mov_b32_e32 v199, v190
	v_mov_b32_e32 v201, v191
	v_pk_fma_f32 v[190:191], v[156:157], v[188:189], v[194:195] neg_lo:[0,0,1] neg_hi:[0,0,1]
	v_pk_fma_f32 v[144:145], v[156:157], v[196:197], v[144:145]
	global_load_dwordx4 v[156:159], v[192:193], off offset:16
	s_nop 0
	global_load_dwordx4 v[192:195], v[192:193], off
	v_pk_add_f32 v[188:189], v[198:199], v[200:201] neg_lo:[0,1] neg_hi:[0,1]
	v_mov_b32_e32 v213, v147
	v_mov_b32_e32 v205, v146
	v_pk_add_f32 v[146:147], v[212:213], v[204:205]
	s_waitcnt vmcnt(0)
	v_mul_f32_e32 v198, v150, v156
	v_mul_f32_e32 v200, v154, v157
	v_mul_f32_e32 v156, v154, v156
	v_mov_b32_e32 v154, v151
	v_mov_b32_e32 v197, v194
	v_mov_b32_e32 v194, v193
	v_mul_f32_e32 v204, v150, v157
	v_pk_mul_f32 v[212:213], v[154:155], v[158:159]
	v_mov_b32_e32 v150, v155
	v_mov_b32_e32 v196, v192
	v_pk_mul_f32 v[192:193], v[152:153], v[194:195]
	v_mov_b32_e32 v199, v212
	v_mov_b32_e32 v201, v213
	v_pk_mul_f32 v[150:151], v[150:151], v[158:159]
	v_pk_mul_f32 v[152:153], v[152:153], v[196:197]
	v_pk_fma_f32 v[192:193], v[148:149], v[196:197], v[192:193] neg_lo:[0,0,1] neg_hi:[0,0,1]
	v_pk_add_f32 v[196:197], v[198:199], v[200:201] neg_lo:[0,1] neg_hi:[0,1]
	v_mov_b32_e32 v205, v151
	v_mov_b32_e32 v157, v150
	v_pk_fma_f32 v[152:153], v[148:149], v[194:195], v[152:153]
	v_pk_add_f32 v[154:155], v[204:205], v[156:157]
	v_mov_b32_e32 v148, v192
	v_mov_b32_e32 v149, v193
	v_mov_b32_e32 v150, v196
	v_mov_b32_e32 v151, v197
	v_mov_b32_e32 v156, v190
	v_mov_b32_e32 v157, v191
	v_mov_b32_e32 v158, v188
	v_mov_b32_e32 v159, v189

.LBB0_677:
	s_ashr_i32 s23, s22, 31
	v_cmp_lt_i64_e32 vcc, s[24:25], v[174:175]
	s_lshl_b64 s[24:25], s[22:23], 19
	s_add_u32 s24, s36, s24
	s_addc_u32 s25, s37, s25
	s_and_b64 s[26:27], vcc, exec
	s_cselect_b32 s1, s25, s9
	s_cselect_b32 s7, s24, s8
	s_ashr_i32 s21, s20, 31
	s_lshl_b64 s[26:27], s[20:21], 19
	s_add_u32 s26, s38, s26
	s_addc_u32 s27, s39, s27
	s_and_b64 s[28:29], vcc, exec
	s_cselect_b32 s21, s27, s3
	s_cselect_b32 s23, s26, s2
	s_add_u32 s8, s8, 0x40080
	s_addc_u32 s9, s9, 0
	s_add_u32 s56, s2, 0x100
	s_addc_u32 s57, s3, 0
	s_mov_b32 s58, -2
	s_add_u32 s2, s8, 0xfffc0080
	s_addc_u32 s3, s9, -1
	ds_read_b128 v[48:51], v206
	ds_read_b128 v[52:55], v206 offset:1024
	ds_read_b128 v[60:63], v206 offset:2048
	ds_read_b128 v[68:71], v206 offset:3072
	s_cmp_eq_u32 s58, 12
	s_cselect_b32 s29, s1, s3
	s_cselect_b32 s28, s7, s2
	s_cselect_b32 s3, s21, s57
	s_cselect_b32 s2, s23, s56
	ds_read_b128 v[72:75], v207
	ds_read_b128 v[76:79], v207 offset:1024
	ds_read_b128 v[80:83], v207 offset:2048
	ds_read_b128 v[84:87], v207 offset:3072
	ds_read_b128 v[160:163], v207 offset:4096
	ds_read_b128 v[164:167], v207 offset:5120
	ds_read_b128 v[192:195], v207 offset:6144
	ds_read_b128 v[196:199], v207 offset:7168
	s_waitcnt lgkmcnt(8)
	s_barrier
	s_waitcnt lgkmcnt(0)
	v_mfma_f32_16x16x32_bf16 v[156:159], v[48:51], v[72:75], 0
	v_mfma_f32_16x16x32_bf16 v[152:155], v[60:63], v[72:75], 0
	v_mfma_f32_16x16x32_bf16 v[140:143], v[48:51], v[80:83], 0
	v_mfma_f32_16x16x32_bf16 v[136:139], v[60:63], v[80:83], 0
	v_mfma_f32_16x16x32_bf16 v[124:127], v[48:51], v[160:163], 0
	v_mfma_f32_16x16x32_bf16 v[120:123], v[60:63], v[160:163], 0
	v_mfma_f32_16x16x32_bf16 v[108:111], v[48:51], v[192:195], 0
	v_mfma_f32_16x16x32_bf16 v[104:107], v[60:63], v[192:195], 0
	v_mfma_f32_16x16x32_bf16 v[156:159], v[52:55], v[76:79], v[156:159]
	v_mfma_f32_16x16x32_bf16 v[152:155], v[68:71], v[76:79], v[152:155]
	v_mfma_f32_16x16x32_bf16 v[140:143], v[52:55], v[84:87], v[140:143]
	v_mfma_f32_16x16x32_bf16 v[136:139], v[68:71], v[84:87], v[136:139]
	v_mfma_f32_16x16x32_bf16 v[124:127], v[52:55], v[164:167], v[124:127]
	v_mfma_f32_16x16x32_bf16 v[120:123], v[68:71], v[164:167], v[120:123]
	v_mfma_f32_16x16x32_bf16 v[108:111], v[52:55], v[196:199], v[108:111]
	v_mfma_f32_16x16x32_bf16 v[104:107], v[68:71], v[196:199], v[104:107]
	s_barrier
	s_add_i32 m0, s41, 0xc000
	ds_read_b128 v[200:203], v206 offset:16384
	ds_read_b128 v[208:211], v206 offset:17408
	ds_read_b128 v[212:215], v206 offset:18432
	global_load_lds_dwordx4 v188, s[8:9]
	s_add_i32 m0, s41, 0xe000
	ds_read_b128 v[216:219], v206 offset:19456
	global_load_lds_dwordx4 v190, s[8:9]
	s_add_u32 s98, s2, 0x80
	s_addc_u32 s99, s3, 0
	s_add_i32 m0, s40, 0x10000
	s_nop 0
	global_load_lds_dwordx4 v182, s[2:3]
	s_add_i32 m0, s40, 0x12000
	s_nop 0
	global_load_lds_dwordx4 v186, s[2:3]
	s_barrier
	s_waitcnt lgkmcnt(0)
	v_mfma_f32_16x16x32_bf16 v[148:151], v[200:203], v[72:75], 0
	v_mfma_f32_16x16x32_bf16 v[72:75], v[212:215], v[72:75], 0
	v_mfma_f32_16x16x32_bf16 v[148:151], v[208:211], v[76:79], v[148:151]
	v_mfma_f32_16x16x32_bf16 v[72:75], v[216:219], v[76:79], v[72:75]
	v_mfma_f32_16x16x32_bf16 v[76:79], v[200:203], v[80:83], 0
	v_mfma_f32_16x16x32_bf16 v[80:83], v[212:215], v[80:83], 0
	v_mfma_f32_16x16x32_bf16 v[112:115], v[212:215], v[160:163], 0
	v_mfma_f32_16x16x32_bf16 v[100:103], v[200:203], v[192:195], 0
	v_mfma_f32_16x16x32_bf16 v[96:99], v[212:215], v[192:195], 0
	v_mfma_f32_16x16x32_bf16 v[76:79], v[208:211], v[84:87], v[76:79]
	v_mfma_f32_16x16x32_bf16 v[80:83], v[216:219], v[84:87], v[80:83]
	v_mfma_f32_16x16x32_bf16 v[84:87], v[200:203], v[160:163], 0
	v_mfma_f32_16x16x32_bf16 v[112:115], v[216:219], v[164:167], v[112:115]
	v_mfma_f32_16x16x32_bf16 v[100:103], v[208:211], v[196:199], v[100:103]
	v_mfma_f32_16x16x32_bf16 v[96:99], v[216:219], v[196:199], v[96:99]
	v_mfma_f32_16x16x32_bf16 v[84:87], v[208:211], v[164:167], v[84:87]
	s_mov_b32 m0, s41
	s_add_u32 s100, s28, 0x80
	s_addc_u32 s101, s29, 0
	s_barrier
	ds_read_b128 v[116:119], v207 offset:16384
	ds_read_b128 v[128:131], v207 offset:17408
	ds_read_b128 v[132:135], v207 offset:18432
	ds_read_b128 v[144:147], v207 offset:19456
	ds_read_b128 v[160:163], v207 offset:20480
	ds_read_b128 v[164:167], v207 offset:21504
	ds_read_b128 v[192:195], v207 offset:22528
	global_load_lds_dwordx4 v180, s[28:29]
	s_mov_b32 m0, s42
	ds_read_b128 v[196:199], v207 offset:23552
	global_load_lds_dwordx4 v184, s[28:29]
	s_barrier
	s_waitcnt lgkmcnt(0)
	v_mfma_f32_16x16x32_bf16 v[92:95], v[48:51], v[116:119], 0
	v_mfma_f32_16x16x32_bf16 v[88:91], v[60:63], v[116:119], 0
	v_mfma_f32_16x16x32_bf16 v[44:47], v[48:51], v[132:135], 0
	v_mfma_f32_16x16x32_bf16 v[40:43], v[60:63], v[132:135], 0
	v_mfma_f32_16x16x32_bf16 v[28:31], v[48:51], v[160:163], 0
	v_mfma_f32_16x16x32_bf16 v[24:27], v[60:63], v[160:163], 0
	v_mfma_f32_16x16x32_bf16 v[12:15], v[48:51], v[192:195], 0
	v_mfma_f32_16x16x32_bf16 v[8:11], v[60:63], v[192:195], 0
	v_mfma_f32_16x16x32_bf16 v[92:95], v[52:55], v[128:131], v[92:95]
	v_mfma_f32_16x16x32_bf16 v[88:91], v[68:71], v[128:131], v[88:91]
	v_mfma_f32_16x16x32_bf16 v[44:47], v[52:55], v[144:147], v[44:47]
	v_mfma_f32_16x16x32_bf16 v[40:43], v[68:71], v[144:147], v[40:43]
	v_mfma_f32_16x16x32_bf16 v[28:31], v[52:55], v[164:167], v[28:31]
	v_mfma_f32_16x16x32_bf16 v[24:27], v[68:71], v[164:167], v[24:27]
	v_mfma_f32_16x16x32_bf16 v[12:15], v[52:55], v[196:199], v[12:15]
	v_mfma_f32_16x16x32_bf16 v[8:11], v[68:71], v[196:199], v[8:11]
	s_barrier
	s_add_i32 m0, s40, 0x14000
	s_add_u32 s60, s2, 0x40000
	s_addc_u32 s61, s3, 0
	global_load_lds_dwordx4 v182, s[60:61]
	s_add_i32 m0, s40, 0x16000
	s_add_u32 s28, s28, 0x40000
	s_addc_u32 s29, s29, 0
	global_load_lds_dwordx4 v186, s[60:61]
	s_waitcnt vmcnt(6)
	s_barrier
	v_mfma_f32_16x16x32_bf16 v[36:39], v[200:203], v[132:135], 0
	v_mfma_f32_16x16x32_bf16 v[32:35], v[212:215], v[132:135], 0
	v_mfma_f32_16x16x32_bf16 v[20:23], v[200:203], v[160:163], 0
	v_mfma_f32_16x16x32_bf16 v[16:19], v[212:215], v[160:163], 0
	v_mfma_f32_16x16x32_bf16 v[4:7], v[200:203], v[192:195], 0
	v_mfma_f32_16x16x32_bf16 v[0:3], v[212:215], v[192:195], 0
	v_mfma_f32_16x16x32_bf16 v[48:51], v[200:203], v[116:119], 0
	v_mfma_f32_16x16x32_bf16 v[52:55], v[212:215], v[116:119], 0
	v_mfma_f32_16x16x32_bf16 v[36:39], v[208:211], v[144:147], v[36:39]
	v_mfma_f32_16x16x32_bf16 v[32:35], v[216:219], v[144:147], v[32:35]
	v_mfma_f32_16x16x32_bf16 v[20:23], v[208:211], v[164:167], v[20:23]
	v_mfma_f32_16x16x32_bf16 v[16:19], v[216:219], v[164:167], v[16:19]
	v_mfma_f32_16x16x32_bf16 v[4:7], v[208:211], v[196:199], v[4:7]
	v_mfma_f32_16x16x32_bf16 v[0:3], v[216:219], v[196:199], v[0:3]
	v_mfma_f32_16x16x32_bf16 v[48:51], v[208:211], v[128:131], v[48:51]
	v_mfma_f32_16x16x32_bf16 v[52:55], v[216:219], v[128:131], v[52:55]
	s_barrier
	ds_read_b128 v[56:59], v206 offset:32768
	ds_read_b128 v[60:63], v206 offset:33792
	ds_read_b128 v[64:67], v206 offset:34816
	ds_read_b128 v[68:71], v206 offset:35840
	ds_read_b128 v[116:119], v207 offset:32768
	ds_read_b128 v[128:131], v207 offset:33792
	ds_read_b128 v[160:163], v207 offset:34816
	ds_read_b128 v[164:167], v207 offset:35840
	ds_read_b128 v[192:195], v207 offset:36864
	ds_read_b128 v[196:199], v207 offset:37888
	ds_read_b128 v[200:203], v207 offset:38912
	ds_read_b128 v[208:211], v207 offset:39936
	s_waitcnt lgkmcnt(8)
	s_barrier
	s_waitcnt lgkmcnt(0)
	v_mfma_f32_16x16x32_bf16 v[132:135], v[56:59], v[116:119], v[156:159]
	v_mfma_f32_16x16x32_bf16 v[156:159], v[60:63], v[128:131], v[132:135]
	v_mfma_f32_16x16x32_bf16 v[132:135], v[64:67], v[116:119], v[152:155]
	v_mfma_f32_16x16x32_bf16 v[152:155], v[68:71], v[128:131], v[132:135]
	v_mfma_f32_16x16x32_bf16 v[132:135], v[56:59], v[160:163], v[140:143]
	v_mfma_f32_16x16x32_bf16 v[140:143], v[60:63], v[164:167], v[132:135]
	v_mfma_f32_16x16x32_bf16 v[132:135], v[64:67], v[160:163], v[136:139]
	v_mfma_f32_16x16x32_bf16 v[124:127], v[56:59], v[192:195], v[124:127]
	v_mfma_f32_16x16x32_bf16 v[120:123], v[64:67], v[192:195], v[120:123]
	v_mfma_f32_16x16x32_bf16 v[108:111], v[56:59], v[200:203], v[108:111]
	v_mfma_f32_16x16x32_bf16 v[104:107], v[64:67], v[200:203], v[104:107]
	v_mfma_f32_16x16x32_bf16 v[136:139], v[68:71], v[164:167], v[132:135]
	v_mfma_f32_16x16x32_bf16 v[124:127], v[60:63], v[196:199], v[124:127]
	v_mfma_f32_16x16x32_bf16 v[120:123], v[68:71], v[196:199], v[120:123]
	v_mfma_f32_16x16x32_bf16 v[108:111], v[60:63], v[208:211], v[108:111]
	v_mfma_f32_16x16x32_bf16 v[104:107], v[68:71], v[208:211], v[104:107]
	s_barrier
	s_mov_b32 m0, s43
	ds_read_b128 v[212:215], v206 offset:49152
	ds_read_b128 v[216:219], v206 offset:50176
	ds_read_b128 v[220:223], v206 offset:51200
	global_load_lds_dwordx4 v180, s[28:29]
	s_mov_b32 m0, s44
	ds_read_b128 v[236:239], v206 offset:52224
	global_load_lds_dwordx4 v184, s[28:29]
	s_add_i32 m0, s40, 0x18000
	s_nop 0
	global_load_lds_dwordx4 v182, s[98:99]
	s_add_i32 m0, s40, 0x1a000
	s_nop 0
	global_load_lds_dwordx4 v186, s[98:99]
	s_barrier
	s_waitcnt lgkmcnt(0)
	v_mfma_f32_16x16x32_bf16 v[72:75], v[220:223], v[116:119], v[72:75]
	v_mfma_f32_16x16x32_bf16 v[132:135], v[212:215], v[116:119], v[148:151]
	v_mfma_f32_16x16x32_bf16 v[144:147], v[236:239], v[128:131], v[72:75]
	v_mfma_f32_16x16x32_bf16 v[72:75], v[212:215], v[160:163], v[76:79]
	v_mfma_f32_16x16x32_bf16 v[148:151], v[216:219], v[128:131], v[132:135]
	v_mfma_f32_16x16x32_bf16 v[132:135], v[216:219], v[164:167], v[72:75]
	v_mfma_f32_16x16x32_bf16 v[72:75], v[220:223], v[160:163], v[80:83]
	v_mfma_f32_16x16x32_bf16 v[128:131], v[236:239], v[164:167], v[72:75]
	v_mfma_f32_16x16x32_bf16 v[72:75], v[212:215], v[192:195], v[84:87]
	v_mfma_f32_16x16x32_bf16 v[116:119], v[216:219], v[196:199], v[72:75]
	v_mfma_f32_16x16x32_bf16 v[72:75], v[220:223], v[192:195], v[112:115]
	v_mfma_f32_16x16x32_bf16 v[112:115], v[236:239], v[196:199], v[72:75]
	v_mfma_f32_16x16x32_bf16 v[72:75], v[212:215], v[200:203], v[100:103]
	v_mfma_f32_16x16x32_bf16 v[100:103], v[216:219], v[208:211], v[72:75]
	v_mfma_f32_16x16x32_bf16 v[72:75], v[220:223], v[200:203], v[96:99]
	v_mfma_f32_16x16x32_bf16 v[96:99], v[236:239], v[208:211], v[72:75]
	s_mov_b32 m0, s53
	s_barrier
	s_nop 2
	ds_read_b128 v[72:75], v207 offset:49152
	ds_read_b128 v[76:79], v207 offset:50176
	ds_read_b128 v[80:83], v207 offset:51200
	ds_read_b128 v[84:87], v207 offset:52224
	ds_read_b128 v[160:163], v207 offset:53248
	ds_read_b128 v[164:167], v207 offset:54272
	ds_read_b128 v[192:195], v207 offset:55296
	global_load_lds_dwordx4 v180, s[100:101]
	s_mov_b32 m0, s54
	ds_read_b128 v[196:199], v207 offset:56320
	global_load_lds_dwordx4 v184, s[100:101]
	s_barrier
	s_waitcnt lgkmcnt(0)
	v_mfma_f32_16x16x32_bf16 v[92:95], v[56:59], v[72:75], v[92:95]
	v_mfma_f32_16x16x32_bf16 v[88:91], v[64:67], v[72:75], v[88:91]
	v_mfma_f32_16x16x32_bf16 v[44:47], v[56:59], v[80:83], v[44:47]
	v_mfma_f32_16x16x32_bf16 v[40:43], v[64:67], v[80:83], v[40:43]
	v_mfma_f32_16x16x32_bf16 v[28:31], v[56:59], v[160:163], v[28:31]
	v_mfma_f32_16x16x32_bf16 v[24:27], v[64:67], v[160:163], v[24:27]
	v_mfma_f32_16x16x32_bf16 v[12:15], v[56:59], v[192:195], v[12:15]
	v_mfma_f32_16x16x32_bf16 v[8:11], v[64:67], v[192:195], v[8:11]
	v_mfma_f32_16x16x32_bf16 v[92:95], v[60:63], v[76:79], v[92:95]
	v_mfma_f32_16x16x32_bf16 v[88:91], v[68:71], v[76:79], v[88:91]
	v_mfma_f32_16x16x32_bf16 v[44:47], v[60:63], v[84:87], v[44:47]
	v_mfma_f32_16x16x32_bf16 v[40:43], v[68:71], v[84:87], v[40:43]
	v_mfma_f32_16x16x32_bf16 v[28:31], v[60:63], v[164:167], v[28:31]
	v_mfma_f32_16x16x32_bf16 v[24:27], v[68:71], v[164:167], v[24:27]
	v_mfma_f32_16x16x32_bf16 v[12:15], v[60:63], v[196:199], v[12:15]
	v_mfma_f32_16x16x32_bf16 v[8:11], v[68:71], v[196:199], v[8:11]
	s_barrier
	s_add_i32 m0, s40, 0x1c000
	s_add_u32 s2, s2, 0x40080
	s_addc_u32 s3, s3, 0
	global_load_lds_dwordx4 v182, s[2:3]
	s_add_i32 m0, s40, 0x1e000
	s_add_i32 s58, s58, 2
	global_load_lds_dwordx4 v186, s[2:3]
	s_waitcnt vmcnt(6)
	s_barrier
	v_mfma_f32_16x16x32_bf16 v[48:51], v[212:215], v[72:75], v[48:51]
	v_mfma_f32_16x16x32_bf16 v[64:67], v[216:219], v[76:79], v[48:51]
	v_mfma_f32_16x16x32_bf16 v[48:51], v[220:223], v[72:75], v[52:55]
	v_mfma_f32_16x16x32_bf16 v[36:39], v[212:215], v[80:83], v[36:39]
	v_mfma_f32_16x16x32_bf16 v[32:35], v[220:223], v[80:83], v[32:35]
	v_mfma_f32_16x16x32_bf16 v[20:23], v[212:215], v[160:163], v[20:23]
	v_mfma_f32_16x16x32_bf16 v[16:19], v[220:223], v[160:163], v[16:19]
	v_mfma_f32_16x16x32_bf16 v[4:7], v[212:215], v[192:195], v[4:7]
	v_mfma_f32_16x16x32_bf16 v[0:3], v[220:223], v[192:195], v[0:3]
	v_mfma_f32_16x16x32_bf16 v[56:59], v[236:239], v[76:79], v[48:51]
	v_mfma_f32_16x16x32_bf16 v[36:39], v[216:219], v[84:87], v[36:39]
	v_mfma_f32_16x16x32_bf16 v[32:35], v[236:239], v[84:87], v[32:35]
	v_mfma_f32_16x16x32_bf16 v[20:23], v[216:219], v[164:167], v[20:23]
	v_mfma_f32_16x16x32_bf16 v[16:19], v[236:239], v[164:167], v[16:19]
	v_mfma_f32_16x16x32_bf16 v[4:7], v[216:219], v[196:199], v[4:7]
	v_mfma_f32_16x16x32_bf16 v[0:3], v[236:239], v[196:199], v[0:3]
	s_add_u32 s8, s8, 0x100
	s_addc_u32 s9, s9, 0
	s_add_u32 s56, s56, 0x100
	s_addc_u32 s57, s57, 0
	s_cmp_gt_u32 s58, 13
	s_barrier
.LBB0_678:
	s_add_u32 s2, s8, 0xfffc0080
	s_addc_u32 s3, s9, -1
	ds_read_b128 v[48:51], v206
	ds_read_b128 v[52:55], v206 offset:1024
	ds_read_b128 v[60:63], v206 offset:2048
	ds_read_b128 v[68:71], v206 offset:3072
	s_cmp_eq_u32 s58, 12
	s_cselect_b32 s29, s1, s3
	s_cselect_b32 s28, s7, s2
	s_cselect_b32 s3, s21, s57
	s_cselect_b32 s2, s23, s56
	ds_read_b128 v[72:75], v207
	ds_read_b128 v[76:79], v207 offset:1024
	ds_read_b128 v[80:83], v207 offset:2048
	ds_read_b128 v[84:87], v207 offset:3072
	ds_read_b128 v[160:163], v207 offset:4096
	ds_read_b128 v[164:167], v207 offset:5120
	ds_read_b128 v[192:195], v207 offset:6144
	ds_read_b128 v[196:199], v207 offset:7168
	s_waitcnt lgkmcnt(8)
	s_barrier
	s_waitcnt lgkmcnt(0)
	v_mfma_f32_16x16x32_bf16 v[156:159], v[48:51], v[72:75], v[156:159]
	v_mfma_f32_16x16x32_bf16 v[152:155], v[60:63], v[72:75], v[152:155]
	v_mfma_f32_16x16x32_bf16 v[140:143], v[48:51], v[80:83], v[140:143]
	v_mfma_f32_16x16x32_bf16 v[136:139], v[60:63], v[80:83], v[136:139]
	v_mfma_f32_16x16x32_bf16 v[124:127], v[48:51], v[160:163], v[124:127]
	v_mfma_f32_16x16x32_bf16 v[120:123], v[60:63], v[160:163], v[120:123]
	v_mfma_f32_16x16x32_bf16 v[108:111], v[48:51], v[192:195], v[108:111]
	v_mfma_f32_16x16x32_bf16 v[104:107], v[60:63], v[192:195], v[104:107]
	v_mfma_f32_16x16x32_bf16 v[156:159], v[52:55], v[76:79], v[156:159]
	v_mfma_f32_16x16x32_bf16 v[152:155], v[68:71], v[76:79], v[152:155]
	v_mfma_f32_16x16x32_bf16 v[140:143], v[52:55], v[84:87], v[140:143]
	v_mfma_f32_16x16x32_bf16 v[136:139], v[68:71], v[84:87], v[136:139]
	v_mfma_f32_16x16x32_bf16 v[124:127], v[52:55], v[164:167], v[124:127]
	v_mfma_f32_16x16x32_bf16 v[120:123], v[68:71], v[164:167], v[120:123]
	v_mfma_f32_16x16x32_bf16 v[108:111], v[52:55], v[196:199], v[108:111]
	v_mfma_f32_16x16x32_bf16 v[104:107], v[68:71], v[196:199], v[104:107]
	s_barrier
	s_add_i32 m0, s41, 0xc000
	ds_read_b128 v[200:203], v206 offset:16384
	ds_read_b128 v[208:211], v206 offset:17408
	ds_read_b128 v[212:215], v206 offset:18432
	global_load_lds_dwordx4 v188, s[8:9]
	s_add_i32 m0, s41, 0xe000
	ds_read_b128 v[216:219], v206 offset:19456
	global_load_lds_dwordx4 v190, s[8:9]
	s_add_u32 s98, s2, 0x80
	s_addc_u32 s99, s3, 0
	s_add_i32 m0, s40, 0x10000
	s_nop 0
	global_load_lds_dwordx4 v182, s[2:3]
	s_add_i32 m0, s40, 0x12000
	s_nop 0
	global_load_lds_dwordx4 v186, s[2:3]
	s_barrier
	s_waitcnt lgkmcnt(0)
	v_mfma_f32_16x16x32_bf16 v[148:151], v[200:203], v[72:75], v[148:151]
	v_mfma_f32_16x16x32_bf16 v[72:75], v[212:215], v[72:75], v[144:147]
	v_mfma_f32_16x16x32_bf16 v[148:151], v[208:211], v[76:79], v[148:151]
	v_mfma_f32_16x16x32_bf16 v[72:75], v[216:219], v[76:79], v[72:75]
	v_mfma_f32_16x16x32_bf16 v[76:79], v[200:203], v[80:83], v[132:135]
	v_mfma_f32_16x16x32_bf16 v[80:83], v[212:215], v[80:83], v[128:131]
	v_mfma_f32_16x16x32_bf16 v[112:115], v[212:215], v[160:163], v[112:115]
	v_mfma_f32_16x16x32_bf16 v[100:103], v[200:203], v[192:195], v[100:103]
	v_mfma_f32_16x16x32_bf16 v[96:99], v[212:215], v[192:195], v[96:99]
	v_mfma_f32_16x16x32_bf16 v[76:79], v[208:211], v[84:87], v[76:79]
	v_mfma_f32_16x16x32_bf16 v[80:83], v[216:219], v[84:87], v[80:83]
	v_mfma_f32_16x16x32_bf16 v[84:87], v[200:203], v[160:163], v[116:119]
	v_mfma_f32_16x16x32_bf16 v[112:115], v[216:219], v[164:167], v[112:115]
	v_mfma_f32_16x16x32_bf16 v[100:103], v[208:211], v[196:199], v[100:103]
	v_mfma_f32_16x16x32_bf16 v[96:99], v[216:219], v[196:199], v[96:99]
	v_mfma_f32_16x16x32_bf16 v[84:87], v[208:211], v[164:167], v[84:87]
	s_mov_b32 m0, s41
	s_add_u32 s100, s28, 0x80
	s_addc_u32 s101, s29, 0
	s_barrier
	ds_read_b128 v[116:119], v207 offset:16384
	ds_read_b128 v[128:131], v207 offset:17408
	ds_read_b128 v[132:135], v207 offset:18432
	ds_read_b128 v[144:147], v207 offset:19456
	ds_read_b128 v[160:163], v207 offset:20480
	ds_read_b128 v[164:167], v207 offset:21504
	ds_read_b128 v[192:195], v207 offset:22528
	global_load_lds_dwordx4 v180, s[28:29]
	s_mov_b32 m0, s42
	ds_read_b128 v[196:199], v207 offset:23552
	global_load_lds_dwordx4 v184, s[28:29]
	s_barrier
	s_waitcnt lgkmcnt(0)
	v_mfma_f32_16x16x32_bf16 v[92:95], v[48:51], v[116:119], v[92:95]
	v_mfma_f32_16x16x32_bf16 v[88:91], v[60:63], v[116:119], v[88:91]
	v_mfma_f32_16x16x32_bf16 v[44:47], v[48:51], v[132:135], v[44:47]
	v_mfma_f32_16x16x32_bf16 v[40:43], v[60:63], v[132:135], v[40:43]
	v_mfma_f32_16x16x32_bf16 v[28:31], v[48:51], v[160:163], v[28:31]
	v_mfma_f32_16x16x32_bf16 v[24:27], v[60:63], v[160:163], v[24:27]
	v_mfma_f32_16x16x32_bf16 v[12:15], v[48:51], v[192:195], v[12:15]
	v_mfma_f32_16x16x32_bf16 v[8:11], v[60:63], v[192:195], v[8:11]
	v_mfma_f32_16x16x32_bf16 v[92:95], v[52:55], v[128:131], v[92:95]
	v_mfma_f32_16x16x32_bf16 v[88:91], v[68:71], v[128:131], v[88:91]
	v_mfma_f32_16x16x32_bf16 v[44:47], v[52:55], v[144:147], v[44:47]
	v_mfma_f32_16x16x32_bf16 v[40:43], v[68:71], v[144:147], v[40:43]
	v_mfma_f32_16x16x32_bf16 v[28:31], v[52:55], v[164:167], v[28:31]
	v_mfma_f32_16x16x32_bf16 v[24:27], v[68:71], v[164:167], v[24:27]
	v_mfma_f32_16x16x32_bf16 v[12:15], v[52:55], v[196:199], v[12:15]
	v_mfma_f32_16x16x32_bf16 v[8:11], v[68:71], v[196:199], v[8:11]
	s_barrier
	s_add_i32 m0, s40, 0x14000
	s_add_u32 s60, s2, 0x40000
	s_addc_u32 s61, s3, 0
	global_load_lds_dwordx4 v182, s[60:61]
	s_add_i32 m0, s40, 0x16000
	s_add_u32 s28, s28, 0x40000
	s_addc_u32 s29, s29, 0
	global_load_lds_dwordx4 v186, s[60:61]
	s_waitcnt vmcnt(6)
	s_barrier
	v_mfma_f32_16x16x32_bf16 v[36:39], v[200:203], v[132:135], v[36:39]
	v_mfma_f32_16x16x32_bf16 v[32:35], v[212:215], v[132:135], v[32:35]
	v_mfma_f32_16x16x32_bf16 v[20:23], v[200:203], v[160:163], v[20:23]
	v_mfma_f32_16x16x32_bf16 v[16:19], v[212:215], v[160:163], v[16:19]
	v_mfma_f32_16x16x32_bf16 v[4:7], v[200:203], v[192:195], v[4:7]
	v_mfma_f32_16x16x32_bf16 v[0:3], v[212:215], v[192:195], v[0:3]
	v_mfma_f32_16x16x32_bf16 v[48:51], v[200:203], v[116:119], v[64:67]
	v_mfma_f32_16x16x32_bf16 v[52:55], v[212:215], v[116:119], v[56:59]
	v_mfma_f32_16x16x32_bf16 v[36:39], v[208:211], v[144:147], v[36:39]
	v_mfma_f32_16x16x32_bf16 v[32:35], v[216:219], v[144:147], v[32:35]
	v_mfma_f32_16x16x32_bf16 v[20:23], v[208:211], v[164:167], v[20:23]
	v_mfma_f32_16x16x32_bf16 v[16:19], v[216:219], v[164:167], v[16:19]
	v_mfma_f32_16x16x32_bf16 v[4:7], v[208:211], v[196:199], v[4:7]
	v_mfma_f32_16x16x32_bf16 v[0:3], v[216:219], v[196:199], v[0:3]
	v_mfma_f32_16x16x32_bf16 v[48:51], v[208:211], v[128:131], v[48:51]
	v_mfma_f32_16x16x32_bf16 v[52:55], v[216:219], v[128:131], v[52:55]
	s_barrier
	ds_read_b128 v[56:59], v206 offset:32768
	ds_read_b128 v[60:63], v206 offset:33792
	ds_read_b128 v[64:67], v206 offset:34816
	ds_read_b128 v[68:71], v206 offset:35840
	ds_read_b128 v[116:119], v207 offset:32768
	ds_read_b128 v[128:131], v207 offset:33792
	ds_read_b128 v[160:163], v207 offset:34816
	ds_read_b128 v[164:167], v207 offset:35840
	ds_read_b128 v[192:195], v207 offset:36864
	ds_read_b128 v[196:199], v207 offset:37888
	ds_read_b128 v[200:203], v207 offset:38912
	ds_read_b128 v[208:211], v207 offset:39936
	s_waitcnt lgkmcnt(8)
	s_barrier
	s_waitcnt lgkmcnt(0)
	v_mfma_f32_16x16x32_bf16 v[132:135], v[56:59], v[116:119], v[156:159]
	v_mfma_f32_16x16x32_bf16 v[156:159], v[60:63], v[128:131], v[132:135]
	v_mfma_f32_16x16x32_bf16 v[132:135], v[64:67], v[116:119], v[152:155]
	v_mfma_f32_16x16x32_bf16 v[152:155], v[68:71], v[128:131], v[132:135]
	v_mfma_f32_16x16x32_bf16 v[132:135], v[56:59], v[160:163], v[140:143]
	v_mfma_f32_16x16x32_bf16 v[140:143], v[60:63], v[164:167], v[132:135]
	v_mfma_f32_16x16x32_bf16 v[132:135], v[64:67], v[160:163], v[136:139]
	v_mfma_f32_16x16x32_bf16 v[124:127], v[56:59], v[192:195], v[124:127]
	v_mfma_f32_16x16x32_bf16 v[120:123], v[64:67], v[192:195], v[120:123]
	v_mfma_f32_16x16x32_bf16 v[108:111], v[56:59], v[200:203], v[108:111]
	v_mfma_f32_16x16x32_bf16 v[104:107], v[64:67], v[200:203], v[104:107]
	v_mfma_f32_16x16x32_bf16 v[136:139], v[68:71], v[164:167], v[132:135]
	v_mfma_f32_16x16x32_bf16 v[124:127], v[60:63], v[196:199], v[124:127]
	v_mfma_f32_16x16x32_bf16 v[120:123], v[68:71], v[196:199], v[120:123]
	v_mfma_f32_16x16x32_bf16 v[108:111], v[60:63], v[208:211], v[108:111]
	v_mfma_f32_16x16x32_bf16 v[104:107], v[68:71], v[208:211], v[104:107]
	s_barrier
	s_mov_b32 m0, s43
	ds_read_b128 v[212:215], v206 offset:49152
	ds_read_b128 v[216:219], v206 offset:50176
	ds_read_b128 v[220:223], v206 offset:51200
	global_load_lds_dwordx4 v180, s[28:29]
	s_mov_b32 m0, s44
	ds_read_b128 v[236:239], v206 offset:52224
	global_load_lds_dwordx4 v184, s[28:29]
	s_add_i32 m0, s40, 0x18000
	s_nop 0
	global_load_lds_dwordx4 v182, s[98:99]
	s_add_i32 m0, s40, 0x1a000
	s_nop 0
	global_load_lds_dwordx4 v186, s[98:99]
	s_barrier
	s_waitcnt lgkmcnt(0)
	v_mfma_f32_16x16x32_bf16 v[72:75], v[220:223], v[116:119], v[72:75]
	v_mfma_f32_16x16x32_bf16 v[132:135], v[212:215], v[116:119], v[148:151]
	v_mfma_f32_16x16x32_bf16 v[144:147], v[236:239], v[128:131], v[72:75]
	v_mfma_f32_16x16x32_bf16 v[72:75], v[212:215], v[160:163], v[76:79]
	v_mfma_f32_16x16x32_bf16 v[148:151], v[216:219], v[128:131], v[132:135]
	v_mfma_f32_16x16x32_bf16 v[132:135], v[216:219], v[164:167], v[72:75]
	v_mfma_f32_16x16x32_bf16 v[72:75], v[220:223], v[160:163], v[80:83]
	v_mfma_f32_16x16x32_bf16 v[128:131], v[236:239], v[164:167], v[72:75]
	v_mfma_f32_16x16x32_bf16 v[72:75], v[212:215], v[192:195], v[84:87]
	v_mfma_f32_16x16x32_bf16 v[116:119], v[216:219], v[196:199], v[72:75]
	v_mfma_f32_16x16x32_bf16 v[72:75], v[220:223], v[192:195], v[112:115]
	v_mfma_f32_16x16x32_bf16 v[112:115], v[236:239], v[196:199], v[72:75]
	v_mfma_f32_16x16x32_bf16 v[72:75], v[212:215], v[200:203], v[100:103]
	v_mfma_f32_16x16x32_bf16 v[100:103], v[216:219], v[208:211], v[72:75]
	v_mfma_f32_16x16x32_bf16 v[72:75], v[220:223], v[200:203], v[96:99]
	v_mfma_f32_16x16x32_bf16 v[96:99], v[236:239], v[208:211], v[72:75]
	s_mov_b32 m0, s53
	s_barrier
	s_nop 2
	ds_read_b128 v[72:75], v207 offset:49152
	ds_read_b128 v[76:79], v207 offset:50176
	ds_read_b128 v[80:83], v207 offset:51200
	ds_read_b128 v[84:87], v207 offset:52224
	ds_read_b128 v[160:163], v207 offset:53248
	ds_read_b128 v[164:167], v207 offset:54272
	ds_read_b128 v[192:195], v207 offset:55296
	global_load_lds_dwordx4 v180, s[100:101]
	s_mov_b32 m0, s54
	ds_read_b128 v[196:199], v207 offset:56320
	global_load_lds_dwordx4 v184, s[100:101]
	s_barrier
	s_waitcnt lgkmcnt(0)
	v_mfma_f32_16x16x32_bf16 v[92:95], v[56:59], v[72:75], v[92:95]
	v_mfma_f32_16x16x32_bf16 v[88:91], v[64:67], v[72:75], v[88:91]
	v_mfma_f32_16x16x32_bf16 v[44:47], v[56:59], v[80:83], v[44:47]
	v_mfma_f32_16x16x32_bf16 v[40:43], v[64:67], v[80:83], v[40:43]
	v_mfma_f32_16x16x32_bf16 v[28:31], v[56:59], v[160:163], v[28:31]
	v_mfma_f32_16x16x32_bf16 v[24:27], v[64:67], v[160:163], v[24:27]
	v_mfma_f32_16x16x32_bf16 v[12:15], v[56:59], v[192:195], v[12:15]
	v_mfma_f32_16x16x32_bf16 v[8:11], v[64:67], v[192:195], v[8:11]
	v_mfma_f32_16x16x32_bf16 v[92:95], v[60:63], v[76:79], v[92:95]
	v_mfma_f32_16x16x32_bf16 v[88:91], v[68:71], v[76:79], v[88:91]
	v_mfma_f32_16x16x32_bf16 v[44:47], v[60:63], v[84:87], v[44:47]
	v_mfma_f32_16x16x32_bf16 v[40:43], v[68:71], v[84:87], v[40:43]
	v_mfma_f32_16x16x32_bf16 v[28:31], v[60:63], v[164:167], v[28:31]
	v_mfma_f32_16x16x32_bf16 v[24:27], v[68:71], v[164:167], v[24:27]
	v_mfma_f32_16x16x32_bf16 v[12:15], v[60:63], v[196:199], v[12:15]
	v_mfma_f32_16x16x32_bf16 v[8:11], v[68:71], v[196:199], v[8:11]
	s_barrier
	s_add_i32 m0, s40, 0x1c000
	s_add_u32 s2, s2, 0x40080
	s_addc_u32 s3, s3, 0
	global_load_lds_dwordx4 v182, s[2:3]
	s_add_i32 m0, s40, 0x1e000
	s_add_i32 s58, s58, 2
	global_load_lds_dwordx4 v186, s[2:3]
	s_waitcnt vmcnt(6)
	s_barrier
	v_mfma_f32_16x16x32_bf16 v[48:51], v[212:215], v[72:75], v[48:51]
	v_mfma_f32_16x16x32_bf16 v[64:67], v[216:219], v[76:79], v[48:51]
	v_mfma_f32_16x16x32_bf16 v[48:51], v[220:223], v[72:75], v[52:55]
	v_mfma_f32_16x16x32_bf16 v[36:39], v[212:215], v[80:83], v[36:39]
	v_mfma_f32_16x16x32_bf16 v[32:35], v[220:223], v[80:83], v[32:35]
	v_mfma_f32_16x16x32_bf16 v[20:23], v[212:215], v[160:163], v[20:23]
	v_mfma_f32_16x16x32_bf16 v[16:19], v[220:223], v[160:163], v[16:19]
	v_mfma_f32_16x16x32_bf16 v[4:7], v[212:215], v[192:195], v[4:7]
	v_mfma_f32_16x16x32_bf16 v[0:3], v[220:223], v[192:195], v[0:3]
	v_mfma_f32_16x16x32_bf16 v[56:59], v[236:239], v[76:79], v[48:51]
	v_mfma_f32_16x16x32_bf16 v[36:39], v[216:219], v[84:87], v[36:39]
	v_mfma_f32_16x16x32_bf16 v[32:35], v[236:239], v[84:87], v[32:35]
	v_mfma_f32_16x16x32_bf16 v[20:23], v[216:219], v[164:167], v[20:23]
	v_mfma_f32_16x16x32_bf16 v[16:19], v[236:239], v[164:167], v[16:19]
	v_mfma_f32_16x16x32_bf16 v[4:7], v[216:219], v[196:199], v[4:7]
	v_mfma_f32_16x16x32_bf16 v[0:3], v[236:239], v[196:199], v[0:3]
	s_add_u32 s8, s8, 0x100
	s_addc_u32 s9, s9, 0
	s_add_u32 s56, s56, 0x100
	s_addc_u32 s57, s57, 0
	s_cmp_gt_u32 s58, 13
	s_barrier
	s_cbranch_scc0 .LBB0_678
	s_lshl_b32 s1, s0, 8
	s_add_i32 s2, s1, s51
	s_lshl_b32 s1, s6, 8
	v_mov_b32_e32 v160, v205
	v_mov_b32_e32 v208, v204
	s_or_b32 s1, s1, s52
	s_nop 0
	v_lshl_add_u32 v192, v208, 3, s1
	s_add_i32 s1, s0, -16
	s_lshr_b32 s1, s1, 3
	s_add_i32 s1, s1, 1
	s_cmp_gt_i32 s0, 15
	s_cselect_b32 s3, s1, 0
	s_mul_i32 s96, s3, 0x1800
	s_lshl_b64 s[0:1], s[96:97], 2
	s_add_u32 s0, s45, s0
	v_ashrrev_i32_e32 v193, 31, v192
	s_addc_u32 s1, s46, s1
	v_lshlrev_b64 v[196:197], 2, v[192:193]
	s_lshl_b32 s96, s3, 10
	v_lshl_add_u64 v[48:49], s[0:1], 0, v[196:197]
	s_lshl_b64 s[0:1], s[96:97], 2
	s_add_u32 s0, s49, s0
	s_addc_u32 s1, s50, s1
	v_lshl_add_u64 v[52:53], s[0:1], 0, v[196:197]
	global_load_dwordx4 v[80:83], v[48:49], off offset:16
	global_load_dwordx4 v[84:87], v[48:49], off
	global_load_dwordx4 v[72:75], v[52:53], off offset:16
	global_load_dwordx4 v[76:79], v[52:53], off
	global_load_dwordx4 v[60:63], v[48:49], off offset:528
	global_load_dwordx4 v[68:71], v[48:49], off offset:512
	s_nop 0
	global_load_dwordx4 v[48:51], v[52:53], off offset:528
	s_nop 0
	global_load_dwordx4 v[52:55], v[52:53], off offset:512
	v_add_u32_e32 v194, s2, v160
	v_ashrrev_i32_e32 v195, 31, v194
	v_lshlrev_b64 v[160:161], 10, v[194:195]
	v_lshl_add_u64 v[198:199], v[160:161], 0, v[192:193]
	v_cndmask_b32_e64 v160, 0, 1, s[74:75]
	v_cmp_gt_i32_e64 s[0:1], s71, v194
	v_cmp_ne_u32_e64 s[6:7], 1, v160
	s_andn2_b64 vcc, exec, s[74:75]
	s_mov_b64 s[2:3], -1
	s_cbranch_vccnz .LBB0_681
	v_lshl_add_u64 v[160:161], v[198:199], 1, s[14:15]
	v_mov_b32_e32 v222, v160
	v_mov_b32_e32 v223, v161
	global_load_dwordx4 v[210:213], v[222:223], off
	global_load_dwordx4 v[214:217], v[222:223], off offset:256
	s_mov_b64 s[80:81], 0x8000
	v_lshl_add_u64 v[222:223], v[222:223], 0, s[80:81]
	global_load_dwordx4 v[218:221], v[222:223], off
	global_load_dwordx4 v[236:239], v[222:223], off offset:256
	s_mov_b64 s[2:3], 0
	s_waitcnt vmcnt(3)
	v_lshlrev_b32_e32 v164, 16, v210
	v_and_b32_e32 v165, 0xffff0000, v210
	v_lshlrev_b32_e32 v166, 16, v211
	v_and_b32_e32 v167, 0xffff0000, v211
	v_lshlrev_b32_e32 v160, 16, v212
	v_and_b32_e32 v161, 0xffff0000, v212
	v_lshlrev_b32_e32 v162, 16, v213
	v_and_b32_e32 v163, 0xffff0000, v213
	s_mov_b64 s[80:81], 0x8000
	v_lshl_add_u64 v[222:223], v[222:223], 0, s[80:81]
	global_load_dwordx4 v[210:213], v[222:223], off

.LBB0_879:
	s_ashr_i32 s39, s38, 31
	v_cmp_lt_i64_e32 vcc, s[12:13], v[178:179]
	s_lshl_b64 s[12:13], s[38:39], 19
	s_add_u32 s40, s49, s12
	s_addc_u32 s41, s50, s13
	s_lshl_b32 s84, s82, 18
	s_add_u32 s40, s40, s84
	s_addc_u32 s41, s41, 0
	s_and_b64 s[12:13], vcc, exec
	s_cselect_b32 s1, s41, s11
	s_cselect_b32 s9, s40, s10
	s_ashr_i32 s37, s36, 31
	s_lshl_b64 s[12:13], s[36:37], 19
	s_add_u32 s42, s51, s12
	s_addc_u32 s43, s52, s13
	s_and_b64 s[12:13], vcc, exec
	s_cselect_b32 s14, s43, s3
	s_cselect_b32 s15, s42, s2
	s_add_u32 s10, s10, 0x40080
	s_addc_u32 s11, s11, 0
	s_add_u32 s37, s2, 0x100
	s_addc_u32 s39, s3, 0
	s_mov_b32 s67, -2
	s_cmp_lg_u32 s83, 0
	s_cbranch_scc1 .Lup_half_peel
	s_add_u32 s2, s10, 0xfffc0080
	s_addc_u32 s3, s11, -1
	ds_read_b128 v[48:51], v237
	ds_read_b128 v[52:55], v237 offset:1024
	ds_read_b128 v[104:107], v237 offset:2048
	ds_read_b128 v[108:111], v237 offset:3072
	s_cmp_eq_u32 s67, 12
	s_cselect_b32 s13, s1, s3
	s_cselect_b32 s12, s9, s2
	s_cselect_b32 s3, s14, s39
	s_cselect_b32 s2, s15, s37
	ds_read_b128 v[112:115], v238
	ds_read_b128 v[116:119], v238 offset:1024
	ds_read_b128 v[120:123], v238 offset:2048
	ds_read_b128 v[156:159], v238 offset:3072
	ds_read_b128 v[160:163], v238 offset:4096
	ds_read_b128 v[164:167], v238 offset:5120
	ds_read_b128 v[190:193], v238 offset:6144
	ds_read_b128 v[194:197], v238 offset:7168
	s_waitcnt lgkmcnt(8)
	s_barrier
	s_waitcnt lgkmcnt(0)
	v_mfma_f32_16x16x32_bf16 v[152:155], v[48:51], v[112:115], 0
	v_mfma_f32_16x16x32_bf16 v[68:71], v[104:107], v[112:115], 0
	v_mfma_f32_16x16x32_bf16 v[148:151], v[48:51], v[120:123], 0
	v_mfma_f32_16x16x32_bf16 v[64:67], v[104:107], v[120:123], 0
	v_mfma_f32_16x16x32_bf16 v[136:139], v[48:51], v[160:163], 0
	v_mfma_f32_16x16x32_bf16 v[44:47], v[104:107], v[160:163], 0
	v_mfma_f32_16x16x32_bf16 v[128:131], v[48:51], v[190:193], 0
	v_mfma_f32_16x16x32_bf16 v[40:43], v[104:107], v[190:193], 0
	v_mfma_f32_16x16x32_bf16 v[152:155], v[52:55], v[116:119], v[152:155]
	v_mfma_f32_16x16x32_bf16 v[68:71], v[108:111], v[116:119], v[68:71]
	v_mfma_f32_16x16x32_bf16 v[148:151], v[52:55], v[156:159], v[148:151]
	v_mfma_f32_16x16x32_bf16 v[64:67], v[108:111], v[156:159], v[64:67]
	v_mfma_f32_16x16x32_bf16 v[136:139], v[52:55], v[164:167], v[136:139]
	v_mfma_f32_16x16x32_bf16 v[44:47], v[108:111], v[164:167], v[44:47]
	v_mfma_f32_16x16x32_bf16 v[128:131], v[52:55], v[194:197], v[128:131]
	v_mfma_f32_16x16x32_bf16 v[40:43], v[108:111], v[194:197], v[40:43]
	s_barrier
	s_add_i32 m0, s54, 0xc000
	ds_read_b128 v[198:201], v237 offset:16384
	ds_read_b128 v[202:205], v237 offset:17408
	ds_read_b128 v[206:209], v237 offset:18432
	global_load_lds_dwordx4 v186, s[10:11]
	s_add_i32 m0, s54, 0xe000
	ds_read_b128 v[210:213], v237 offset:19456
	global_load_lds_dwordx4 v188, s[10:11]
	s_add_u32 s98, s2, 0x80
	s_addc_u32 s99, s3, 0
	s_add_i32 m0, s53, 0x10000
	s_nop 0
	global_load_lds_dwordx4 v168, s[2:3]
	s_add_i32 m0, s53, 0x12000
	s_nop 0
	global_load_lds_dwordx4 v184, s[2:3]
	s_barrier
	s_waitcnt lgkmcnt(0)
	v_mfma_f32_16x16x32_bf16 v[144:147], v[198:201], v[112:115], 0
	v_mfma_f32_16x16x32_bf16 v[60:63], v[206:209], v[112:115], 0
	v_mfma_f32_16x16x32_bf16 v[56:59], v[206:209], v[120:123], 0
	v_mfma_f32_16x16x32_bf16 v[36:39], v[206:209], v[160:163], 0
	v_mfma_f32_16x16x32_bf16 v[32:35], v[206:209], v[190:193], 0
	v_mfma_f32_16x16x32_bf16 v[144:147], v[202:205], v[116:119], v[144:147]
	v_mfma_f32_16x16x32_bf16 v[60:63], v[210:213], v[116:119], v[60:63]
	v_mfma_f32_16x16x32_bf16 v[112:115], v[198:201], v[120:123], 0
	v_mfma_f32_16x16x32_bf16 v[56:59], v[210:213], v[156:159], v[56:59]
	v_mfma_f32_16x16x32_bf16 v[116:119], v[198:201], v[160:163], 0
	v_mfma_f32_16x16x32_bf16 v[36:39], v[210:213], v[164:167], v[36:39]
	v_mfma_f32_16x16x32_bf16 v[120:123], v[198:201], v[190:193], 0
	v_mfma_f32_16x16x32_bf16 v[32:35], v[210:213], v[194:197], v[32:35]
	v_mfma_f32_16x16x32_bf16 v[112:115], v[202:205], v[156:159], v[112:115]
	v_mfma_f32_16x16x32_bf16 v[116:119], v[202:205], v[164:167], v[116:119]
	v_mfma_f32_16x16x32_bf16 v[120:123], v[202:205], v[194:197], v[120:123]
	s_mov_b32 m0, s54
	s_add_u32 s100, s12, 0x80
	s_addc_u32 s101, s13, 0
	s_barrier
	ds_read_b128 v[124:127], v238 offset:16384
	ds_read_b128 v[132:135], v238 offset:17408
	ds_read_b128 v[140:143], v238 offset:18432
	ds_read_b128 v[156:159], v238 offset:19456
	ds_read_b128 v[160:163], v238 offset:20480
	ds_read_b128 v[164:167], v238 offset:21504
	ds_read_b128 v[190:193], v238 offset:22528
	global_load_lds_dwordx4 v180, s[12:13]
	s_mov_b32 m0, s55
	ds_read_b128 v[194:197], v238 offset:23552
	global_load_lds_dwordx4 v182, s[12:13]
	s_barrier
	s_waitcnt lgkmcnt(0)
	v_mfma_f32_16x16x32_bf16 v[100:103], v[48:51], v[124:127], 0
	v_mfma_f32_16x16x32_bf16 v[28:31], v[104:107], v[124:127], 0
	v_mfma_f32_16x16x32_bf16 v[96:99], v[48:51], v[140:143], 0
	v_mfma_f32_16x16x32_bf16 v[24:27], v[104:107], v[140:143], 0
	v_mfma_f32_16x16x32_bf16 v[84:87], v[48:51], v[160:163], 0
	v_mfma_f32_16x16x32_bf16 v[12:15], v[104:107], v[160:163], 0
	v_mfma_f32_16x16x32_bf16 v[8:11], v[104:107], v[190:193], 0
	v_mfma_f32_16x16x32_bf16 v[100:103], v[52:55], v[132:135], v[100:103]
	v_mfma_f32_16x16x32_bf16 v[28:31], v[108:111], v[132:135], v[28:31]
	v_mfma_f32_16x16x32_bf16 v[96:99], v[52:55], v[156:159], v[96:99]
	v_mfma_f32_16x16x32_bf16 v[24:27], v[108:111], v[156:159], v[24:27]
	v_mfma_f32_16x16x32_bf16 v[84:87], v[52:55], v[164:167], v[84:87]
	v_mfma_f32_16x16x32_bf16 v[12:15], v[108:111], v[164:167], v[12:15]
	v_mfma_f32_16x16x32_bf16 v[48:51], v[48:51], v[190:193], 0
	v_mfma_f32_16x16x32_bf16 v[8:11], v[108:111], v[194:197], v[8:11]
	v_mfma_f32_16x16x32_bf16 v[48:51], v[52:55], v[194:197], v[48:51]
	s_barrier
	s_add_i32 m0, s53, 0x14000
	s_add_u32 s68, s2, 0x40000
	s_addc_u32 s69, s3, 0
	global_load_lds_dwordx4 v168, s[68:69]
	s_add_i32 m0, s53, 0x16000
	s_add_u32 s12, s12, 0x40000
	s_addc_u32 s13, s13, 0
	global_load_lds_dwordx4 v184, s[68:69]
	s_waitcnt vmcnt(6)
	s_barrier
	v_mfma_f32_16x16x32_bf16 v[76:79], v[198:201], v[140:143], 0
	v_mfma_f32_16x16x32_bf16 v[20:23], v[206:209], v[124:127], 0
	v_mfma_f32_16x16x32_bf16 v[88:91], v[202:205], v[156:159], v[76:79]
	v_mfma_f32_16x16x32_bf16 v[16:19], v[206:209], v[140:143], 0
	v_mfma_f32_16x16x32_bf16 v[76:79], v[198:201], v[160:163], 0
	v_mfma_f32_16x16x32_bf16 v[4:7], v[206:209], v[160:163], 0
	v_mfma_f32_16x16x32_bf16 v[72:75], v[198:201], v[190:193], 0
	v_mfma_f32_16x16x32_bf16 v[0:3], v[206:209], v[190:193], 0
	v_mfma_f32_16x16x32_bf16 v[52:55], v[198:201], v[124:127], 0
	v_mfma_f32_16x16x32_bf16 v[20:23], v[210:213], v[132:135], v[20:23]
	v_mfma_f32_16x16x32_bf16 v[16:19], v[210:213], v[156:159], v[16:19]
	v_mfma_f32_16x16x32_bf16 v[80:83], v[202:205], v[164:167], v[76:79]
	v_mfma_f32_16x16x32_bf16 v[4:7], v[210:213], v[164:167], v[4:7]
	v_mfma_f32_16x16x32_bf16 v[72:75], v[202:205], v[194:197], v[72:75]
	v_mfma_f32_16x16x32_bf16 v[0:3], v[210:213], v[194:197], v[0:3]
	v_mfma_f32_16x16x32_bf16 v[52:55], v[202:205], v[132:135], v[52:55]
	s_barrier
	ds_read_b128 v[76:79], v237 offset:32768
	ds_read_b128 v[92:95], v237 offset:33792
	ds_read_b128 v[104:107], v237 offset:34816
	ds_read_b128 v[108:111], v237 offset:35840
	ds_read_b128 v[124:127], v238 offset:32768
	ds_read_b128 v[132:135], v238 offset:33792
	ds_read_b128 v[156:159], v238 offset:34816
	ds_read_b128 v[160:163], v238 offset:35840
	ds_read_b128 v[164:167], v238 offset:36864
	ds_read_b128 v[190:193], v238 offset:37888
	ds_read_b128 v[194:197], v238 offset:38912
	ds_read_b128 v[198:201], v238 offset:39936
	s_waitcnt lgkmcnt(8)
	s_barrier
	s_waitcnt lgkmcnt(0)
	v_mfma_f32_16x16x32_bf16 v[140:143], v[76:79], v[124:127], v[152:155]
	v_mfma_f32_16x16x32_bf16 v[152:155], v[92:95], v[132:135], v[140:143]
	v_mfma_f32_16x16x32_bf16 v[68:71], v[104:107], v[124:127], v[68:71]
	v_mfma_f32_16x16x32_bf16 v[140:143], v[76:79], v[156:159], v[148:151]
	v_mfma_f32_16x16x32_bf16 v[64:67], v[104:107], v[156:159], v[64:67]
	v_mfma_f32_16x16x32_bf16 v[136:139], v[76:79], v[164:167], v[136:139]
	v_mfma_f32_16x16x32_bf16 v[44:47], v[104:107], v[164:167], v[44:47]
	v_mfma_f32_16x16x32_bf16 v[128:131], v[76:79], v[194:197], v[128:131]
	v_mfma_f32_16x16x32_bf16 v[40:43], v[104:107], v[194:197], v[40:43]
	v_mfma_f32_16x16x32_bf16 v[68:71], v[108:111], v[132:135], v[68:71]
	v_mfma_f32_16x16x32_bf16 v[148:151], v[92:95], v[160:163], v[140:143]
	v_mfma_f32_16x16x32_bf16 v[64:67], v[108:111], v[160:163], v[64:67]
	v_mfma_f32_16x16x32_bf16 v[136:139], v[92:95], v[190:193], v[136:139]
	v_mfma_f32_16x16x32_bf16 v[44:47], v[108:111], v[190:193], v[44:47]
	v_mfma_f32_16x16x32_bf16 v[128:131], v[92:95], v[198:201], v[128:131]
	v_mfma_f32_16x16x32_bf16 v[40:43], v[108:111], v[198:201], v[40:43]
	s_barrier
	s_mov_b32 m0, s56
	ds_read_b128 v[202:205], v237 offset:49152
	ds_read_b128 v[206:209], v237 offset:50176
	ds_read_b128 v[210:213], v237 offset:51200
	global_load_lds_dwordx4 v180, s[12:13]
	s_mov_b32 m0, s57
	ds_read_b128 v[214:217], v237 offset:52224
	global_load_lds_dwordx4 v182, s[12:13]
	s_add_i32 m0, s53, 0x18000
	s_nop 0
	global_load_lds_dwordx4 v168, s[98:99]
	s_add_i32 m0, s53, 0x1a000
	s_nop 0
	global_load_lds_dwordx4 v184, s[98:99]
	s_barrier
	s_waitcnt lgkmcnt(0)
	v_mfma_f32_16x16x32_bf16 v[140:143], v[202:205], v[124:127], v[144:147]
	v_mfma_f32_16x16x32_bf16 v[112:115], v[202:205], v[156:159], v[112:115]
	v_mfma_f32_16x16x32_bf16 v[144:147], v[206:209], v[132:135], v[140:143]
	v_mfma_f32_16x16x32_bf16 v[60:63], v[210:213], v[124:127], v[60:63]
	v_mfma_f32_16x16x32_bf16 v[140:143], v[206:209], v[160:163], v[112:115]
	v_mfma_f32_16x16x32_bf16 v[112:115], v[202:205], v[164:167], v[116:119]
	v_mfma_f32_16x16x32_bf16 v[60:63], v[214:217], v[132:135], v[60:63]
	v_mfma_f32_16x16x32_bf16 v[56:59], v[210:213], v[156:159], v[56:59]
	v_mfma_f32_16x16x32_bf16 v[132:135], v[206:209], v[190:193], v[112:115]
	v_mfma_f32_16x16x32_bf16 v[36:39], v[210:213], v[164:167], v[36:39]
	v_mfma_f32_16x16x32_bf16 v[112:115], v[202:205], v[194:197], v[120:123]
	v_mfma_f32_16x16x32_bf16 v[32:35], v[210:213], v[194:197], v[32:35]
	v_mfma_f32_16x16x32_bf16 v[56:59], v[214:217], v[160:163], v[56:59]
	v_mfma_f32_16x16x32_bf16 v[36:39], v[214:217], v[190:193], v[36:39]
	v_mfma_f32_16x16x32_bf16 v[124:127], v[206:209], v[198:201], v[112:115]
	v_mfma_f32_16x16x32_bf16 v[32:35], v[214:217], v[198:201], v[32:35]
	s_mov_b32 m0, s62
	s_barrier
	ds_read_b128 v[112:115], v238 offset:49152
	ds_read_b128 v[116:119], v238 offset:50176
	ds_read_b128 v[120:123], v238 offset:51200
	ds_read_b128 v[156:159], v238 offset:52224
	ds_read_b128 v[160:163], v238 offset:53248
	ds_read_b128 v[164:167], v238 offset:54272
	ds_read_b128 v[190:193], v238 offset:55296
	global_load_lds_dwordx4 v180, s[100:101]
	s_mov_b32 m0, s63
	ds_read_b128 v[194:197], v238 offset:56320
	global_load_lds_dwordx4 v182, s[100:101]
	s_barrier
	s_waitcnt lgkmcnt(0)
	v_mfma_f32_16x16x32_bf16 v[100:103], v[76:79], v[112:115], v[100:103]
	v_mfma_f32_16x16x32_bf16 v[28:31], v[104:107], v[112:115], v[28:31]
	v_mfma_f32_16x16x32_bf16 v[96:99], v[76:79], v[120:123], v[96:99]
	v_mfma_f32_16x16x32_bf16 v[24:27], v[104:107], v[120:123], v[24:27]
	v_mfma_f32_16x16x32_bf16 v[84:87], v[76:79], v[160:163], v[84:87]
	v_mfma_f32_16x16x32_bf16 v[12:15], v[104:107], v[160:163], v[12:15]
	v_mfma_f32_16x16x32_bf16 v[48:51], v[76:79], v[190:193], v[48:51]
	v_mfma_f32_16x16x32_bf16 v[8:11], v[104:107], v[190:193], v[8:11]
	v_mfma_f32_16x16x32_bf16 v[100:103], v[92:95], v[116:119], v[100:103]
	v_mfma_f32_16x16x32_bf16 v[28:31], v[108:111], v[116:119], v[28:31]
	v_mfma_f32_16x16x32_bf16 v[96:99], v[92:95], v[156:159], v[96:99]
	v_mfma_f32_16x16x32_bf16 v[24:27], v[108:111], v[156:159], v[24:27]
	v_mfma_f32_16x16x32_bf16 v[84:87], v[92:95], v[164:167], v[84:87]
	v_mfma_f32_16x16x32_bf16 v[12:15], v[108:111], v[164:167], v[12:15]
	v_mfma_f32_16x16x32_bf16 v[76:79], v[92:95], v[194:197], v[48:51]
	v_mfma_f32_16x16x32_bf16 v[8:11], v[108:111], v[194:197], v[8:11]
	s_barrier
	s_add_i32 m0, s53, 0x1c000
	s_add_u32 s2, s2, 0x40080
	s_addc_u32 s3, s3, 0
	global_load_lds_dwordx4 v168, s[2:3]
	s_add_i32 m0, s53, 0x1e000
	s_add_i32 s67, s67, 2
	global_load_lds_dwordx4 v184, s[2:3]
	s_waitcnt vmcnt(6)
	s_barrier
	v_mfma_f32_16x16x32_bf16 v[48:51], v[202:205], v[112:115], v[52:55]
	v_mfma_f32_16x16x32_bf16 v[92:95], v[206:209], v[116:119], v[48:51]
	v_mfma_f32_16x16x32_bf16 v[48:51], v[202:205], v[120:123], v[88:91]
	v_mfma_f32_16x16x32_bf16 v[88:91], v[206:209], v[156:159], v[48:51]
	v_mfma_f32_16x16x32_bf16 v[48:51], v[202:205], v[160:163], v[80:83]
	v_mfma_f32_16x16x32_bf16 v[20:23], v[210:213], v[112:115], v[20:23]
	v_mfma_f32_16x16x32_bf16 v[16:19], v[210:213], v[120:123], v[16:19]
	v_mfma_f32_16x16x32_bf16 v[80:83], v[206:209], v[164:167], v[48:51]
	v_mfma_f32_16x16x32_bf16 v[4:7], v[210:213], v[160:163], v[4:7]
	v_mfma_f32_16x16x32_bf16 v[48:51], v[202:205], v[190:193], v[72:75]
	v_mfma_f32_16x16x32_bf16 v[0:3], v[210:213], v[190:193], v[0:3]
	v_mfma_f32_16x16x32_bf16 v[20:23], v[214:217], v[116:119], v[20:23]
	v_mfma_f32_16x16x32_bf16 v[16:19], v[214:217], v[156:159], v[16:19]
	v_mfma_f32_16x16x32_bf16 v[4:7], v[214:217], v[164:167], v[4:7]
	v_mfma_f32_16x16x32_bf16 v[72:75], v[206:209], v[194:197], v[48:51]
	v_mfma_f32_16x16x32_bf16 v[0:3], v[214:217], v[194:197], v[0:3]
	s_add_u32 s10, s10, 0x100
	s_addc_u32 s11, s11, 0
	s_add_u32 s37, s37, 0x100
	s_addc_u32 s39, s39, 0
	s_cmp_gt_u32 s67, 13
	s_barrier
.LBB0_880:
	s_add_u32 s2, s10, 0xfffc0080
	s_addc_u32 s3, s11, -1
	ds_read_b128 v[48:51], v237
	ds_read_b128 v[52:55], v237 offset:1024
	ds_read_b128 v[104:107], v237 offset:2048
	ds_read_b128 v[108:111], v237 offset:3072
	s_cmp_eq_u32 s67, 12
	s_cselect_b32 s13, s1, s3
	s_cselect_b32 s12, s9, s2
	s_cselect_b32 s3, s14, s39
	s_cselect_b32 s2, s15, s37
	ds_read_b128 v[112:115], v238
	ds_read_b128 v[116:119], v238 offset:1024
	ds_read_b128 v[120:123], v238 offset:2048
	ds_read_b128 v[156:159], v238 offset:3072
	ds_read_b128 v[160:163], v238 offset:4096
	ds_read_b128 v[164:167], v238 offset:5120
	ds_read_b128 v[190:193], v238 offset:6144
	ds_read_b128 v[194:197], v238 offset:7168
	s_waitcnt lgkmcnt(8)
	s_barrier
	s_waitcnt lgkmcnt(0)
	v_mfma_f32_16x16x32_bf16 v[152:155], v[48:51], v[112:115], v[152:155]
	v_mfma_f32_16x16x32_bf16 v[68:71], v[104:107], v[112:115], v[68:71]
	v_mfma_f32_16x16x32_bf16 v[148:151], v[48:51], v[120:123], v[148:151]
	v_mfma_f32_16x16x32_bf16 v[64:67], v[104:107], v[120:123], v[64:67]
	v_mfma_f32_16x16x32_bf16 v[136:139], v[48:51], v[160:163], v[136:139]
	v_mfma_f32_16x16x32_bf16 v[44:47], v[104:107], v[160:163], v[44:47]
	v_mfma_f32_16x16x32_bf16 v[128:131], v[48:51], v[190:193], v[128:131]
	v_mfma_f32_16x16x32_bf16 v[40:43], v[104:107], v[190:193], v[40:43]
	v_mfma_f32_16x16x32_bf16 v[152:155], v[52:55], v[116:119], v[152:155]
	v_mfma_f32_16x16x32_bf16 v[68:71], v[108:111], v[116:119], v[68:71]
	v_mfma_f32_16x16x32_bf16 v[148:151], v[52:55], v[156:159], v[148:151]
	v_mfma_f32_16x16x32_bf16 v[64:67], v[108:111], v[156:159], v[64:67]
	v_mfma_f32_16x16x32_bf16 v[136:139], v[52:55], v[164:167], v[136:139]
	v_mfma_f32_16x16x32_bf16 v[44:47], v[108:111], v[164:167], v[44:47]
	v_mfma_f32_16x16x32_bf16 v[128:131], v[52:55], v[194:197], v[128:131]
	v_mfma_f32_16x16x32_bf16 v[40:43], v[108:111], v[194:197], v[40:43]
	s_barrier
	s_add_i32 m0, s54, 0xc000
	ds_read_b128 v[198:201], v237 offset:16384
	ds_read_b128 v[202:205], v237 offset:17408
	ds_read_b128 v[206:209], v237 offset:18432
	global_load_lds_dwordx4 v186, s[10:11]
	s_add_i32 m0, s54, 0xe000
	ds_read_b128 v[210:213], v237 offset:19456
	global_load_lds_dwordx4 v188, s[10:11]
	s_add_u32 s98, s2, 0x80
	s_addc_u32 s99, s3, 0
	s_add_i32 m0, s53, 0x10000
	s_nop 0
	global_load_lds_dwordx4 v168, s[2:3]
	s_add_i32 m0, s53, 0x12000
	s_nop 0
	global_load_lds_dwordx4 v184, s[2:3]
	s_barrier
	s_waitcnt lgkmcnt(0)
	v_mfma_f32_16x16x32_bf16 v[144:147], v[198:201], v[112:115], v[144:147]
	v_mfma_f32_16x16x32_bf16 v[60:63], v[206:209], v[112:115], v[60:63]
	v_mfma_f32_16x16x32_bf16 v[56:59], v[206:209], v[120:123], v[56:59]
	v_mfma_f32_16x16x32_bf16 v[36:39], v[206:209], v[160:163], v[36:39]
	v_mfma_f32_16x16x32_bf16 v[32:35], v[206:209], v[190:193], v[32:35]
	v_mfma_f32_16x16x32_bf16 v[144:147], v[202:205], v[116:119], v[144:147]
	v_mfma_f32_16x16x32_bf16 v[60:63], v[210:213], v[116:119], v[60:63]
	v_mfma_f32_16x16x32_bf16 v[112:115], v[198:201], v[120:123], v[140:143]
	v_mfma_f32_16x16x32_bf16 v[56:59], v[210:213], v[156:159], v[56:59]
	v_mfma_f32_16x16x32_bf16 v[116:119], v[198:201], v[160:163], v[132:135]
	v_mfma_f32_16x16x32_bf16 v[36:39], v[210:213], v[164:167], v[36:39]
	v_mfma_f32_16x16x32_bf16 v[120:123], v[198:201], v[190:193], v[124:127]
	v_mfma_f32_16x16x32_bf16 v[32:35], v[210:213], v[194:197], v[32:35]
	v_mfma_f32_16x16x32_bf16 v[112:115], v[202:205], v[156:159], v[112:115]
	v_mfma_f32_16x16x32_bf16 v[116:119], v[202:205], v[164:167], v[116:119]
	v_mfma_f32_16x16x32_bf16 v[120:123], v[202:205], v[194:197], v[120:123]
	s_mov_b32 m0, s54
	s_add_u32 s100, s12, 0x80
	s_addc_u32 s101, s13, 0
	s_barrier
	ds_read_b128 v[124:127], v238 offset:16384
	ds_read_b128 v[132:135], v238 offset:17408
	ds_read_b128 v[140:143], v238 offset:18432
	ds_read_b128 v[156:159], v238 offset:19456
	ds_read_b128 v[160:163], v238 offset:20480
	ds_read_b128 v[164:167], v238 offset:21504
	ds_read_b128 v[190:193], v238 offset:22528
	global_load_lds_dwordx4 v180, s[12:13]
	s_mov_b32 m0, s55
	ds_read_b128 v[194:197], v238 offset:23552
	global_load_lds_dwordx4 v182, s[12:13]
	s_barrier
	s_waitcnt lgkmcnt(0)
	v_mfma_f32_16x16x32_bf16 v[100:103], v[48:51], v[124:127], v[100:103]
	v_mfma_f32_16x16x32_bf16 v[28:31], v[104:107], v[124:127], v[28:31]
	v_mfma_f32_16x16x32_bf16 v[96:99], v[48:51], v[140:143], v[96:99]
	v_mfma_f32_16x16x32_bf16 v[24:27], v[104:107], v[140:143], v[24:27]
	v_mfma_f32_16x16x32_bf16 v[84:87], v[48:51], v[160:163], v[84:87]
	v_mfma_f32_16x16x32_bf16 v[12:15], v[104:107], v[160:163], v[12:15]
	v_mfma_f32_16x16x32_bf16 v[8:11], v[104:107], v[190:193], v[8:11]
	v_mfma_f32_16x16x32_bf16 v[100:103], v[52:55], v[132:135], v[100:103]
	v_mfma_f32_16x16x32_bf16 v[28:31], v[108:111], v[132:135], v[28:31]
	v_mfma_f32_16x16x32_bf16 v[96:99], v[52:55], v[156:159], v[96:99]
	v_mfma_f32_16x16x32_bf16 v[24:27], v[108:111], v[156:159], v[24:27]
	v_mfma_f32_16x16x32_bf16 v[84:87], v[52:55], v[164:167], v[84:87]
	v_mfma_f32_16x16x32_bf16 v[12:15], v[108:111], v[164:167], v[12:15]
	v_mfma_f32_16x16x32_bf16 v[48:51], v[48:51], v[190:193], v[76:79]
	v_mfma_f32_16x16x32_bf16 v[8:11], v[108:111], v[194:197], v[8:11]
	v_mfma_f32_16x16x32_bf16 v[48:51], v[52:55], v[194:197], v[48:51]
	s_barrier
	s_add_i32 m0, s53, 0x14000
	s_add_u32 s68, s2, 0x40000
	s_addc_u32 s69, s3, 0
	global_load_lds_dwordx4 v168, s[68:69]
	s_add_i32 m0, s53, 0x16000
	s_add_u32 s12, s12, 0x40000
	s_addc_u32 s13, s13, 0
	global_load_lds_dwordx4 v184, s[68:69]
	s_waitcnt vmcnt(6)
	s_barrier
	v_mfma_f32_16x16x32_bf16 v[76:79], v[198:201], v[140:143], v[88:91]
	v_mfma_f32_16x16x32_bf16 v[20:23], v[206:209], v[124:127], v[20:23]
	v_mfma_f32_16x16x32_bf16 v[88:91], v[202:205], v[156:159], v[76:79]
	v_mfma_f32_16x16x32_bf16 v[16:19], v[206:209], v[140:143], v[16:19]
	v_mfma_f32_16x16x32_bf16 v[76:79], v[198:201], v[160:163], v[80:83]
	v_mfma_f32_16x16x32_bf16 v[4:7], v[206:209], v[160:163], v[4:7]
	v_mfma_f32_16x16x32_bf16 v[72:75], v[198:201], v[190:193], v[72:75]
	v_mfma_f32_16x16x32_bf16 v[0:3], v[206:209], v[190:193], v[0:3]
	v_mfma_f32_16x16x32_bf16 v[52:55], v[198:201], v[124:127], v[92:95]
	v_mfma_f32_16x16x32_bf16 v[20:23], v[210:213], v[132:135], v[20:23]
	v_mfma_f32_16x16x32_bf16 v[16:19], v[210:213], v[156:159], v[16:19]
	v_mfma_f32_16x16x32_bf16 v[80:83], v[202:205], v[164:167], v[76:79]
	v_mfma_f32_16x16x32_bf16 v[4:7], v[210:213], v[164:167], v[4:7]
	v_mfma_f32_16x16x32_bf16 v[72:75], v[202:205], v[194:197], v[72:75]
	v_mfma_f32_16x16x32_bf16 v[0:3], v[210:213], v[194:197], v[0:3]
	v_mfma_f32_16x16x32_bf16 v[52:55], v[202:205], v[132:135], v[52:55]
	s_barrier
	ds_read_b128 v[76:79], v237 offset:32768
	ds_read_b128 v[92:95], v237 offset:33792
	ds_read_b128 v[104:107], v237 offset:34816
	ds_read_b128 v[108:111], v237 offset:35840
	ds_read_b128 v[124:127], v238 offset:32768
	ds_read_b128 v[132:135], v238 offset:33792
	ds_read_b128 v[156:159], v238 offset:34816
	ds_read_b128 v[160:163], v238 offset:35840
	ds_read_b128 v[164:167], v238 offset:36864
	ds_read_b128 v[190:193], v238 offset:37888
	ds_read_b128 v[194:197], v238 offset:38912
	ds_read_b128 v[198:201], v238 offset:39936
	s_waitcnt lgkmcnt(8)
	s_barrier
	s_waitcnt lgkmcnt(0)
	v_mfma_f32_16x16x32_bf16 v[140:143], v[76:79], v[124:127], v[152:155]
	v_mfma_f32_16x16x32_bf16 v[152:155], v[92:95], v[132:135], v[140:143]
	v_mfma_f32_16x16x32_bf16 v[68:71], v[104:107], v[124:127], v[68:71]
	v_mfma_f32_16x16x32_bf16 v[140:143], v[76:79], v[156:159], v[148:151]
	v_mfma_f32_16x16x32_bf16 v[64:67], v[104:107], v[156:159], v[64:67]
	v_mfma_f32_16x16x32_bf16 v[136:139], v[76:79], v[164:167], v[136:139]
	v_mfma_f32_16x16x32_bf16 v[44:47], v[104:107], v[164:167], v[44:47]
	v_mfma_f32_16x16x32_bf16 v[128:131], v[76:79], v[194:197], v[128:131]
	v_mfma_f32_16x16x32_bf16 v[40:43], v[104:107], v[194:197], v[40:43]
	v_mfma_f32_16x16x32_bf16 v[68:71], v[108:111], v[132:135], v[68:71]
	v_mfma_f32_16x16x32_bf16 v[148:151], v[92:95], v[160:163], v[140:143]
	v_mfma_f32_16x16x32_bf16 v[64:67], v[108:111], v[160:163], v[64:67]
	v_mfma_f32_16x16x32_bf16 v[136:139], v[92:95], v[190:193], v[136:139]
	v_mfma_f32_16x16x32_bf16 v[44:47], v[108:111], v[190:193], v[44:47]
	v_mfma_f32_16x16x32_bf16 v[128:131], v[92:95], v[198:201], v[128:131]
	v_mfma_f32_16x16x32_bf16 v[40:43], v[108:111], v[198:201], v[40:43]
	s_barrier
	s_mov_b32 m0, s56
	ds_read_b128 v[202:205], v237 offset:49152
	ds_read_b128 v[206:209], v237 offset:50176
	ds_read_b128 v[210:213], v237 offset:51200
	global_load_lds_dwordx4 v180, s[12:13]
	s_mov_b32 m0, s57
	ds_read_b128 v[214:217], v237 offset:52224
	global_load_lds_dwordx4 v182, s[12:13]
	s_add_i32 m0, s53, 0x18000
	s_nop 0
	global_load_lds_dwordx4 v168, s[98:99]
	s_add_i32 m0, s53, 0x1a000
	s_nop 0
	global_load_lds_dwordx4 v184, s[98:99]
	s_barrier
	s_waitcnt lgkmcnt(0)
	v_mfma_f32_16x16x32_bf16 v[140:143], v[202:205], v[124:127], v[144:147]
	v_mfma_f32_16x16x32_bf16 v[112:115], v[202:205], v[156:159], v[112:115]
	v_mfma_f32_16x16x32_bf16 v[144:147], v[206:209], v[132:135], v[140:143]
	v_mfma_f32_16x16x32_bf16 v[60:63], v[210:213], v[124:127], v[60:63]
	v_mfma_f32_16x16x32_bf16 v[140:143], v[206:209], v[160:163], v[112:115]
	v_mfma_f32_16x16x32_bf16 v[112:115], v[202:205], v[164:167], v[116:119]
	v_mfma_f32_16x16x32_bf16 v[60:63], v[214:217], v[132:135], v[60:63]
	v_mfma_f32_16x16x32_bf16 v[56:59], v[210:213], v[156:159], v[56:59]
	v_mfma_f32_16x16x32_bf16 v[132:135], v[206:209], v[190:193], v[112:115]
	v_mfma_f32_16x16x32_bf16 v[36:39], v[210:213], v[164:167], v[36:39]
	v_mfma_f32_16x16x32_bf16 v[112:115], v[202:205], v[194:197], v[120:123]
	v_mfma_f32_16x16x32_bf16 v[32:35], v[210:213], v[194:197], v[32:35]
	v_mfma_f32_16x16x32_bf16 v[56:59], v[214:217], v[160:163], v[56:59]
	v_mfma_f32_16x16x32_bf16 v[36:39], v[214:217], v[190:193], v[36:39]
	v_mfma_f32_16x16x32_bf16 v[124:127], v[206:209], v[198:201], v[112:115]
	v_mfma_f32_16x16x32_bf16 v[32:35], v[214:217], v[198:201], v[32:35]
	s_mov_b32 m0, s62
	s_barrier
	ds_read_b128 v[112:115], v238 offset:49152
	ds_read_b128 v[116:119], v238 offset:50176
	ds_read_b128 v[120:123], v238 offset:51200
	ds_read_b128 v[156:159], v238 offset:52224
	ds_read_b128 v[160:163], v238 offset:53248
	ds_read_b128 v[164:167], v238 offset:54272
	ds_read_b128 v[190:193], v238 offset:55296
	global_load_lds_dwordx4 v180, s[100:101]
	s_mov_b32 m0, s63
	ds_read_b128 v[194:197], v238 offset:56320
	global_load_lds_dwordx4 v182, s[100:101]
	s_barrier
	s_waitcnt lgkmcnt(0)
	v_mfma_f32_16x16x32_bf16 v[100:103], v[76:79], v[112:115], v[100:103]
	v_mfma_f32_16x16x32_bf16 v[28:31], v[104:107], v[112:115], v[28:31]
	v_mfma_f32_16x16x32_bf16 v[96:99], v[76:79], v[120:123], v[96:99]
	v_mfma_f32_16x16x32_bf16 v[24:27], v[104:107], v[120:123], v[24:27]
	v_mfma_f32_16x16x32_bf16 v[84:87], v[76:79], v[160:163], v[84:87]
	v_mfma_f32_16x16x32_bf16 v[12:15], v[104:107], v[160:163], v[12:15]
	v_mfma_f32_16x16x32_bf16 v[48:51], v[76:79], v[190:193], v[48:51]
	v_mfma_f32_16x16x32_bf16 v[8:11], v[104:107], v[190:193], v[8:11]
	v_mfma_f32_16x16x32_bf16 v[100:103], v[92:95], v[116:119], v[100:103]
	v_mfma_f32_16x16x32_bf16 v[28:31], v[108:111], v[116:119], v[28:31]
	v_mfma_f32_16x16x32_bf16 v[96:99], v[92:95], v[156:159], v[96:99]
	v_mfma_f32_16x16x32_bf16 v[24:27], v[108:111], v[156:159], v[24:27]
	v_mfma_f32_16x16x32_bf16 v[84:87], v[92:95], v[164:167], v[84:87]
	v_mfma_f32_16x16x32_bf16 v[12:15], v[108:111], v[164:167], v[12:15]
	v_mfma_f32_16x16x32_bf16 v[76:79], v[92:95], v[194:197], v[48:51]
	v_mfma_f32_16x16x32_bf16 v[8:11], v[108:111], v[194:197], v[8:11]
	s_barrier
	s_add_i32 m0, s53, 0x1c000
	s_add_u32 s2, s2, 0x40080
	s_addc_u32 s3, s3, 0
	global_load_lds_dwordx4 v168, s[2:3]
	s_add_i32 m0, s53, 0x1e000
	s_add_i32 s67, s67, 2
	global_load_lds_dwordx4 v184, s[2:3]
	s_waitcnt vmcnt(6)
	s_barrier
	v_mfma_f32_16x16x32_bf16 v[48:51], v[202:205], v[112:115], v[52:55]
	v_mfma_f32_16x16x32_bf16 v[92:95], v[206:209], v[116:119], v[48:51]
	v_mfma_f32_16x16x32_bf16 v[48:51], v[202:205], v[120:123], v[88:91]
	v_mfma_f32_16x16x32_bf16 v[88:91], v[206:209], v[156:159], v[48:51]
	v_mfma_f32_16x16x32_bf16 v[48:51], v[202:205], v[160:163], v[80:83]
	v_mfma_f32_16x16x32_bf16 v[20:23], v[210:213], v[112:115], v[20:23]
	v_mfma_f32_16x16x32_bf16 v[16:19], v[210:213], v[120:123], v[16:19]
	v_mfma_f32_16x16x32_bf16 v[80:83], v[206:209], v[164:167], v[48:51]
	v_mfma_f32_16x16x32_bf16 v[4:7], v[210:213], v[160:163], v[4:7]
	v_mfma_f32_16x16x32_bf16 v[48:51], v[202:205], v[190:193], v[72:75]
	v_mfma_f32_16x16x32_bf16 v[0:3], v[210:213], v[190:193], v[0:3]
	v_mfma_f32_16x16x32_bf16 v[20:23], v[214:217], v[116:119], v[20:23]
	v_mfma_f32_16x16x32_bf16 v[16:19], v[214:217], v[156:159], v[16:19]
	v_mfma_f32_16x16x32_bf16 v[4:7], v[214:217], v[164:167], v[4:7]
	v_mfma_f32_16x16x32_bf16 v[72:75], v[206:209], v[194:197], v[48:51]
	v_mfma_f32_16x16x32_bf16 v[0:3], v[214:217], v[194:197], v[0:3]
	s_add_u32 s10, s10, 0x100
	s_addc_u32 s11, s11, 0
	s_add_u32 s37, s37, 0x100
	s_addc_u32 s39, s39, 0
	s_cmp_gt_u32 s67, 13
	s_barrier
	s_cbranch_scc0 .LBB0_880

.LBB0_1048:
	s_add_u32 s56, s2, 0x100
	s_addc_u32 s57, s3, 0
	s_mov_b32 s58, -2
	s_add_u32 s2, s24, 0x100
	s_addc_u32 s3, s25, 0
	ds_read_b128 v[40:43], v194
	ds_read_b128 v[44:47], v194 offset:1024
	ds_read_b128 v[48:51], v194 offset:2048
	ds_read_b128 v[52:55], v194 offset:3072
	s_cmp_eq_u32 s58, 40
	s_cselect_b32 s27, s1, s3
	s_cselect_b32 s26, s0, s2
	s_cselect_b32 s9, s23, s57
	s_cselect_b32 s8, s22, s56
	ds_read_b128 v[56:59], v195
	ds_read_b128 v[60:63], v195 offset:1024
	ds_read_b128 v[72:75], v195 offset:2048
	ds_read_b128 v[84:87], v195 offset:3072
	ds_read_b128 v[182:185], v195 offset:4096
	ds_read_b128 v[186:189], v195 offset:5120
	ds_read_b128 v[196:199], v195 offset:6144
	ds_read_b128 v[200:203], v195 offset:7168
	s_waitcnt lgkmcnt(8)
	s_barrier
	s_waitcnt lgkmcnt(0)
	v_mfma_f32_16x16x32_bf16 v[156:159], v[40:43], v[56:59], 0
	v_mfma_f32_16x16x32_bf16 v[152:155], v[48:51], v[56:59], 0
	v_mfma_f32_16x16x32_bf16 v[140:143], v[40:43], v[72:75], 0
	v_mfma_f32_16x16x32_bf16 v[136:139], v[48:51], v[72:75], 0
	v_mfma_f32_16x16x32_bf16 v[124:127], v[40:43], v[182:185], 0
	v_mfma_f32_16x16x32_bf16 v[120:123], v[48:51], v[182:185], 0
	v_mfma_f32_16x16x32_bf16 v[108:111], v[40:43], v[196:199], 0
	v_mfma_f32_16x16x32_bf16 v[104:107], v[48:51], v[196:199], 0
	v_mfma_f32_16x16x32_bf16 v[156:159], v[44:47], v[60:63], v[156:159]
	v_mfma_f32_16x16x32_bf16 v[152:155], v[52:55], v[60:63], v[152:155]
	v_mfma_f32_16x16x32_bf16 v[140:143], v[44:47], v[84:87], v[140:143]
	v_mfma_f32_16x16x32_bf16 v[136:139], v[52:55], v[84:87], v[136:139]
	v_mfma_f32_16x16x32_bf16 v[124:127], v[44:47], v[186:189], v[124:127]
	v_mfma_f32_16x16x32_bf16 v[120:123], v[52:55], v[186:189], v[120:123]
	v_mfma_f32_16x16x32_bf16 v[108:111], v[44:47], v[200:203], v[108:111]
	v_mfma_f32_16x16x32_bf16 v[104:107], v[52:55], v[200:203], v[104:107]
	s_barrier
	s_add_i32 m0, s37, 0xc000
	ds_read_b128 v[204:207], v194 offset:16384
	ds_read_b128 v[208:211], v194 offset:17408
	ds_read_b128 v[212:215], v194 offset:18432
	global_load_lds_dwordx4 v166, s[24:25]
	s_add_i32 m0, s37, 0xe000
	ds_read_b128 v[216:219], v194 offset:19456
	global_load_lds_dwordx4 v180, s[24:25]
	s_add_u32 s98, s8, 0x80
	s_addc_u32 s99, s9, 0
	s_add_i32 m0, s36, 0x10000
	s_nop 0
	global_load_lds_dwordx4 v168, s[8:9]
	s_add_i32 m0, s36, 0x12000
	s_nop 0
	global_load_lds_dwordx4 v164, s[8:9]
	s_barrier
	s_waitcnt lgkmcnt(0)
	v_mfma_f32_16x16x32_bf16 v[148:151], v[204:207], v[56:59], 0
	v_mfma_f32_16x16x32_bf16 v[56:59], v[212:215], v[56:59], 0
	v_mfma_f32_16x16x32_bf16 v[148:151], v[208:211], v[60:63], v[148:151]
	v_mfma_f32_16x16x32_bf16 v[56:59], v[216:219], v[60:63], v[56:59]
	v_mfma_f32_16x16x32_bf16 v[60:63], v[204:207], v[72:75], 0
	v_mfma_f32_16x16x32_bf16 v[72:75], v[212:215], v[72:75], 0
	v_mfma_f32_16x16x32_bf16 v[112:115], v[212:215], v[182:185], 0
	v_mfma_f32_16x16x32_bf16 v[100:103], v[204:207], v[196:199], 0
	v_mfma_f32_16x16x32_bf16 v[96:99], v[212:215], v[196:199], 0
	v_mfma_f32_16x16x32_bf16 v[60:63], v[208:211], v[84:87], v[60:63]
	v_mfma_f32_16x16x32_bf16 v[72:75], v[216:219], v[84:87], v[72:75]
	v_mfma_f32_16x16x32_bf16 v[84:87], v[204:207], v[182:185], 0
	v_mfma_f32_16x16x32_bf16 v[112:115], v[216:219], v[186:189], v[112:115]
	v_mfma_f32_16x16x32_bf16 v[100:103], v[208:211], v[200:203], v[100:103]
	v_mfma_f32_16x16x32_bf16 v[96:99], v[216:219], v[200:203], v[96:99]
	v_mfma_f32_16x16x32_bf16 v[84:87], v[208:211], v[186:189], v[84:87]
	s_mov_b32 m0, s37
	s_add_u32 s100, s26, 0x80
	s_addc_u32 s101, s27, 0
	s_barrier
	ds_read_b128 v[116:119], v195 offset:16384
	ds_read_b128 v[128:131], v195 offset:17408
	ds_read_b128 v[132:135], v195 offset:18432
	ds_read_b128 v[144:147], v195 offset:19456
	ds_read_b128 v[182:185], v195 offset:20480
	ds_read_b128 v[186:189], v195 offset:21504
	ds_read_b128 v[196:199], v195 offset:22528
	global_load_lds_dwordx4 v160, s[26:27]
	s_mov_b32 m0, s38
	ds_read_b128 v[200:203], v195 offset:23552
	global_load_lds_dwordx4 v162, s[26:27]
	s_barrier
	s_waitcnt lgkmcnt(0)
	v_mfma_f32_16x16x32_bf16 v[92:95], v[40:43], v[116:119], 0
	v_mfma_f32_16x16x32_bf16 v[88:91], v[48:51], v[116:119], 0
	v_mfma_f32_16x16x32_bf16 v[68:71], v[40:43], v[132:135], 0
	v_mfma_f32_16x16x32_bf16 v[64:67], v[48:51], v[132:135], 0
	v_mfma_f32_16x16x32_bf16 v[28:31], v[40:43], v[182:185], 0
	v_mfma_f32_16x16x32_bf16 v[24:27], v[48:51], v[182:185], 0
	v_mfma_f32_16x16x32_bf16 v[12:15], v[40:43], v[196:199], 0
	v_mfma_f32_16x16x32_bf16 v[8:11], v[48:51], v[196:199], 0
	v_mfma_f32_16x16x32_bf16 v[92:95], v[44:47], v[128:131], v[92:95]
	v_mfma_f32_16x16x32_bf16 v[88:91], v[52:55], v[128:131], v[88:91]
	v_mfma_f32_16x16x32_bf16 v[68:71], v[44:47], v[144:147], v[68:71]
	v_mfma_f32_16x16x32_bf16 v[64:67], v[52:55], v[144:147], v[64:67]
	v_mfma_f32_16x16x32_bf16 v[28:31], v[44:47], v[186:189], v[28:31]
	v_mfma_f32_16x16x32_bf16 v[24:27], v[52:55], v[186:189], v[24:27]
	v_mfma_f32_16x16x32_bf16 v[12:15], v[44:47], v[200:203], v[12:15]
	v_mfma_f32_16x16x32_bf16 v[8:11], v[52:55], v[200:203], v[8:11]
	s_barrier
	s_add_i32 m0, s36, 0x14000
	s_add_u32 s24, s8, 0xb0000
	s_addc_u32 s25, s9, 0
	global_load_lds_dwordx4 v168, s[24:25]
	s_add_i32 m0, s36, 0x16000
	s_nop 0
	global_load_lds_dwordx4 v164, s[24:25]
	s_waitcnt vmcnt(6)
	s_barrier
	v_mfma_f32_16x16x32_bf16 v[36:39], v[204:207], v[132:135], 0
	v_mfma_f32_16x16x32_bf16 v[32:35], v[212:215], v[132:135], 0
	v_mfma_f32_16x16x32_bf16 v[20:23], v[204:207], v[182:185], 0
	v_mfma_f32_16x16x32_bf16 v[16:19], v[212:215], v[182:185], 0
	v_mfma_f32_16x16x32_bf16 v[4:7], v[204:207], v[196:199], 0
	v_mfma_f32_16x16x32_bf16 v[0:3], v[212:215], v[196:199], 0
	v_mfma_f32_16x16x32_bf16 v[40:43], v[204:207], v[116:119], 0
	v_mfma_f32_16x16x32_bf16 v[44:47], v[212:215], v[116:119], 0
	v_mfma_f32_16x16x32_bf16 v[36:39], v[208:211], v[144:147], v[36:39]
	v_mfma_f32_16x16x32_bf16 v[32:35], v[216:219], v[144:147], v[32:35]
	v_mfma_f32_16x16x32_bf16 v[20:23], v[208:211], v[186:189], v[20:23]
	v_mfma_f32_16x16x32_bf16 v[16:19], v[216:219], v[186:189], v[16:19]
	v_mfma_f32_16x16x32_bf16 v[4:7], v[208:211], v[200:203], v[4:7]
	v_mfma_f32_16x16x32_bf16 v[0:3], v[216:219], v[200:203], v[0:3]
	v_mfma_f32_16x16x32_bf16 v[40:43], v[208:211], v[128:131], v[40:43]
	v_mfma_f32_16x16x32_bf16 v[44:47], v[216:219], v[128:131], v[44:47]
	s_barrier
	ds_read_b128 v[48:51], v194 offset:32768
	ds_read_b128 v[52:55], v194 offset:33792
	ds_read_b128 v[76:79], v194 offset:34816
	ds_read_b128 v[80:83], v194 offset:35840
	s_add_u32 s24, s26, 0xb0000
	s_addc_u32 s25, s27, 0
	ds_read_b128 v[116:119], v195 offset:32768
	ds_read_b128 v[128:131], v195 offset:33792
	ds_read_b128 v[182:185], v195 offset:34816
	ds_read_b128 v[186:189], v195 offset:35840
	ds_read_b128 v[196:199], v195 offset:36864
	ds_read_b128 v[200:203], v195 offset:37888
	ds_read_b128 v[204:207], v195 offset:38912
	ds_read_b128 v[208:211], v195 offset:39936
	s_waitcnt lgkmcnt(8)
	s_barrier
	s_waitcnt lgkmcnt(0)
	v_mfma_f32_16x16x32_bf16 v[132:135], v[48:51], v[116:119], v[156:159]
	v_mfma_f32_16x16x32_bf16 v[156:159], v[52:55], v[128:131], v[132:135]
	v_mfma_f32_16x16x32_bf16 v[132:135], v[76:79], v[116:119], v[152:155]
	v_mfma_f32_16x16x32_bf16 v[152:155], v[80:83], v[128:131], v[132:135]
	v_mfma_f32_16x16x32_bf16 v[132:135], v[48:51], v[182:185], v[140:143]
	v_mfma_f32_16x16x32_bf16 v[140:143], v[52:55], v[186:189], v[132:135]
	v_mfma_f32_16x16x32_bf16 v[132:135], v[76:79], v[182:185], v[136:139]
	v_mfma_f32_16x16x32_bf16 v[124:127], v[48:51], v[196:199], v[124:127]
	v_mfma_f32_16x16x32_bf16 v[120:123], v[76:79], v[196:199], v[120:123]
	v_mfma_f32_16x16x32_bf16 v[108:111], v[48:51], v[204:207], v[108:111]
	v_mfma_f32_16x16x32_bf16 v[104:107], v[76:79], v[204:207], v[104:107]
	v_mfma_f32_16x16x32_bf16 v[136:139], v[80:83], v[186:189], v[132:135]
	v_mfma_f32_16x16x32_bf16 v[124:127], v[52:55], v[200:203], v[124:127]
	v_mfma_f32_16x16x32_bf16 v[120:123], v[80:83], v[200:203], v[120:123]
	v_mfma_f32_16x16x32_bf16 v[108:111], v[52:55], v[208:211], v[108:111]
	v_mfma_f32_16x16x32_bf16 v[104:107], v[80:83], v[208:211], v[104:107]
	s_barrier
	s_mov_b32 m0, s39
	ds_read_b128 v[212:215], v194 offset:49152
	ds_read_b128 v[216:219], v194 offset:50176
	ds_read_b128 v[220:223], v194 offset:51200
	global_load_lds_dwordx4 v160, s[24:25]
	s_mov_b32 m0, s40
	ds_read_b128 v[236:239], v194 offset:52224
	global_load_lds_dwordx4 v162, s[24:25]
	s_add_i32 m0, s36, 0x18000
	s_nop 0
	global_load_lds_dwordx4 v168, s[98:99]
	s_add_i32 m0, s36, 0x1a000
	s_nop 0
	global_load_lds_dwordx4 v164, s[98:99]
	s_barrier
	s_waitcnt lgkmcnt(0)
	v_mfma_f32_16x16x32_bf16 v[56:59], v[220:223], v[116:119], v[56:59]
	v_mfma_f32_16x16x32_bf16 v[132:135], v[212:215], v[116:119], v[148:151]
	v_mfma_f32_16x16x32_bf16 v[144:147], v[236:239], v[128:131], v[56:59]
	v_mfma_f32_16x16x32_bf16 v[56:59], v[212:215], v[182:185], v[60:63]
	v_mfma_f32_16x16x32_bf16 v[148:151], v[216:219], v[128:131], v[132:135]
	v_mfma_f32_16x16x32_bf16 v[132:135], v[216:219], v[186:189], v[56:59]
	v_mfma_f32_16x16x32_bf16 v[56:59], v[220:223], v[182:185], v[72:75]
	v_mfma_f32_16x16x32_bf16 v[128:131], v[236:239], v[186:189], v[56:59]
	v_mfma_f32_16x16x32_bf16 v[56:59], v[212:215], v[196:199], v[84:87]
	v_mfma_f32_16x16x32_bf16 v[116:119], v[216:219], v[200:203], v[56:59]
	v_mfma_f32_16x16x32_bf16 v[56:59], v[220:223], v[196:199], v[112:115]
	v_mfma_f32_16x16x32_bf16 v[112:115], v[236:239], v[200:203], v[56:59]
	v_mfma_f32_16x16x32_bf16 v[56:59], v[212:215], v[204:207], v[100:103]
	v_mfma_f32_16x16x32_bf16 v[100:103], v[216:219], v[208:211], v[56:59]
	v_mfma_f32_16x16x32_bf16 v[56:59], v[220:223], v[204:207], v[96:99]
	v_mfma_f32_16x16x32_bf16 v[96:99], v[236:239], v[208:211], v[56:59]
	s_mov_b32 m0, s47
	s_barrier
	s_nop 2
	ds_read_b128 v[56:59], v195 offset:49152
	ds_read_b128 v[60:63], v195 offset:50176
	ds_read_b128 v[72:75], v195 offset:51200
	ds_read_b128 v[84:87], v195 offset:52224
	ds_read_b128 v[182:185], v195 offset:53248
	ds_read_b128 v[186:189], v195 offset:54272
	ds_read_b128 v[196:199], v195 offset:55296
	global_load_lds_dwordx4 v160, s[100:101]
	s_mov_b32 m0, s49
	ds_read_b128 v[200:203], v195 offset:56320
	global_load_lds_dwordx4 v162, s[100:101]
	s_barrier
	s_waitcnt lgkmcnt(0)
	v_mfma_f32_16x16x32_bf16 v[92:95], v[48:51], v[56:59], v[92:95]
	v_mfma_f32_16x16x32_bf16 v[88:91], v[76:79], v[56:59], v[88:91]
	v_mfma_f32_16x16x32_bf16 v[68:71], v[48:51], v[72:75], v[68:71]
	v_mfma_f32_16x16x32_bf16 v[64:67], v[76:79], v[72:75], v[64:67]
	v_mfma_f32_16x16x32_bf16 v[28:31], v[48:51], v[182:185], v[28:31]
	v_mfma_f32_16x16x32_bf16 v[24:27], v[76:79], v[182:185], v[24:27]
	v_mfma_f32_16x16x32_bf16 v[12:15], v[48:51], v[196:199], v[12:15]
	v_mfma_f32_16x16x32_bf16 v[8:11], v[76:79], v[196:199], v[8:11]
	v_mfma_f32_16x16x32_bf16 v[92:95], v[52:55], v[60:63], v[92:95]
	v_mfma_f32_16x16x32_bf16 v[88:91], v[80:83], v[60:63], v[88:91]
	v_mfma_f32_16x16x32_bf16 v[68:71], v[52:55], v[84:87], v[68:71]
	v_mfma_f32_16x16x32_bf16 v[64:67], v[80:83], v[84:87], v[64:67]
	v_mfma_f32_16x16x32_bf16 v[28:31], v[52:55], v[186:189], v[28:31]
	v_mfma_f32_16x16x32_bf16 v[24:27], v[80:83], v[186:189], v[24:27]
	v_mfma_f32_16x16x32_bf16 v[12:15], v[52:55], v[200:203], v[12:15]
	v_mfma_f32_16x16x32_bf16 v[8:11], v[80:83], v[200:203], v[8:11]
	s_barrier
	s_add_i32 m0, s36, 0x1c000
	s_add_u32 s8, s8, 0xb0080
	s_addc_u32 s9, s9, 0
	global_load_lds_dwordx4 v168, s[8:9]
	s_add_i32 m0, s36, 0x1e000
	s_add_i32 s58, s58, 2
	global_load_lds_dwordx4 v164, s[8:9]
	s_waitcnt vmcnt(6)
	s_barrier
	v_mfma_f32_16x16x32_bf16 v[40:43], v[212:215], v[56:59], v[40:43]
	v_mfma_f32_16x16x32_bf16 v[80:83], v[216:219], v[60:63], v[40:43]
	v_mfma_f32_16x16x32_bf16 v[40:43], v[220:223], v[56:59], v[44:47]
	v_mfma_f32_16x16x32_bf16 v[36:39], v[212:215], v[72:75], v[36:39]
	v_mfma_f32_16x16x32_bf16 v[32:35], v[220:223], v[72:75], v[32:35]
	v_mfma_f32_16x16x32_bf16 v[20:23], v[212:215], v[182:185], v[20:23]
	v_mfma_f32_16x16x32_bf16 v[16:19], v[220:223], v[182:185], v[16:19]
	v_mfma_f32_16x16x32_bf16 v[4:7], v[212:215], v[196:199], v[4:7]
	v_mfma_f32_16x16x32_bf16 v[0:3], v[220:223], v[196:199], v[0:3]
	v_mfma_f32_16x16x32_bf16 v[76:79], v[236:239], v[60:63], v[40:43]
	v_mfma_f32_16x16x32_bf16 v[36:39], v[216:219], v[84:87], v[36:39]
	v_mfma_f32_16x16x32_bf16 v[32:35], v[236:239], v[84:87], v[32:35]
	v_mfma_f32_16x16x32_bf16 v[20:23], v[216:219], v[186:189], v[20:23]
	v_mfma_f32_16x16x32_bf16 v[16:19], v[236:239], v[186:189], v[16:19]
	v_mfma_f32_16x16x32_bf16 v[4:7], v[216:219], v[200:203], v[4:7]
	v_mfma_f32_16x16x32_bf16 v[0:3], v[236:239], v[200:203], v[0:3]
	s_add_u32 s56, s56, 0x100
	s_addc_u32 s57, s57, 0
	s_cmp_gt_u32 s58, 41
	s_mov_b64 s[24:25], s[2:3]
	s_barrier
.LBB0_1049:
	s_add_u32 s2, s24, 0x100
	s_addc_u32 s3, s25, 0
	ds_read_b128 v[40:43], v194
	ds_read_b128 v[44:47], v194 offset:1024
	ds_read_b128 v[48:51], v194 offset:2048
	ds_read_b128 v[52:55], v194 offset:3072
	s_cmp_eq_u32 s58, 40
	s_cselect_b32 s27, s1, s3
	s_cselect_b32 s26, s0, s2
	s_cselect_b32 s9, s23, s57
	s_cselect_b32 s8, s22, s56
	ds_read_b128 v[56:59], v195
	ds_read_b128 v[60:63], v195 offset:1024
	ds_read_b128 v[72:75], v195 offset:2048
	ds_read_b128 v[84:87], v195 offset:3072
	ds_read_b128 v[182:185], v195 offset:4096
	ds_read_b128 v[186:189], v195 offset:5120
	ds_read_b128 v[196:199], v195 offset:6144
	ds_read_b128 v[200:203], v195 offset:7168
	s_waitcnt lgkmcnt(8)
	s_barrier
	s_waitcnt lgkmcnt(0)
	v_mfma_f32_16x16x32_bf16 v[156:159], v[40:43], v[56:59], v[156:159]
	v_mfma_f32_16x16x32_bf16 v[152:155], v[48:51], v[56:59], v[152:155]
	v_mfma_f32_16x16x32_bf16 v[140:143], v[40:43], v[72:75], v[140:143]
	v_mfma_f32_16x16x32_bf16 v[136:139], v[48:51], v[72:75], v[136:139]
	v_mfma_f32_16x16x32_bf16 v[124:127], v[40:43], v[182:185], v[124:127]
	v_mfma_f32_16x16x32_bf16 v[120:123], v[48:51], v[182:185], v[120:123]
	v_mfma_f32_16x16x32_bf16 v[108:111], v[40:43], v[196:199], v[108:111]
	v_mfma_f32_16x16x32_bf16 v[104:107], v[48:51], v[196:199], v[104:107]
	v_mfma_f32_16x16x32_bf16 v[156:159], v[44:47], v[60:63], v[156:159]
	v_mfma_f32_16x16x32_bf16 v[152:155], v[52:55], v[60:63], v[152:155]
	v_mfma_f32_16x16x32_bf16 v[140:143], v[44:47], v[84:87], v[140:143]
	v_mfma_f32_16x16x32_bf16 v[136:139], v[52:55], v[84:87], v[136:139]
	v_mfma_f32_16x16x32_bf16 v[124:127], v[44:47], v[186:189], v[124:127]
	v_mfma_f32_16x16x32_bf16 v[120:123], v[52:55], v[186:189], v[120:123]
	v_mfma_f32_16x16x32_bf16 v[108:111], v[44:47], v[200:203], v[108:111]
	v_mfma_f32_16x16x32_bf16 v[104:107], v[52:55], v[200:203], v[104:107]
	s_barrier
	s_add_i32 m0, s37, 0xc000
	ds_read_b128 v[204:207], v194 offset:16384
	ds_read_b128 v[208:211], v194 offset:17408
	ds_read_b128 v[212:215], v194 offset:18432
	global_load_lds_dwordx4 v166, s[24:25]
	s_add_i32 m0, s37, 0xe000
	ds_read_b128 v[216:219], v194 offset:19456
	global_load_lds_dwordx4 v180, s[24:25]
	s_add_u32 s98, s8, 0x80
	s_addc_u32 s99, s9, 0
	s_add_i32 m0, s36, 0x10000
	s_nop 0
	global_load_lds_dwordx4 v168, s[8:9]
	s_add_i32 m0, s36, 0x12000
	s_nop 0
	global_load_lds_dwordx4 v164, s[8:9]
	s_barrier
	s_waitcnt lgkmcnt(0)
	v_mfma_f32_16x16x32_bf16 v[148:151], v[204:207], v[56:59], v[148:151]
	v_mfma_f32_16x16x32_bf16 v[56:59], v[212:215], v[56:59], v[144:147]
	v_mfma_f32_16x16x32_bf16 v[148:151], v[208:211], v[60:63], v[148:151]
	v_mfma_f32_16x16x32_bf16 v[56:59], v[216:219], v[60:63], v[56:59]
	v_mfma_f32_16x16x32_bf16 v[60:63], v[204:207], v[72:75], v[132:135]
	v_mfma_f32_16x16x32_bf16 v[72:75], v[212:215], v[72:75], v[128:131]
	v_mfma_f32_16x16x32_bf16 v[112:115], v[212:215], v[182:185], v[112:115]
	v_mfma_f32_16x16x32_bf16 v[100:103], v[204:207], v[196:199], v[100:103]
	v_mfma_f32_16x16x32_bf16 v[96:99], v[212:215], v[196:199], v[96:99]
	v_mfma_f32_16x16x32_bf16 v[60:63], v[208:211], v[84:87], v[60:63]
	v_mfma_f32_16x16x32_bf16 v[72:75], v[216:219], v[84:87], v[72:75]
	v_mfma_f32_16x16x32_bf16 v[84:87], v[204:207], v[182:185], v[116:119]
	v_mfma_f32_16x16x32_bf16 v[112:115], v[216:219], v[186:189], v[112:115]
	v_mfma_f32_16x16x32_bf16 v[100:103], v[208:211], v[200:203], v[100:103]
	v_mfma_f32_16x16x32_bf16 v[96:99], v[216:219], v[200:203], v[96:99]
	v_mfma_f32_16x16x32_bf16 v[84:87], v[208:211], v[186:189], v[84:87]
	s_mov_b32 m0, s37
	s_add_u32 s100, s26, 0x80
	s_addc_u32 s101, s27, 0
	s_barrier
	ds_read_b128 v[116:119], v195 offset:16384
	ds_read_b128 v[128:131], v195 offset:17408
	ds_read_b128 v[132:135], v195 offset:18432
	ds_read_b128 v[144:147], v195 offset:19456
	ds_read_b128 v[182:185], v195 offset:20480
	ds_read_b128 v[186:189], v195 offset:21504
	ds_read_b128 v[196:199], v195 offset:22528
	global_load_lds_dwordx4 v160, s[26:27]
	s_mov_b32 m0, s38
	ds_read_b128 v[200:203], v195 offset:23552
	global_load_lds_dwordx4 v162, s[26:27]
	s_barrier
	s_waitcnt lgkmcnt(0)
	v_mfma_f32_16x16x32_bf16 v[92:95], v[40:43], v[116:119], v[92:95]
	v_mfma_f32_16x16x32_bf16 v[88:91], v[48:51], v[116:119], v[88:91]
	v_mfma_f32_16x16x32_bf16 v[68:71], v[40:43], v[132:135], v[68:71]
	v_mfma_f32_16x16x32_bf16 v[64:67], v[48:51], v[132:135], v[64:67]
	v_mfma_f32_16x16x32_bf16 v[28:31], v[40:43], v[182:185], v[28:31]
	v_mfma_f32_16x16x32_bf16 v[24:27], v[48:51], v[182:185], v[24:27]
	v_mfma_f32_16x16x32_bf16 v[12:15], v[40:43], v[196:199], v[12:15]
	v_mfma_f32_16x16x32_bf16 v[8:11], v[48:51], v[196:199], v[8:11]
	v_mfma_f32_16x16x32_bf16 v[92:95], v[44:47], v[128:131], v[92:95]
	v_mfma_f32_16x16x32_bf16 v[88:91], v[52:55], v[128:131], v[88:91]
	v_mfma_f32_16x16x32_bf16 v[68:71], v[44:47], v[144:147], v[68:71]
	v_mfma_f32_16x16x32_bf16 v[64:67], v[52:55], v[144:147], v[64:67]
	v_mfma_f32_16x16x32_bf16 v[28:31], v[44:47], v[186:189], v[28:31]
	v_mfma_f32_16x16x32_bf16 v[24:27], v[52:55], v[186:189], v[24:27]
	v_mfma_f32_16x16x32_bf16 v[12:15], v[44:47], v[200:203], v[12:15]
	v_mfma_f32_16x16x32_bf16 v[8:11], v[52:55], v[200:203], v[8:11]
	s_barrier
	s_add_i32 m0, s36, 0x14000
	s_add_u32 s24, s8, 0xb0000
	s_addc_u32 s25, s9, 0
	global_load_lds_dwordx4 v168, s[24:25]
	s_add_i32 m0, s36, 0x16000
	s_nop 0
	global_load_lds_dwordx4 v164, s[24:25]
	s_waitcnt vmcnt(6)
	s_barrier
	v_mfma_f32_16x16x32_bf16 v[36:39], v[204:207], v[132:135], v[36:39]
	v_mfma_f32_16x16x32_bf16 v[32:35], v[212:215], v[132:135], v[32:35]
	v_mfma_f32_16x16x32_bf16 v[20:23], v[204:207], v[182:185], v[20:23]
	v_mfma_f32_16x16x32_bf16 v[16:19], v[212:215], v[182:185], v[16:19]
	v_mfma_f32_16x16x32_bf16 v[4:7], v[204:207], v[196:199], v[4:7]
	v_mfma_f32_16x16x32_bf16 v[0:3], v[212:215], v[196:199], v[0:3]
	v_mfma_f32_16x16x32_bf16 v[40:43], v[204:207], v[116:119], v[80:83]
	v_mfma_f32_16x16x32_bf16 v[44:47], v[212:215], v[116:119], v[76:79]
	v_mfma_f32_16x16x32_bf16 v[36:39], v[208:211], v[144:147], v[36:39]
	v_mfma_f32_16x16x32_bf16 v[32:35], v[216:219], v[144:147], v[32:35]
	v_mfma_f32_16x16x32_bf16 v[20:23], v[208:211], v[186:189], v[20:23]
	v_mfma_f32_16x16x32_bf16 v[16:19], v[216:219], v[186:189], v[16:19]
	v_mfma_f32_16x16x32_bf16 v[4:7], v[208:211], v[200:203], v[4:7]
	v_mfma_f32_16x16x32_bf16 v[0:3], v[216:219], v[200:203], v[0:3]
	v_mfma_f32_16x16x32_bf16 v[40:43], v[208:211], v[128:131], v[40:43]
	v_mfma_f32_16x16x32_bf16 v[44:47], v[216:219], v[128:131], v[44:47]
	s_barrier
	ds_read_b128 v[48:51], v194 offset:32768
	ds_read_b128 v[52:55], v194 offset:33792
	ds_read_b128 v[76:79], v194 offset:34816
	ds_read_b128 v[80:83], v194 offset:35840
	s_add_u32 s24, s26, 0xb0000
	s_addc_u32 s25, s27, 0
	ds_read_b128 v[116:119], v195 offset:32768
	ds_read_b128 v[128:131], v195 offset:33792
	ds_read_b128 v[182:185], v195 offset:34816
	ds_read_b128 v[186:189], v195 offset:35840
	ds_read_b128 v[196:199], v195 offset:36864
	ds_read_b128 v[200:203], v195 offset:37888
	ds_read_b128 v[204:207], v195 offset:38912
	ds_read_b128 v[208:211], v195 offset:39936
	s_waitcnt lgkmcnt(8)
	s_barrier
	s_waitcnt lgkmcnt(0)
	v_mfma_f32_16x16x32_bf16 v[132:135], v[48:51], v[116:119], v[156:159]
	v_mfma_f32_16x16x32_bf16 v[156:159], v[52:55], v[128:131], v[132:135]
	v_mfma_f32_16x16x32_bf16 v[132:135], v[76:79], v[116:119], v[152:155]
	v_mfma_f32_16x16x32_bf16 v[152:155], v[80:83], v[128:131], v[132:135]
	v_mfma_f32_16x16x32_bf16 v[132:135], v[48:51], v[182:185], v[140:143]
	v_mfma_f32_16x16x32_bf16 v[140:143], v[52:55], v[186:189], v[132:135]
	v_mfma_f32_16x16x32_bf16 v[132:135], v[76:79], v[182:185], v[136:139]
	v_mfma_f32_16x16x32_bf16 v[124:127], v[48:51], v[196:199], v[124:127]
	v_mfma_f32_16x16x32_bf16 v[120:123], v[76:79], v[196:199], v[120:123]
	v_mfma_f32_16x16x32_bf16 v[108:111], v[48:51], v[204:207], v[108:111]
	v_mfma_f32_16x16x32_bf16 v[104:107], v[76:79], v[204:207], v[104:107]
	v_mfma_f32_16x16x32_bf16 v[136:139], v[80:83], v[186:189], v[132:135]
	v_mfma_f32_16x16x32_bf16 v[124:127], v[52:55], v[200:203], v[124:127]
	v_mfma_f32_16x16x32_bf16 v[120:123], v[80:83], v[200:203], v[120:123]
	v_mfma_f32_16x16x32_bf16 v[108:111], v[52:55], v[208:211], v[108:111]
	v_mfma_f32_16x16x32_bf16 v[104:107], v[80:83], v[208:211], v[104:107]
	s_barrier
	s_mov_b32 m0, s39
	ds_read_b128 v[212:215], v194 offset:49152
	ds_read_b128 v[216:219], v194 offset:50176
	ds_read_b128 v[220:223], v194 offset:51200
	global_load_lds_dwordx4 v160, s[24:25]
	s_mov_b32 m0, s40
	ds_read_b128 v[236:239], v194 offset:52224
	global_load_lds_dwordx4 v162, s[24:25]
	s_add_i32 m0, s36, 0x18000
	s_nop 0
	global_load_lds_dwordx4 v168, s[98:99]
	s_add_i32 m0, s36, 0x1a000
	s_nop 0
	global_load_lds_dwordx4 v164, s[98:99]
	s_barrier
	s_waitcnt lgkmcnt(0)
	v_mfma_f32_16x16x32_bf16 v[56:59], v[220:223], v[116:119], v[56:59]
	v_mfma_f32_16x16x32_bf16 v[132:135], v[212:215], v[116:119], v[148:151]
	v_mfma_f32_16x16x32_bf16 v[144:147], v[236:239], v[128:131], v[56:59]
	v_mfma_f32_16x16x32_bf16 v[56:59], v[212:215], v[182:185], v[60:63]
	v_mfma_f32_16x16x32_bf16 v[148:151], v[216:219], v[128:131], v[132:135]
	v_mfma_f32_16x16x32_bf16 v[132:135], v[216:219], v[186:189], v[56:59]
	v_mfma_f32_16x16x32_bf16 v[56:59], v[220:223], v[182:185], v[72:75]
	v_mfma_f32_16x16x32_bf16 v[128:131], v[236:239], v[186:189], v[56:59]
	v_mfma_f32_16x16x32_bf16 v[56:59], v[212:215], v[196:199], v[84:87]
	v_mfma_f32_16x16x32_bf16 v[116:119], v[216:219], v[200:203], v[56:59]
	v_mfma_f32_16x16x32_bf16 v[56:59], v[220:223], v[196:199], v[112:115]
	v_mfma_f32_16x16x32_bf16 v[112:115], v[236:239], v[200:203], v[56:59]
	v_mfma_f32_16x16x32_bf16 v[56:59], v[212:215], v[204:207], v[100:103]
	v_mfma_f32_16x16x32_bf16 v[100:103], v[216:219], v[208:211], v[56:59]
	v_mfma_f32_16x16x32_bf16 v[56:59], v[220:223], v[204:207], v[96:99]
	v_mfma_f32_16x16x32_bf16 v[96:99], v[236:239], v[208:211], v[56:59]
	s_mov_b32 m0, s47
	s_barrier
	s_nop 2
	ds_read_b128 v[56:59], v195 offset:49152
	ds_read_b128 v[60:63], v195 offset:50176
	ds_read_b128 v[72:75], v195 offset:51200
	ds_read_b128 v[84:87], v195 offset:52224
	ds_read_b128 v[182:185], v195 offset:53248
	ds_read_b128 v[186:189], v195 offset:54272
	ds_read_b128 v[196:199], v195 offset:55296
	global_load_lds_dwordx4 v160, s[100:101]
	s_mov_b32 m0, s49
	ds_read_b128 v[200:203], v195 offset:56320
	global_load_lds_dwordx4 v162, s[100:101]
	s_barrier
	s_waitcnt lgkmcnt(0)
	v_mfma_f32_16x16x32_bf16 v[92:95], v[48:51], v[56:59], v[92:95]
	v_mfma_f32_16x16x32_bf16 v[88:91], v[76:79], v[56:59], v[88:91]
	v_mfma_f32_16x16x32_bf16 v[68:71], v[48:51], v[72:75], v[68:71]
	v_mfma_f32_16x16x32_bf16 v[64:67], v[76:79], v[72:75], v[64:67]
	v_mfma_f32_16x16x32_bf16 v[28:31], v[48:51], v[182:185], v[28:31]
	v_mfma_f32_16x16x32_bf16 v[24:27], v[76:79], v[182:185], v[24:27]
	v_mfma_f32_16x16x32_bf16 v[12:15], v[48:51], v[196:199], v[12:15]
	v_mfma_f32_16x16x32_bf16 v[8:11], v[76:79], v[196:199], v[8:11]
	v_mfma_f32_16x16x32_bf16 v[92:95], v[52:55], v[60:63], v[92:95]
	v_mfma_f32_16x16x32_bf16 v[88:91], v[80:83], v[60:63], v[88:91]
	v_mfma_f32_16x16x32_bf16 v[68:71], v[52:55], v[84:87], v[68:71]
	v_mfma_f32_16x16x32_bf16 v[64:67], v[80:83], v[84:87], v[64:67]
	v_mfma_f32_16x16x32_bf16 v[28:31], v[52:55], v[186:189], v[28:31]
	v_mfma_f32_16x16x32_bf16 v[24:27], v[80:83], v[186:189], v[24:27]
	v_mfma_f32_16x16x32_bf16 v[12:15], v[52:55], v[200:203], v[12:15]
	v_mfma_f32_16x16x32_bf16 v[8:11], v[80:83], v[200:203], v[8:11]
	s_barrier
	s_add_i32 m0, s36, 0x1c000
	s_add_u32 s8, s8, 0xb0080
	s_addc_u32 s9, s9, 0
	global_load_lds_dwordx4 v168, s[8:9]
	s_add_i32 m0, s36, 0x1e000
	s_add_i32 s58, s58, 2
	global_load_lds_dwordx4 v164, s[8:9]
	s_waitcnt vmcnt(6)
	s_barrier
	v_mfma_f32_16x16x32_bf16 v[40:43], v[212:215], v[56:59], v[40:43]
	v_mfma_f32_16x16x32_bf16 v[80:83], v[216:219], v[60:63], v[40:43]
	v_mfma_f32_16x16x32_bf16 v[40:43], v[220:223], v[56:59], v[44:47]
	v_mfma_f32_16x16x32_bf16 v[36:39], v[212:215], v[72:75], v[36:39]
	v_mfma_f32_16x16x32_bf16 v[32:35], v[220:223], v[72:75], v[32:35]
	v_mfma_f32_16x16x32_bf16 v[20:23], v[212:215], v[182:185], v[20:23]
	v_mfma_f32_16x16x32_bf16 v[16:19], v[220:223], v[182:185], v[16:19]
	v_mfma_f32_16x16x32_bf16 v[4:7], v[212:215], v[196:199], v[4:7]
	v_mfma_f32_16x16x32_bf16 v[0:3], v[220:223], v[196:199], v[0:3]
	v_mfma_f32_16x16x32_bf16 v[76:79], v[236:239], v[60:63], v[40:43]
	v_mfma_f32_16x16x32_bf16 v[36:39], v[216:219], v[84:87], v[36:39]
	v_mfma_f32_16x16x32_bf16 v[32:35], v[236:239], v[84:87], v[32:35]
	v_mfma_f32_16x16x32_bf16 v[20:23], v[216:219], v[186:189], v[20:23]
	v_mfma_f32_16x16x32_bf16 v[16:19], v[236:239], v[186:189], v[16:19]
	v_mfma_f32_16x16x32_bf16 v[4:7], v[216:219], v[200:203], v[4:7]
	v_mfma_f32_16x16x32_bf16 v[0:3], v[236:239], v[200:203], v[0:3]
	s_add_u32 s56, s56, 0x100
	s_addc_u32 s57, s57, 0
	s_cmp_gt_u32 s58, 41
	s_mov_b64 s[24:25], s[2:3]
	s_barrier
	s_cbranch_scc0 .LBB0_1049
	s_lshl_b32 s2, s55, 8
	v_mov_b32_e32 v186, v193
	v_mov_b32_e32 v196, v192
	s_or_b32 s2, s2, s46
	v_mov_b32_e32 v52, 0
	v_lshl_add_u32 v182, v196, 3, s2
	s_add_i32 s2, s54, -16
	s_lshr_b32 s2, s2, 3
	s_add_i32 s2, s2, 1
	s_cmp_gt_i32 s54, 15
	s_cselect_b32 s8, s2, 0
	s_mul_i32 s96, s8, 0x1800
	s_lshl_b64 s[2:3], s[96:97], 2
	s_add_u32 s2, s41, s2
	v_ashrrev_i32_e32 v183, 31, v182
	s_addc_u32 s3, s42, s3
	v_lshlrev_b64 v[40:41], 2, v[182:183]
	v_lshl_add_u64 v[42:43], s[2:3], 0, v[40:41]
	global_load_dwordx4 v[72:75], v[42:43], off
	s_lshl_b32 s96, s8, 10
	s_lshl_b64 s[2:3], s[96:97], 2
	s_add_u32 s2, s43, s2
	s_addc_u32 s3, s44, s3
	v_lshl_add_u64 v[184:185], s[2:3], 0, v[40:41]
	s_and_b64 vcc, exec, s[4:5]
	v_mov_b32_e32 v60, 0
	v_mov_b32_e32 v61, v52
	v_mov_b32_e32 v62, 0
	v_mov_b32_e32 v63, 0
	s_cbranch_vccnz .LBB0_1052
	global_load_dwordx4 v[60:63], v[184:185], off
